# hand-pipelined attention tile loop: softmax(t) interleaved with PV(t-1)+QK(t+1) MFMAs, 6-deep LDS operand ring
# speedup vs baseline: 1.0332x; 1.0332x over previous
; __device__ __forceinline__ void attn_unit(LAS unsigned char* lds, const bf16_t* Z, bf16_t* A2, const float* tabg, int seq_base, int S, int h, int qb, float lam) {
;     ...
;     const int qlo = qb * 128 + rg * 32;
;     bf16x8 qf[4];
;     { const bf16_t* qrow = Z + (size_t)(seq_base + qlo + r32) * NZ + h * 128 + m * 64 + 8 * hi;
; #pragma unroll
;       for (int ds = 0; ds < 4; ++ds) qf[ds] = *(const bf16x8*)(qrow + 16 * ds); }
;     const char* kvbase = (const char*)(Z + (size_t)seq_base * NZ + h * 128);
;     unsigned koff[2], voff[2];
; #pragma unroll
;     for (int i = 0; i < 2; ++i) { const int row = (i * 8 + w) * 4 + (lane >> 4), cp = lane & 15;
;         koff[i] = (unsigned)(row * NZ + 512 + ((cp ^ (row & 15)) << 3)) * 2u; voff[i] = (unsigned)(row * NZ + 1024 + ((cp ^ (4 * (row & 3))) << 3)) * 2u; }
;     const unsigned kb_u = (unsigned)(size_t)Kb + (unsigned)w * 1024u, vb_u = (unsigned)(size_t)Vb + (unsigned)w * 1024u;
;     ...
;     ATT_STAGE(0, 0); ATT_STAGE(1, 1);
;     asm volatile("s_waitcnt vmcnt(4) lgkmcnt(0)" ::: "memory"); __builtin_amdgcn_s_barrier(); asm volatile("" ::: "memory");
; #pragma unroll
;     for (int ds = 0; ds < 4; ++ds) asm volatile("" : "+v"(qf[ds]));
;     const float tabL = tab[0], tabR = tab[448];
;     f32x16 O[4];
; #pragma unroll
;     for (int d = 0; d < 4; ++d)
; #pragma unroll
;         for (int r = 0; r < 16; ++r) O[d][r] = 0.f;
;     float mu = 0.f; f32x2 ls2 = {0.f, 0.f};
;     f32x16 cblk; float coff_cur = __builtin_nanf("");
; #pragma unroll
;     for (int r = 0; r < 16; ++r) cblk[r] = 0.f;
;     const int NT = S >> 6;
;     const unsigned kfo = r32 * 256 + ((unsigned)((m * 8 + hi) ^ (r32 & 15)) << 4);
;     const unsigned vj = (i16 >> 2) & 3;
;     const unsigned vfo = (4 * hi + (i16 >> 2)) * 256 + (vj << 6) + 32 * (g4 & 1) + 8 * (i16 & 3);
;     int bc = 0, bn = 2;
.LBB0_292:
	s_or_b64 exec, exec, s[8:9]
	s_waitcnt lgkmcnt(0)
	s_add_u32 s8, s4, 0x7800000
	s_addc_u32 s9, s5, 0
	s_lshl_b32 s10, s26, 11
	s_and_b32 s11, s10, 0x2000
	s_and_b32 s10, s25, 32
	s_ashr_i32 s15, s27, 6
	s_or_b32 s10, s10, s23
	s_and_b32 s17, s15, 3
	s_lshl_b32 s14, s10, 7
	s_lshl_b32 s10, s17, 5
	s_or_b32 s34, s10, s14
	v_and_b32_e32 v148, 31, v68
	s_or_b32 s14, s34, s11
	v_or_b32_e32 v2, s14, v148
	s_ashr_i32 s16, s27, 8
	v_lshlrev_b32_e32 v162, 12, v2
	v_lshl_add_u64 v[2:3], s[8:9], 0, v[162:163]
	s_lshl_b32 s48, s30, 8
	s_lshl_b32 s28, s16, 6
	v_bfe_u32 v159, v68, 5, 1
	v_lshl_add_u64 v[2:3], v[2:3], 0, s[48:49]
	s_ashr_i32 s29, s28, 31
	v_lshl_add_u64 v[2:3], s[28:29], 1, v[2:3]
	v_lshlrev_b32_e32 v162, 4, v159
	v_lshl_add_u64 v[2:3], v[2:3], 0, v[162:163]
	global_load_dwordx4 v[116:119], v[2:3], off
	global_load_dwordx4 v[120:123], v[2:3], off offset:32
	global_load_dwordx4 v[124:127], v[2:3], off offset:64
	global_load_dwordx4 v[128:131], v[2:3], off offset:96
	s_lshl_b32 s11, s11, 12
	s_add_u32 s8, s8, s11
	v_bfe_u32 v4, v68, 4, 2
	s_addc_u32 s9, s9, 0
	s_lshl_b32 s11, s15, 2
	v_or_b32_e32 v5, s11, v4
	v_lshlrev_b32_e32 v35, 5, v4
	v_bitop3_b32 v4, s11, v68, v4 bitop3:0x36
	v_lshlrev_b32_e32 v4, 3, v4
	v_and_b32_e32 v34, 15, v68
	v_lshlrev_b32_e32 v5, 11, v5
	v_and_b32_e32 v4, 0x78, v4
	v_lshlrev_b32_e32 v6, 3, v34
	v_or_b32_e32 v7, v4, v5
	v_lshl_or_b32 v149, v7, 1, v249
	v_bitop3_b32 v7, v5, v35, v6 bitop3:0xf6
	v_add_u32_e32 v5, 0x10000, v5
	v_or_b32_e32 v4, v4, v5
	s_add_u32 s8, s8, s48
	v_lshl_or_b32 v161, v4, 1, v249
	v_bitop3_b32 v4, v5, v35, v6 bitop3:0xf6
	s_addc_u32 s9, s9, 0
	s_lshl_b32 s29, s15, 10
	s_add_i32 s11, 0, 0xc000
	v_lshl_or_b32 v160, v7, 1, v250
	v_lshl_or_b32 v176, v4, 1, v250
	s_add_i32 s28, s29, 0
	s_add_i32 s29, s29, s11
	s_mov_b32 s15, m0
	s_mov_b32 m0, s28
	s_nop 0
	global_load_lds_dwordx4 v149, s[8:9]
	s_mov_b32 m0, s29
	s_nop 0
	global_load_lds_dwordx4 v160, s[8:9]
	s_add_u32 m0, s28, 0x2000
	s_nop 0
	global_load_lds_dwordx4 v161, s[8:9]
	s_add_u32 m0, s29, 0x2000
	s_nop 0
	global_load_lds_dwordx4 v176, s[8:9]
	s_mov_b32 m0, s15
	s_add_u32 s36, s8, 0x40000
	s_addc_u32 s37, s9, 0
	s_add_i32 s15, s28, 0x4000
	s_add_i32 s31, s29, 0x4000
	s_mov_b32 s33, m0
	s_mov_b32 m0, s15
	s_nop 0
	global_load_lds_dwordx4 v149, s[36:37]
	s_mov_b32 m0, s31
	s_nop 0
	global_load_lds_dwordx4 v160, s[36:37]
	s_add_u32 m0, s15, 0x2000
	s_nop 0
	global_load_lds_dwordx4 v161, s[36:37]
	s_add_u32 m0, s31, 0x2000
	s_nop 0
	global_load_lds_dwordx4 v176, s[36:37]
	s_mov_b32 m0, s33
	s_mov_b32 s32, m0
	s_add_u32 s8, s8, 0x40000
	s_addc_u32 s9, s9, 0
	s_add_u32 s4, s8, 0x40000
	s_addc_u32 s5, s9, 0
	s_lshl_b32 s15, s30, 7
	s_and_b32 s42, s27, 0x3fffffc0
	s_lshl_b32 s42, s42, 2
	s_add_i32 s30, s42, 0x18000
	v_and_b32_e32 v183, 63, v68
	v_lshl_add_u32 v185, v159, 4, s30
	v_lshl_add_u32 v184, v148, 2, s30
	s_add_i32 s33, s34, 0x9f
	v_add_lshl_u32 v251, s34, v148, 2
	v_lshlrev_b32_e32 v252, 4, v159
	v_sub_u32_e32 v162, v252, v251
	s_add_i32 s34, s34, 0xffffff41
	s_lshl_b32 s42, s16, 3
	v_lshlrev_b32_e32 v19, 8, v148
	v_bitop3_b32 v251, s42, v34, v159 bitop3:0x36
	v_lshlrev_b32_e32 v252, 2, v159
	v_lshrrev_b32_e32 v253, 2, v34
	v_lshlrev_b32_e32 v254, 3, v68
	v_lshl_add_u32 v19, v251, 4, v19
	v_or_b32_e32 v252, v252, v253
	v_and_b32_e32 v254, 24, v254
	v_and_b32_e32 v251, 32, v35
	v_lshlrev_b32_e32 v252, 8, v252
	v_lshl_or_b32 v253, v253, 6, v254
	v_xor_b32_e32 v180, 32, v19
	v_or3_b32 v179, v252, v251, v253
	v_xor_b32_e32 v181, 64, v19
	v_xor_b32_e32 v182, 0x60, v19
	v_add_u32_e32 v228, 0xc000, v179
	v_xor_b32_e32 v229, 0x40, v179
	v_add_u32_e32 v229, 0xc000, v229
	v_xor_b32_e32 v230, 0x80, v179
	v_add_u32_e32 v230, 0xc000, v230
	v_xor_b32_e32 v231, 0xc0, v179
	v_add_u32_e32 v231, 0xc000, v231
	s_add_u32 m0, s28, 0x8000
	s_nop 0
	global_load_lds_dwordx4 v149, s[4:5]
	s_add_u32 m0, s28, 0xa000
	s_nop 0
	global_load_lds_dwordx4 v161, s[4:5]
	s_mov_b32 s10, 0
	s_movk_i32 s11, 0x4000
	s_mov_b32 s31, 0x8000
	s_mov_b32 s35, 0
	v_mov_b64_e32 v[20:21], 0
	v_mov_b64_e32 v[22:23], 0
	v_mov_b64_e32 v[24:25], 0
	v_mov_b64_e32 v[26:27], 0
	v_mov_b64_e32 v[28:29], 0
	v_mov_b64_e32 v[30:31], 0
	v_mov_b64_e32 v[32:33], 0
	v_mov_b64_e32 v[34:35], 0
	v_mov_b64_e32 v[36:37], 0
	v_mov_b64_e32 v[38:39], 0
	v_mov_b64_e32 v[40:41], 0
	v_mov_b64_e32 v[42:43], 0
	v_mov_b64_e32 v[44:45], 0
	v_mov_b64_e32 v[46:47], 0
	v_mov_b64_e32 v[48:49], 0
	v_mov_b64_e32 v[50:51], 0
	v_mov_b64_e32 v[52:53], 0
	v_mov_b64_e32 v[54:55], 0
	v_mov_b64_e32 v[56:57], 0
	v_mov_b64_e32 v[58:59], 0
	v_mov_b64_e32 v[60:61], 0
	v_mov_b64_e32 v[62:63], 0
	v_mov_b64_e32 v[64:65], 0
	v_mov_b64_e32 v[66:67], 0
	v_mov_b64_e32 v[68:69], 0
	v_mov_b64_e32 v[70:71], 0
	v_mov_b64_e32 v[72:73], 0
	v_mov_b64_e32 v[74:75], 0
	v_mov_b64_e32 v[76:77], 0
	v_mov_b64_e32 v[78:79], 0
	v_mov_b64_e32 v[80:81], 0
	v_mov_b64_e32 v[82:83], 0
	v_mov_b64_e32 v[150:151], 0
	v_mov_b32_e32 v186, 0
	s_cmp_lt_u32 s35, s33
	s_cselect_b32 s43, 0, 2
	s_cmp_gt_i32 s35, s34
	s_cselect_b32 s42, 0, 1
	s_or_b32 s40, s42, s43
	s_mov_b32 s38, s40
	s_waitcnt vmcnt(6) lgkmcnt(0)
	s_barrier
	v_mov_b32_e32 v187, 0x18800
	ds_read_b32 v177, v187
	ds_read_b32 v178, v187 offset:1792
	ds_read_b128 v[132:135], v19
	ds_read_b128 v[136:139], v19 offset:8192
	ds_read_b128 v[140:143], v180
	ds_read_b128 v[144:147], v180 offset:8192
	ds_read_b128 v[220:223], v181
	ds_read_b128 v[224:227], v181 offset:8192
	ds_read_b128 v[232:235], v182
	ds_read_b128 v[236:239], v182 offset:8192
	s_waitcnt lgkmcnt(8)
	s_branch .LatA_rebuild_p0
; #define LAS __attribute__((address_space(3)))
; __device__ __forceinline__ void attn_unit(LAS unsigned char* lds, const bf16_t* Z, bf16_t* A2, const float* tabg, int seq_base, int S, int h, int qb, float lam) {
;     ...
;             for (int ds = 0; ds < 4; ++ds) { kf[2 * ds] = *(const LAS bf16x8*)(Kt + (kfo ^ (unsigned)(ds << 5))); kf[2 * ds + 1] = *(const LAS bf16x8*)(Kt + 32 * 256 + (kfo ^ (unsigned)(ds << 5))); }
;             __builtin_amdgcn_sched_barrier(0);
;             p0 = __builtin_amdgcn_mfma_f32_32x32x16_bf16(kf[0], qf[0], cblk, 0, 0, 0);
;             p1 = __builtin_amdgcn_mfma_f32_32x32x16_bf16(kf[1], qf[0], cblk, 0, 0, 0);
; #pragma unroll
;             for (int ds = 1; ds < 4; ++ds) {
;                 p0 = __builtin_amdgcn_mfma_f32_32x32x16_bf16(kf[2 * ds], qf[ds], p0, 0, 0, 0);
;                 p1 = __builtin_amdgcn_mfma_f32_32x32x16_bf16(kf[2 * ds + 1], qf[ds], p1, 0, 0, 0);
;             }
;         }
;     ...
;         const unsigned vbase = (unsigned)(size_t)Vt + vfo;
;         s16x4 va[8], vb[8];
;         VREADS1(va, 0);
;         if (near) {
;             const LAS float* tp = tab + (kv0 + 4 * hi - (qlo + r32) + 224);
; #pragma unroll
;             for (int r = 0; r < 16; ++r) { p0[r] += tp[(r & 3) + 8 * (r >> 2)]; p1[r] += tp[32 + (r & 3) + 8 * (r >> 2)]; }
;         }
;         float mx = max2f(max16f(p0), max16f(p1));
;         const bool first = (t == 0);
;         if (first || __any(mx > THR)) {
;             { auto rr = __builtin_amdgcn_permlane32_swap(__float_as_uint(mx), __float_as_uint(mx), false, false); mx = max2f(__uint_as_float(rr[0]), __uint_as_float(rr[1])); }
;             const float delta = first ? mx : fmaxf(mx, 0.f);
;             const float alpha = first ? 1.0f : __builtin_amdgcn_exp2f(-delta);
;             mu += delta; ls2 *= alpha;
;             if (!first) {
;                 asm volatile("" ::: "memory");
;                 scr[r32] = alpha;
;                 asm volatile("s_waitcnt lgkmcnt(0)" ::: "memory");
; #pragma unroll
;                 for (int g = 0; g < 4; ++g) { const f32x4 a4 = *(const LAS f32x4*)(scr + 8 * g + 4 * hi);
; #pragma unroll
;                     for (int d = 0; d < 4; ++d) { O[d][4 * g + 0] *= a4[0]; O[d][4 * g + 1] *= a4[1]; O[d][4 * g + 2] *= a4[2]; O[d][4 * g + 3] *= a4[3]; } }
;                 asm volatile("s_waitcnt lgkmcnt(0)" ::: "memory");
;             }
; #pragma unroll
.LatA_rebuildret_p0:
	s_waitcnt lgkmcnt(7)
	v_mfma_f32_32x32x16_bf16 v[84:99], v[132:135], v[116:119], v[2:17]
	s_waitcnt lgkmcnt(6)
	v_mfma_f32_32x32x16_bf16 v[100:115], v[136:139], v[116:119], v[2:17]
	s_waitcnt lgkmcnt(5)
	v_mfma_f32_32x32x16_bf16 v[84:99], v[140:143], v[120:123], v[84:99]
	s_waitcnt lgkmcnt(4)
	v_mfma_f32_32x32x16_bf16 v[100:115], v[144:147], v[120:123], v[100:115]
	s_waitcnt lgkmcnt(3)
	v_mfma_f32_32x32x16_bf16 v[84:99], v[220:223], v[124:127], v[84:99]
	s_waitcnt lgkmcnt(2)
	v_mfma_f32_32x32x16_bf16 v[100:115], v[224:227], v[124:127], v[100:115]
	s_waitcnt lgkmcnt(1)
	v_mfma_f32_32x32x16_bf16 v[84:99], v[232:235], v[128:131], v[84:99]
	s_waitcnt lgkmcnt(0)
	v_mfma_f32_32x32x16_bf16 v[100:115], v[236:239], v[128:131], v[100:115]
	s_nop 15
	s_nop 15
	s_cmp_eq_u32 s38, 0
	s_cbranch_scc1 .LatA_near_p0
.LatA_nearret_p0:
	v_max3_f32 v251, v84, v85, v86
	v_max3_f32 v252, v87, v88, v89
	v_max3_f32 v251, v251, v90, v91
	v_max3_f32 v252, v252, v92, v93
	v_max3_f32 v251, v251, v94, v95
	v_max3_f32 v252, v252, v96, v97
	v_max3_f32 v251, v251, v98, v99
	v_max3_f32 v252, v252, v100, v101
	v_max3_f32 v251, v251, v102, v103
	v_max3_f32 v252, v252, v104, v105
	v_max3_f32 v251, v251, v106, v107
	v_max3_f32 v252, v252, v108, v109
	v_max3_f32 v251, v251, v110, v111
	v_max3_f32 v252, v252, v112, v113
	v_max3_f32 v251, v251, v114, v115
	v_max_f32_e32 v251, v251, v252
	v_mov_b32_e32 v252, v251
	s_nop 1
	v_permlane32_swap_b32_e32 v251, v252
	v_max_f32_e32 v186, v251, v252
	v_sub_f32_e32 v84, v84, v186
	v_sub_f32_e32 v85, v85, v186
	v_sub_f32_e32 v86, v86, v186
	v_sub_f32_e32 v87, v87, v186
	v_sub_f32_e32 v88, v88, v186
	v_sub_f32_e32 v89, v89, v186
	v_sub_f32_e32 v90, v90, v186
	v_sub_f32_e32 v91, v91, v186
	v_sub_f32_e32 v92, v92, v186
	v_sub_f32_e32 v93, v93, v186
	v_sub_f32_e32 v94, v94, v186
	v_sub_f32_e32 v95, v95, v186
	v_sub_f32_e32 v96, v96, v186
	v_sub_f32_e32 v97, v97, v186
	v_sub_f32_e32 v98, v98, v186
	v_sub_f32_e32 v99, v99, v186
	v_sub_f32_e32 v100, v100, v186
	v_sub_f32_e32 v101, v101, v186
	v_sub_f32_e32 v102, v102, v186
	v_sub_f32_e32 v103, v103, v186
	v_sub_f32_e32 v104, v104, v186
	v_sub_f32_e32 v105, v105, v186
	v_sub_f32_e32 v106, v106, v186
	v_sub_f32_e32 v107, v107, v186
	v_sub_f32_e32 v108, v108, v186
	v_sub_f32_e32 v109, v109, v186
	v_sub_f32_e32 v110, v110, v186
	v_sub_f32_e32 v111, v111, v186
	v_sub_f32_e32 v112, v112, v186
	v_sub_f32_e32 v113, v113, v186
	v_sub_f32_e32 v114, v114, v186
	v_sub_f32_e32 v115, v115, v186
	s_mov_b32 s36, -1
	s_waitcnt vmcnt(0)
	s_barrier
	v_add_u32_e32 v232, s11, v19
	v_add_u32_e32 v233, s11, v180
	v_add_u32_e32 v234, s11, v181
	v_add_u32_e32 v235, s11, v182
	s_add_u32 s4, s8, 0x80000
	s_addc_u32 s5, s9, 0
	ds_read_b128 v[220:223], v232
	ds_read_b128 v[224:227], v232 offset:8192
	ds_read_b128 v[132:135], v233
	ds_read_b128 v[136:139], v233 offset:8192
	ds_read_b128 v[140:143], v234
	ds_read_b128 v[144:147], v234 offset:8192
	v_max3_f32 v251, v84, v85, v86
	v_max3_f32 v252, v87, v88, v89
	v_max3_f32 v251, v251, v90, v91
	v_max3_f32 v252, v252, v92, v93
	v_max3_f32 v251, v251, v94, v95
	v_max3_f32 v252, v252, v96, v97
	v_max3_f32 v251, v251, v98, v99
	v_max3_f32 v252, v252, v100, v101
	v_max3_f32 v251, v251, v102, v103
	v_max3_f32 v252, v252, v104, v105
	v_max3_f32 v251, v251, v106, v107
	v_max3_f32 v252, v252, v108, v109
	v_max3_f32 v251, v251, v110, v111
	v_max3_f32 v252, v252, v112, v113
	v_max3_f32 v251, v251, v114, v115
	v_max_f32_e32 v251, v251, v252
	s_nop 0
	v_cmp_lt_f32_e32 vcc, 0x41000000, v251
	s_cbranch_vccnz .LatA_rare_t0
.LatA_rareret_t0:
	s_add_i32 s42, s35, 64
	s_cmp_lt_u32 s42, s33
	s_cselect_b32 s43, 0, 2
	s_cmp_gt_i32 s42, s34
	s_cselect_b32 s42, 0, 1
	s_or_b32 s40, s42, s43
	s_cmp_lg_u32 s40, s36
	s_cbranch_scc1 .LatA_rebuild_t0
; __device__ __forceinline__ void attn_unit(LAS unsigned char* lds, const bf16_t* Z, bf16_t* A2, const float* tabg, int seq_base, int S, int h, int qb, float lam) {
;     ...
;             p0 = __builtin_amdgcn_mfma_f32_32x32x16_bf16(kf[0], qf[0], cblk, 0, 0, 0);
;             p1 = __builtin_amdgcn_mfma_f32_32x32x16_bf16(kf[1], qf[0], cblk, 0, 0, 0);
; #pragma unroll
;             for (int ds = 1; ds < 4; ++ds) {
;                 p0 = __builtin_amdgcn_mfma_f32_32x32x16_bf16(kf[2 * ds], qf[ds], p0, 0, 0, 0);
;                 p1 = __builtin_amdgcn_mfma_f32_32x32x16_bf16(kf[2 * ds + 1], qf[ds], p1, 0, 0, 0);
;             }
;         }
;     ...
;         const unsigned vbase = (unsigned)(size_t)Vt + vfo;
;         s16x4 va[8], vb[8];
;         VREADS1(va, 0);
;         if (near) {
;             const LAS float* tp = tab + (kv0 + 4 * hi - (qlo + r32) + 224);
; #pragma unroll
;             for (int r = 0; r < 16; ++r) { p0[r] += tp[(r & 3) + 8 * (r >> 2)]; p1[r] += tp[32 + (r & 3) + 8 * (r >> 2)]; }
;         }
;         float mx = max2f(max16f(p0), max16f(p1));
;         const bool first = (t == 0);
;         if (first || __any(mx > THR)) {
;             { auto rr = __builtin_amdgcn_permlane32_swap(__float_as_uint(mx), __float_as_uint(mx), false, false); mx = max2f(__uint_as_float(rr[0]), __uint_as_float(rr[1])); }
;             const float delta = first ? mx : fmaxf(mx, 0.f);
;             const float alpha = first ? 1.0f : __builtin_amdgcn_exp2f(-delta);
;             mu += delta; ls2 *= alpha;
;             if (!first) {
;                 asm volatile("" ::: "memory");
;                 scr[r32] = alpha;
;                 asm volatile("s_waitcnt lgkmcnt(0)" ::: "memory");
; #pragma unroll
;                 for (int g = 0; g < 4; ++g) { const f32x4 a4 = *(const LAS f32x4*)(scr + 8 * g + 4 * hi);
; #pragma unroll
;                     for (int d = 0; d < 4; ++d) { O[d][4 * g + 0] *= a4[0]; O[d][4 * g + 1] *= a4[1]; O[d][4 * g + 2] *= a4[2]; O[d][4 * g + 3] *= a4[3]; } }
;                 asm volatile("s_waitcnt lgkmcnt(0)" ::: "memory");
;             }
; #pragma unroll
;             for (int r = 0; r < 16; ++r) { p0[r] -= delta; p1[r] -= delta; }
;             asm volatile("" : "+v"(p0), "+v"(p1));
;         }
; #pragma unroll
;         for (int r = 0; r < 16; ++r) { p0[r] = __builtin_amdgcn_exp2f(p0[r]); p1[r] = __builtin_amdgcn_exp2f(p1[r]); }
; #pragma unroll
.LatA_rebuildret_t0:
	s_waitcnt lgkmcnt(5)
	v_mfma_f32_32x32x16_bf16 v[188:203], v[220:223], v[116:119], v[2:17]
	ds_read_b128 v[220:223], v235
	v_exp_f32_e32 v84, v84
	v_exp_f32_e32 v85, v85
	v_exp_f32_e32 v86, v86
	v_exp_f32_e32 v87, v87
	v_pk_add_f32 v[150:151], v[150:151], v[84:85]
	v_pk_add_f32 v[150:151], v[150:151], v[86:87]
	v_exp_f32_e32 v88, v88
	s_waitcnt lgkmcnt(5)
	v_mfma_f32_32x32x16_bf16 v[204:219], v[224:227], v[116:119], v[2:17]
	ds_read_b128 v[224:227], v235 offset:8192
	s_add_u32 m0, s28, s10
	s_nop 0
	global_load_lds_dwordx4 v149, s[4:5]
	v_exp_f32_e32 v89, v89
	v_cvt_pk_bf16_f32 v84, v84, v85
	v_cvt_pk_bf16_f32 v85, v86, v87
	v_exp_f32_e32 v90, v90
	v_exp_f32_e32 v91, v91
	v_pk_add_f32 v[150:151], v[150:151], v[88:89]
	v_pk_add_f32 v[150:151], v[150:151], v[90:91]
	v_cvt_pk_bf16_f32 v86, v88, v89
	v_cvt_pk_bf16_f32 v87, v90, v91
	s_waitcnt lgkmcnt(5)
	v_mfma_f32_32x32x16_bf16 v[188:203], v[132:135], v[120:123], v[188:203]
	v_exp_f32_e32 v92, v92
	v_exp_f32_e32 v93, v93
	v_exp_f32_e32 v94, v94
	v_exp_f32_e32 v95, v95
	v_pk_add_f32 v[150:151], v[150:151], v[92:93]
	v_pk_add_f32 v[150:151], v[150:151], v[94:95]
	v_exp_f32_e32 v96, v96
	s_waitcnt lgkmcnt(4)
	v_mfma_f32_32x32x16_bf16 v[204:219], v[136:139], v[120:123], v[204:219]
	s_add_u32 m0, s28, s10
	s_add_u32 m0, m0, 0x2000
	s_nop 0
	global_load_lds_dwordx4 v161, s[4:5]
	v_exp_f32_e32 v97, v97
	v_cvt_pk_bf16_f32 v88, v92, v93
	v_cvt_pk_bf16_f32 v89, v94, v95
	v_exp_f32_e32 v98, v98
	v_exp_f32_e32 v99, v99
	v_pk_add_f32 v[150:151], v[150:151], v[96:97]
	v_pk_add_f32 v[150:151], v[150:151], v[98:99]
	v_cvt_pk_bf16_f32 v90, v96, v97
	v_cvt_pk_bf16_f32 v91, v98, v99
	s_waitcnt lgkmcnt(3)
	v_mfma_f32_32x32x16_bf16 v[188:203], v[140:143], v[124:127], v[188:203]
	v_exp_f32_e32 v100, v100
	v_exp_f32_e32 v101, v101
	v_exp_f32_e32 v102, v102
	v_exp_f32_e32 v103, v103
	v_pk_add_f32 v[150:151], v[150:151], v[100:101]
	v_pk_add_f32 v[150:151], v[150:151], v[102:103]
	v_exp_f32_e32 v104, v104
	s_waitcnt lgkmcnt(2)
	v_mfma_f32_32x32x16_bf16 v[204:219], v[144:147], v[124:127], v[204:219]
	v_exp_f32_e32 v105, v105
	v_cvt_pk_bf16_f32 v100, v100, v101
	v_cvt_pk_bf16_f32 v101, v102, v103
	v_exp_f32_e32 v106, v106
	v_exp_f32_e32 v107, v107
	v_pk_add_f32 v[150:151], v[150:151], v[104:105]
	v_pk_add_f32 v[150:151], v[150:151], v[106:107]
	v_cvt_pk_bf16_f32 v102, v104, v105
	v_cvt_pk_bf16_f32 v103, v106, v107
	s_waitcnt lgkmcnt(1)
	v_mfma_f32_32x32x16_bf16 v[188:203], v[220:223], v[128:131], v[188:203]
	v_exp_f32_e32 v108, v108
	v_exp_f32_e32 v109, v109
	v_exp_f32_e32 v110, v110
	v_exp_f32_e32 v111, v111
	v_pk_add_f32 v[150:151], v[150:151], v[108:109]
	v_pk_add_f32 v[150:151], v[150:151], v[110:111]
	v_exp_f32_e32 v112, v112
	s_waitcnt lgkmcnt(0)
	v_mfma_f32_32x32x16_bf16 v[204:219], v[224:227], v[128:131], v[204:219]
	v_exp_f32_e32 v113, v113
	v_cvt_pk_bf16_f32 v104, v108, v109
	v_cvt_pk_bf16_f32 v105, v110, v111
	v_exp_f32_e32 v114, v114
	v_exp_f32_e32 v115, v115
	v_pk_add_f32 v[150:151], v[150:151], v[112:113]
	v_pk_add_f32 v[150:151], v[150:151], v[114:115]
	v_cvt_pk_bf16_f32 v106, v112, v113
	v_cvt_pk_bf16_f32 v107, v114, v115
	s_mov_b32 s42, s10
	s_mov_b32 s10, s11
	s_mov_b32 s11, s31
	s_mov_b32 s31, s42
	s_add_u32 s8, s8, 0x40000
	s_addc_u32 s9, s9, 0
	s_add_i32 s35, s35, 64
	s_mov_b32 s38, s40
	s_waitcnt vmcnt(2) lgkmcnt(0)
	s_barrier
	s_cmp_eq_u32 s38, 0
	s_cbranch_scc1 .LatA_near_t1
.LatA_nearret_t1:
	v_add_u32_e32 v232, s11, v19
	v_add_u32_e32 v233, s11, v180
	v_add_u32_e32 v234, s11, v181
	v_add_u32_e32 v235, s11, v182
	v_add_u32_e32 v236, s31, v228
	v_add_u32_e32 v237, s31, v229
	v_add_u32_e32 v238, s31, v230
	v_add_u32_e32 v239, s31, v231
	s_add_u32 s4, s8, 0x80000
	s_addc_u32 s5, s9, 0
	ds_read_b64_tr_b16 v[132:133], v236 offset:0
	ds_read_b64_tr_b16 v[134:135], v236 offset:2048
	ds_read_b64_tr_b16 v[136:137], v237 offset:0
	ds_read_b64_tr_b16 v[138:139], v237 offset:2048
	ds_read_b64_tr_b16 v[140:141], v238 offset:0
	ds_read_b64_tr_b16 v[142:143], v238 offset:2048
	ds_read_b64_tr_b16 v[144:145], v239 offset:0
	ds_read_b64_tr_b16 v[146:147], v239 offset:2048
	ds_read_b64_tr_b16 v[220:221], v236 offset:4096
	ds_read_b64_tr_b16 v[222:223], v236 offset:6144
	ds_read_b64_tr_b16 v[224:225], v237 offset:4096
	ds_read_b64_tr_b16 v[226:227], v237 offset:6144
	v_max3_f32 v251, v188, v189, v190
	v_max3_f32 v252, v191, v192, v193
	v_max3_f32 v251, v251, v194, v195
	v_max3_f32 v252, v252, v196, v197
	v_max3_f32 v251, v251, v198, v199
	v_max3_f32 v252, v252, v200, v201
	v_max3_f32 v251, v251, v202, v203
	v_max3_f32 v252, v252, v204, v205
	v_max3_f32 v251, v251, v206, v207
	v_max3_f32 v252, v252, v208, v209
	v_max3_f32 v251, v251, v210, v211
	v_max3_f32 v252, v252, v212, v213
	v_max3_f32 v251, v251, v214, v215
	v_max3_f32 v252, v252, v216, v217
	v_max3_f32 v251, v251, v218, v219
	v_max_f32_e32 v251, v251, v252
	s_nop 0
	v_cmp_lt_f32_e32 vcc, 0x41000000, v251
	s_cbranch_vccnz .LatA_rare_t1

; __device__ __forceinline__ void attn_unit(LAS unsigned char* lds, const bf16_t* Z, bf16_t* A2, const float* tabg, int seq_base, int S, int h, int qb, float lam) {
;     ...
;             p0 = __builtin_amdgcn_mfma_f32_32x32x16_bf16(kf[0], qf[0], cblk, 0, 0, 0);
;             p1 = __builtin_amdgcn_mfma_f32_32x32x16_bf16(kf[1], qf[0], cblk, 0, 0, 0);
; #pragma unroll
;             for (int ds = 1; ds < 4; ++ds) {
;                 p0 = __builtin_amdgcn_mfma_f32_32x32x16_bf16(kf[2 * ds], qf[ds], p0, 0, 0, 0);
;                 p1 = __builtin_amdgcn_mfma_f32_32x32x16_bf16(kf[2 * ds + 1], qf[ds], p1, 0, 0, 0);
;             }
;         }
;     ...
;         const unsigned vbase = (unsigned)(size_t)Vt + vfo;
;         s16x4 va[8], vb[8];
;         VREADS1(va, 0);
;         if (near) {
;             const LAS float* tp = tab + (kv0 + 4 * hi - (qlo + r32) + 224);
; #pragma unroll
;             for (int r = 0; r < 16; ++r) { p0[r] += tp[(r & 3) + 8 * (r >> 2)]; p1[r] += tp[32 + (r & 3) + 8 * (r >> 2)]; }
;         }
;         float mx = max2f(max16f(p0), max16f(p1));
;         const bool first = (t == 0);
;         if (first || __any(mx > THR)) {
;             { auto rr = __builtin_amdgcn_permlane32_swap(__float_as_uint(mx), __float_as_uint(mx), false, false); mx = max2f(__uint_as_float(rr[0]), __uint_as_float(rr[1])); }
;             const float delta = first ? mx : fmaxf(mx, 0.f);
;             const float alpha = first ? 1.0f : __builtin_amdgcn_exp2f(-delta);
;             mu += delta; ls2 *= alpha;
;             if (!first) {
;                 asm volatile("" ::: "memory");
;                 scr[r32] = alpha;
;                 asm volatile("s_waitcnt lgkmcnt(0)" ::: "memory");
; #pragma unroll
;                 for (int g = 0; g < 4; ++g) { const f32x4 a4 = *(const LAS f32x4*)(scr + 8 * g + 4 * hi);
; #pragma unroll
;                     for (int d = 0; d < 4; ++d) { O[d][4 * g + 0] *= a4[0]; O[d][4 * g + 1] *= a4[1]; O[d][4 * g + 2] *= a4[2]; O[d][4 * g + 3] *= a4[3]; } }
;                 asm volatile("s_waitcnt lgkmcnt(0)" ::: "memory");
;             }
; #pragma unroll
;             for (int r = 0; r < 16; ++r) { p0[r] -= delta; p1[r] -= delta; }
;             asm volatile("" : "+v"(p0), "+v"(p1));
;         }
; #pragma unroll
;         for (int r = 0; r < 16; ++r) { p0[r] = __builtin_amdgcn_exp2f(p0[r]); p1[r] = __builtin_amdgcn_exp2f(p1[r]); }
; #pragma unroll
.LatA_rebuildret_t1:
	s_waitcnt lgkmcnt(10)
	v_mfma_f32_32x32x16_bf16 v[20:35], v[84:87], v[132:135], v[20:35]
	ds_read_b64_tr_b16 v[132:133], v238 offset:4096
	ds_read_b64_tr_b16 v[134:135], v238 offset:6144
	v_exp_f32_e32 v188, v188
	v_exp_f32_e32 v189, v189
	s_waitcnt lgkmcnt(10)
	v_mfma_f32_32x32x16_bf16 v[36:51], v[84:87], v[136:139], v[36:51]
	ds_read_b64_tr_b16 v[136:137], v239 offset:4096
	ds_read_b64_tr_b16 v[138:139], v239 offset:6144
	v_exp_f32_e32 v190, v190
	v_exp_f32_e32 v191, v191
	s_waitcnt lgkmcnt(10)
	v_mfma_f32_32x32x16_bf16 v[52:67], v[84:87], v[140:143], v[52:67]
	ds_read_b64_tr_b16 v[140:141], v236 offset:8192
	ds_read_b64_tr_b16 v[142:143], v236 offset:10240
	v_pk_add_f32 v[150:151], v[150:151], v[188:189]
	v_pk_add_f32 v[150:151], v[150:151], v[190:191]
	v_exp_f32_e32 v192, v192
	s_waitcnt lgkmcnt(10)
	v_mfma_f32_32x32x16_bf16 v[68:83], v[84:87], v[144:147], v[68:83]
	ds_read_b64_tr_b16 v[144:145], v237 offset:8192
	ds_read_b64_tr_b16 v[146:147], v237 offset:10240
	s_add_u32 m0, s28, s10
	s_nop 0
	global_load_lds_dwordx4 v149, s[4:5]
	v_exp_f32_e32 v193, v193
	v_cvt_pk_bf16_f32 v188, v188, v189
	v_cvt_pk_bf16_f32 v189, v190, v191
	s_waitcnt lgkmcnt(10)
	v_mfma_f32_32x32x16_bf16 v[20:35], v[88:91], v[220:223], v[20:35]
	ds_read_b64_tr_b16 v[220:221], v238 offset:8192
	ds_read_b64_tr_b16 v[222:223], v238 offset:10240
	v_exp_f32_e32 v194, v194
	v_exp_f32_e32 v195, v195
	s_waitcnt lgkmcnt(10)
	v_mfma_f32_32x32x16_bf16 v[36:51], v[88:91], v[224:227], v[36:51]
	ds_read_b64_tr_b16 v[224:225], v239 offset:8192
	ds_read_b64_tr_b16 v[226:227], v239 offset:10240
	v_pk_add_f32 v[150:151], v[150:151], v[192:193]
	v_pk_add_f32 v[150:151], v[150:151], v[194:195]
	v_cvt_pk_bf16_f32 v190, v192, v193
	v_cvt_pk_bf16_f32 v191, v194, v195
	s_waitcnt lgkmcnt(10)
	v_mfma_f32_32x32x16_bf16 v[52:67], v[88:91], v[132:135], v[52:67]
	ds_read_b64_tr_b16 v[132:133], v236 offset:12288
	ds_read_b64_tr_b16 v[134:135], v236 offset:14336
	v_exp_f32_e32 v196, v196
	v_exp_f32_e32 v197, v197
	s_waitcnt lgkmcnt(10)
	v_mfma_f32_32x32x16_bf16 v[68:83], v[88:91], v[136:139], v[68:83]
	ds_read_b64_tr_b16 v[136:137], v237 offset:12288
	ds_read_b64_tr_b16 v[138:139], v237 offset:14336
	s_add_u32 m0, s29, s11
	s_nop 0
	global_load_lds_dwordx4 v160, s[8:9]
	v_exp_f32_e32 v198, v198
	v_exp_f32_e32 v199, v199
	s_waitcnt lgkmcnt(10)
	v_mfma_f32_32x32x16_bf16 v[20:35], v[100:103], v[140:143], v[20:35]
	ds_read_b64_tr_b16 v[140:141], v238 offset:12288
	ds_read_b64_tr_b16 v[142:143], v238 offset:14336
	v_pk_add_f32 v[150:151], v[150:151], v[196:197]
	v_pk_add_f32 v[150:151], v[150:151], v[198:199]
	v_exp_f32_e32 v200, v200
	s_waitcnt lgkmcnt(10)
	v_mfma_f32_32x32x16_bf16 v[36:51], v[100:103], v[144:147], v[36:51]
	ds_read_b64_tr_b16 v[144:145], v239 offset:12288
	ds_read_b64_tr_b16 v[146:147], v239 offset:14336
	v_exp_f32_e32 v201, v201
	v_cvt_pk_bf16_f32 v192, v196, v197
	v_cvt_pk_bf16_f32 v193, v198, v199
	s_waitcnt lgkmcnt(10)
	v_mfma_f32_32x32x16_bf16 v[52:67], v[100:103], v[220:223], v[52:67]
	ds_read_b128 v[220:223], v232
	v_exp_f32_e32 v202, v202
	v_exp_f32_e32 v203, v203
	s_waitcnt lgkmcnt(9)
	v_mfma_f32_32x32x16_bf16 v[68:83], v[100:103], v[224:227], v[68:83]
	ds_read_b128 v[224:227], v232 offset:8192
	s_add_u32 m0, s28, s10
	s_add_u32 m0, m0, 0x2000
	s_nop 0
	global_load_lds_dwordx4 v161, s[4:5]
	v_pk_add_f32 v[150:151], v[150:151], v[200:201]
	v_pk_add_f32 v[150:151], v[150:151], v[202:203]
	v_cvt_pk_bf16_f32 v194, v200, v201
	v_cvt_pk_bf16_f32 v195, v202, v203
	s_waitcnt lgkmcnt(8)
	v_mfma_f32_32x32x16_bf16 v[20:35], v[104:107], v[132:135], v[20:35]
	ds_read_b128 v[132:135], v233
	v_exp_f32_e32 v204, v204
	v_exp_f32_e32 v205, v205
	s_waitcnt lgkmcnt(7)
	v_mfma_f32_32x32x16_bf16 v[36:51], v[104:107], v[136:139], v[36:51]
	ds_read_b128 v[136:139], v233 offset:8192
	v_exp_f32_e32 v206, v206
	v_exp_f32_e32 v207, v207
	s_waitcnt lgkmcnt(6)
	v_mfma_f32_32x32x16_bf16 v[52:67], v[104:107], v[140:143], v[52:67]
	ds_read_b128 v[140:143], v234
	v_pk_add_f32 v[150:151], v[150:151], v[204:205]
	v_pk_add_f32 v[150:151], v[150:151], v[206:207]
	v_exp_f32_e32 v208, v208
	s_waitcnt lgkmcnt(5)
	v_mfma_f32_32x32x16_bf16 v[68:83], v[104:107], v[144:147], v[68:83]
	ds_read_b128 v[144:147], v234 offset:8192
	s_add_u32 m0, s29, s11
	s_add_u32 m0, m0, 0x2000
	s_nop 0
	global_load_lds_dwordx4 v176, s[8:9]
	v_exp_f32_e32 v209, v209
	v_cvt_pk_bf16_f32 v204, v204, v205
	v_cvt_pk_bf16_f32 v205, v206, v207
	s_waitcnt lgkmcnt(5)
	v_mfma_f32_32x32x16_bf16 v[84:99], v[220:223], v[116:119], v[2:17]
	ds_read_b128 v[220:223], v235
	v_exp_f32_e32 v210, v210
	v_exp_f32_e32 v211, v211
	s_waitcnt lgkmcnt(5)
	v_mfma_f32_32x32x16_bf16 v[100:115], v[224:227], v[116:119], v[2:17]
	ds_read_b128 v[224:227], v235 offset:8192
	v_pk_add_f32 v[150:151], v[150:151], v[208:209]
	v_pk_add_f32 v[150:151], v[150:151], v[210:211]
	v_cvt_pk_bf16_f32 v206, v208, v209
	v_cvt_pk_bf16_f32 v207, v210, v211
	s_waitcnt lgkmcnt(5)
	v_mfma_f32_32x32x16_bf16 v[84:99], v[132:135], v[120:123], v[84:99]
	v_exp_f32_e32 v212, v212
	v_exp_f32_e32 v213, v213
	s_waitcnt lgkmcnt(4)
	v_mfma_f32_32x32x16_bf16 v[100:115], v[136:139], v[120:123], v[100:115]
	v_exp_f32_e32 v214, v214
	v_exp_f32_e32 v215, v215
	s_waitcnt lgkmcnt(3)
	v_mfma_f32_32x32x16_bf16 v[84:99], v[140:143], v[124:127], v[84:99]
	v_pk_add_f32 v[150:151], v[150:151], v[212:213]
	v_pk_add_f32 v[150:151], v[150:151], v[214:215]
	v_exp_f32_e32 v216, v216
	s_waitcnt lgkmcnt(2)
	v_mfma_f32_32x32x16_bf16 v[100:115], v[144:147], v[124:127], v[100:115]
	v_exp_f32_e32 v217, v217
	v_cvt_pk_bf16_f32 v208, v212, v213
	v_cvt_pk_bf16_f32 v209, v214, v215
	s_waitcnt lgkmcnt(1)
	v_mfma_f32_32x32x16_bf16 v[84:99], v[220:223], v[128:131], v[84:99]
	v_exp_f32_e32 v218, v218
	v_exp_f32_e32 v219, v219
	s_waitcnt lgkmcnt(0)
	v_mfma_f32_32x32x16_bf16 v[100:115], v[224:227], v[128:131], v[100:115]
	v_pk_add_f32 v[150:151], v[150:151], v[216:217]
	v_pk_add_f32 v[150:151], v[150:151], v[218:219]
	v_cvt_pk_bf16_f32 v210, v216, v217
	v_cvt_pk_bf16_f32 v211, v218, v219
	s_mov_b32 s42, s10
	s_mov_b32 s10, s11
	s_mov_b32 s11, s31
	s_mov_b32 s31, s42
	s_add_u32 s8, s8, 0x40000
	s_addc_u32 s9, s9, 0
	s_add_i32 s35, s35, 64
	s_mov_b32 s38, s40
	s_waitcnt vmcnt(4) lgkmcnt(0)
	s_barrier
	s_movk_i32 s37, 61
; #define LAS __attribute__((address_space(3)))
; __device__ __forceinline__ float max2f(float a, float b) { float r; asm("v_max_f32_e32 %0, %1, %2" : "=v"(r) : "v"(a), "v"(b)); return r; }
; #define VREADS1(arr, d_) do { const unsigned ad_ = vbase ^ (unsigned)((d_) << 6); __builtin_amdgcn_sched_barrier(0); \
;         _Pragma("unroll") for (int ks_ = 0; ks_ < 4; ++ks_) { VTR(arr[ks_ * 2], ad_, ks_ * 4096); VTR(arr[ks_ * 2 + 1], ad_, ks_ * 4096 + 2048); } __builtin_amdgcn_sched_barrier(0); } while (0)
; __device__ __forceinline__ void attn_unit(LAS unsigned char* lds, const bf16_t* Z, bf16_t* A2, const float* tabg, int seq_base, int S, int h, int qb, float lam) {
;     ...
;         const unsigned vbase = (unsigned)(size_t)Vt + vfo;
;         s16x4 va[8], vb[8];
;         VREADS1(va, 0);
;         if (near) {
;             const LAS float* tp = tab + (kv0 + 4 * hi - (qlo + r32) + 224);
; #pragma unroll
;             for (int r = 0; r < 16; ++r) { p0[r] += tp[(r & 3) + 8 * (r >> 2)]; p1[r] += tp[32 + (r & 3) + 8 * (r >> 2)]; }
;         }
;         float mx = max2f(max16f(p0), max16f(p1));
;         const bool first = (t == 0);
;         if (first || __any(mx > THR)) {
.LatA_loop:
	s_cmp_eq_u32 s38, 0
	s_cbranch_scc1 .LatA_near_e
.LatA_nearret_e:
	v_add_u32_e32 v232, s11, v19
	v_add_u32_e32 v233, s11, v180
	v_add_u32_e32 v234, s11, v181
	v_add_u32_e32 v235, s11, v182
	v_add_u32_e32 v236, s31, v228
	v_add_u32_e32 v237, s31, v229
	v_add_u32_e32 v238, s31, v230
	v_add_u32_e32 v239, s31, v231
	s_add_u32 s4, s8, 0x80000
	s_addc_u32 s5, s9, 0
	ds_read_b64_tr_b16 v[132:133], v236 offset:0
	ds_read_b64_tr_b16 v[134:135], v236 offset:2048
	ds_read_b64_tr_b16 v[136:137], v237 offset:0
	ds_read_b64_tr_b16 v[138:139], v237 offset:2048
	ds_read_b64_tr_b16 v[140:141], v238 offset:0
	ds_read_b64_tr_b16 v[142:143], v238 offset:2048
	ds_read_b64_tr_b16 v[144:145], v239 offset:0
	ds_read_b64_tr_b16 v[146:147], v239 offset:2048
	ds_read_b64_tr_b16 v[220:221], v236 offset:4096
	ds_read_b64_tr_b16 v[222:223], v236 offset:6144
	ds_read_b64_tr_b16 v[224:225], v237 offset:4096
	ds_read_b64_tr_b16 v[226:227], v237 offset:6144
	v_max3_f32 v251, v84, v85, v86
	v_max3_f32 v252, v87, v88, v89
	v_max3_f32 v251, v251, v90, v91
	v_max3_f32 v252, v252, v92, v93
	v_max3_f32 v251, v251, v94, v95
	v_max3_f32 v252, v252, v96, v97
	v_max3_f32 v251, v251, v98, v99
	v_max3_f32 v252, v252, v100, v101
	v_max3_f32 v251, v251, v102, v103
	v_max3_f32 v252, v252, v104, v105
	v_max3_f32 v251, v251, v106, v107
	v_max3_f32 v252, v252, v108, v109
	v_max3_f32 v251, v251, v110, v111
	v_max3_f32 v252, v252, v112, v113
	v_max3_f32 v251, v251, v114, v115
	v_max_f32_e32 v251, v251, v252
	s_nop 0
	v_cmp_lt_f32_e32 vcc, 0x41000000, v251
	s_cbranch_vccnz .LatA_rare_e

; __device__ __forceinline__ void attn_unit(LAS unsigned char* lds, const bf16_t* Z, bf16_t* A2, const float* tabg, int seq_base, int S, int h, int qb, float lam) {
;     ...
;             p0 = __builtin_amdgcn_mfma_f32_32x32x16_bf16(kf[0], qf[0], cblk, 0, 0, 0);
;             p1 = __builtin_amdgcn_mfma_f32_32x32x16_bf16(kf[1], qf[0], cblk, 0, 0, 0);
; #pragma unroll
;             for (int ds = 1; ds < 4; ++ds) {
;                 p0 = __builtin_amdgcn_mfma_f32_32x32x16_bf16(kf[2 * ds], qf[ds], p0, 0, 0, 0);
;                 p1 = __builtin_amdgcn_mfma_f32_32x32x16_bf16(kf[2 * ds + 1], qf[ds], p1, 0, 0, 0);
;             }
;         }
;     ...
;         const unsigned vbase = (unsigned)(size_t)Vt + vfo;
;         s16x4 va[8], vb[8];
;         VREADS1(va, 0);
;         if (near) {
;             const LAS float* tp = tab + (kv0 + 4 * hi - (qlo + r32) + 224);
; #pragma unroll
;             for (int r = 0; r < 16; ++r) { p0[r] += tp[(r & 3) + 8 * (r >> 2)]; p1[r] += tp[32 + (r & 3) + 8 * (r >> 2)]; }
;         }
;         float mx = max2f(max16f(p0), max16f(p1));
;         const bool first = (t == 0);
;         if (first || __any(mx > THR)) {
;             { auto rr = __builtin_amdgcn_permlane32_swap(__float_as_uint(mx), __float_as_uint(mx), false, false); mx = max2f(__uint_as_float(rr[0]), __uint_as_float(rr[1])); }
;             const float delta = first ? mx : fmaxf(mx, 0.f);
;             const float alpha = first ? 1.0f : __builtin_amdgcn_exp2f(-delta);
;             mu += delta; ls2 *= alpha;
;             if (!first) {
;                 asm volatile("" ::: "memory");
;                 scr[r32] = alpha;
;                 asm volatile("s_waitcnt lgkmcnt(0)" ::: "memory");
; #pragma unroll
;                 for (int g = 0; g < 4; ++g) { const f32x4 a4 = *(const LAS f32x4*)(scr + 8 * g + 4 * hi);
; #pragma unroll
;                     for (int d = 0; d < 4; ++d) { O[d][4 * g + 0] *= a4[0]; O[d][4 * g + 1] *= a4[1]; O[d][4 * g + 2] *= a4[2]; O[d][4 * g + 3] *= a4[3]; } }
;                 asm volatile("s_waitcnt lgkmcnt(0)" ::: "memory");
;             }
; #pragma unroll
;             for (int r = 0; r < 16; ++r) { p0[r] -= delta; p1[r] -= delta; }
;             asm volatile("" : "+v"(p0), "+v"(p1));
;         }
; #pragma unroll
;         for (int r = 0; r < 16; ++r) { p0[r] = __builtin_amdgcn_exp2f(p0[r]); p1[r] = __builtin_amdgcn_exp2f(p1[r]); }
; #pragma unroll
.LatA_rebuildret_e:
	s_waitcnt lgkmcnt(10)
	v_mfma_f32_32x32x16_bf16 v[20:35], v[188:191], v[132:135], v[20:35]
	ds_read_b64_tr_b16 v[132:133], v238 offset:4096
	ds_read_b64_tr_b16 v[134:135], v238 offset:6144
	v_exp_f32_e32 v84, v84
	v_exp_f32_e32 v85, v85
	s_waitcnt lgkmcnt(10)
	v_mfma_f32_32x32x16_bf16 v[36:51], v[188:191], v[136:139], v[36:51]
	ds_read_b64_tr_b16 v[136:137], v239 offset:4096
	ds_read_b64_tr_b16 v[138:139], v239 offset:6144
	v_exp_f32_e32 v86, v86
	v_exp_f32_e32 v87, v87
	s_waitcnt lgkmcnt(10)
	v_mfma_f32_32x32x16_bf16 v[52:67], v[188:191], v[140:143], v[52:67]
	ds_read_b64_tr_b16 v[140:141], v236 offset:8192
	ds_read_b64_tr_b16 v[142:143], v236 offset:10240
	v_pk_add_f32 v[150:151], v[150:151], v[84:85]
	v_pk_add_f32 v[150:151], v[150:151], v[86:87]
	v_exp_f32_e32 v88, v88
	s_waitcnt lgkmcnt(10)
	v_mfma_f32_32x32x16_bf16 v[68:83], v[188:191], v[144:147], v[68:83]
	ds_read_b64_tr_b16 v[144:145], v237 offset:8192
	ds_read_b64_tr_b16 v[146:147], v237 offset:10240
	s_add_u32 m0, s28, s10
	s_nop 0
	global_load_lds_dwordx4 v149, s[4:5]
	v_exp_f32_e32 v89, v89
	v_cvt_pk_bf16_f32 v84, v84, v85
	v_cvt_pk_bf16_f32 v85, v86, v87
	s_waitcnt lgkmcnt(10)
	v_mfma_f32_32x32x16_bf16 v[20:35], v[192:195], v[220:223], v[20:35]
	ds_read_b64_tr_b16 v[220:221], v238 offset:8192
	ds_read_b64_tr_b16 v[222:223], v238 offset:10240
	v_exp_f32_e32 v90, v90
	v_exp_f32_e32 v91, v91
	s_waitcnt lgkmcnt(10)
	v_mfma_f32_32x32x16_bf16 v[36:51], v[192:195], v[224:227], v[36:51]
	ds_read_b64_tr_b16 v[224:225], v239 offset:8192
	ds_read_b64_tr_b16 v[226:227], v239 offset:10240
	v_pk_add_f32 v[150:151], v[150:151], v[88:89]
	v_pk_add_f32 v[150:151], v[150:151], v[90:91]
	v_cvt_pk_bf16_f32 v86, v88, v89
	v_cvt_pk_bf16_f32 v87, v90, v91
	s_waitcnt lgkmcnt(10)
	v_mfma_f32_32x32x16_bf16 v[52:67], v[192:195], v[132:135], v[52:67]
	ds_read_b64_tr_b16 v[132:133], v236 offset:12288
	ds_read_b64_tr_b16 v[134:135], v236 offset:14336
	v_exp_f32_e32 v92, v92
	v_exp_f32_e32 v93, v93
	s_waitcnt lgkmcnt(10)
	v_mfma_f32_32x32x16_bf16 v[68:83], v[192:195], v[136:139], v[68:83]
	ds_read_b64_tr_b16 v[136:137], v237 offset:12288
	ds_read_b64_tr_b16 v[138:139], v237 offset:14336
	s_add_u32 m0, s29, s11
	s_nop 0
	global_load_lds_dwordx4 v160, s[8:9]
	v_exp_f32_e32 v94, v94
	v_exp_f32_e32 v95, v95
	s_waitcnt lgkmcnt(10)
	v_mfma_f32_32x32x16_bf16 v[20:35], v[204:207], v[140:143], v[20:35]
	ds_read_b64_tr_b16 v[140:141], v238 offset:12288
	ds_read_b64_tr_b16 v[142:143], v238 offset:14336
	v_pk_add_f32 v[150:151], v[150:151], v[92:93]
	v_pk_add_f32 v[150:151], v[150:151], v[94:95]
	v_exp_f32_e32 v96, v96
	s_waitcnt lgkmcnt(10)
	v_mfma_f32_32x32x16_bf16 v[36:51], v[204:207], v[144:147], v[36:51]
	ds_read_b64_tr_b16 v[144:145], v239 offset:12288
	ds_read_b64_tr_b16 v[146:147], v239 offset:14336
	v_exp_f32_e32 v97, v97
	v_cvt_pk_bf16_f32 v88, v92, v93
	v_cvt_pk_bf16_f32 v89, v94, v95
	s_waitcnt lgkmcnt(10)
	v_mfma_f32_32x32x16_bf16 v[52:67], v[204:207], v[220:223], v[52:67]
	ds_read_b128 v[220:223], v232
	v_exp_f32_e32 v98, v98
	v_exp_f32_e32 v99, v99
	s_waitcnt lgkmcnt(9)
	v_mfma_f32_32x32x16_bf16 v[68:83], v[204:207], v[224:227], v[68:83]
	ds_read_b128 v[224:227], v232 offset:8192
	s_add_u32 m0, s28, s10
	s_add_u32 m0, m0, 0x2000
	s_nop 0
	global_load_lds_dwordx4 v161, s[4:5]
	v_pk_add_f32 v[150:151], v[150:151], v[96:97]
	v_pk_add_f32 v[150:151], v[150:151], v[98:99]
	v_cvt_pk_bf16_f32 v90, v96, v97
	v_cvt_pk_bf16_f32 v91, v98, v99
	s_waitcnt lgkmcnt(8)
	v_mfma_f32_32x32x16_bf16 v[20:35], v[208:211], v[132:135], v[20:35]
	ds_read_b128 v[132:135], v233
	v_exp_f32_e32 v100, v100
	v_exp_f32_e32 v101, v101
	s_waitcnt lgkmcnt(7)
	v_mfma_f32_32x32x16_bf16 v[36:51], v[208:211], v[136:139], v[36:51]
	ds_read_b128 v[136:139], v233 offset:8192
	v_exp_f32_e32 v102, v102
	v_exp_f32_e32 v103, v103
	s_waitcnt lgkmcnt(6)
	v_mfma_f32_32x32x16_bf16 v[52:67], v[208:211], v[140:143], v[52:67]
	ds_read_b128 v[140:143], v234
	v_pk_add_f32 v[150:151], v[150:151], v[100:101]
	v_pk_add_f32 v[150:151], v[150:151], v[102:103]
	v_exp_f32_e32 v104, v104
	s_waitcnt lgkmcnt(5)
	v_mfma_f32_32x32x16_bf16 v[68:83], v[208:211], v[144:147], v[68:83]
	ds_read_b128 v[144:147], v234 offset:8192
	s_add_u32 m0, s29, s11
	s_add_u32 m0, m0, 0x2000
	s_nop 0
	global_load_lds_dwordx4 v176, s[8:9]
	v_exp_f32_e32 v105, v105
	v_cvt_pk_bf16_f32 v100, v100, v101
	v_cvt_pk_bf16_f32 v101, v102, v103
	s_waitcnt lgkmcnt(5)
	v_mfma_f32_32x32x16_bf16 v[188:203], v[220:223], v[116:119], v[2:17]
	ds_read_b128 v[220:223], v235
	v_exp_f32_e32 v106, v106
	v_exp_f32_e32 v107, v107
	s_waitcnt lgkmcnt(5)
	v_mfma_f32_32x32x16_bf16 v[204:219], v[224:227], v[116:119], v[2:17]
	ds_read_b128 v[224:227], v235 offset:8192
	v_pk_add_f32 v[150:151], v[150:151], v[104:105]
	v_pk_add_f32 v[150:151], v[150:151], v[106:107]
	v_cvt_pk_bf16_f32 v102, v104, v105
	v_cvt_pk_bf16_f32 v103, v106, v107
	s_waitcnt lgkmcnt(5)
	v_mfma_f32_32x32x16_bf16 v[188:203], v[132:135], v[120:123], v[188:203]
	v_exp_f32_e32 v108, v108
	v_exp_f32_e32 v109, v109
	s_waitcnt lgkmcnt(4)
	v_mfma_f32_32x32x16_bf16 v[204:219], v[136:139], v[120:123], v[204:219]
	v_exp_f32_e32 v110, v110
	v_exp_f32_e32 v111, v111
	s_waitcnt lgkmcnt(3)
	v_mfma_f32_32x32x16_bf16 v[188:203], v[140:143], v[124:127], v[188:203]
	v_pk_add_f32 v[150:151], v[150:151], v[108:109]
	v_pk_add_f32 v[150:151], v[150:151], v[110:111]
	v_exp_f32_e32 v112, v112
	s_waitcnt lgkmcnt(2)
	v_mfma_f32_32x32x16_bf16 v[204:219], v[144:147], v[124:127], v[204:219]
	v_exp_f32_e32 v113, v113
	v_cvt_pk_bf16_f32 v104, v108, v109
	v_cvt_pk_bf16_f32 v105, v110, v111
	s_waitcnt lgkmcnt(1)
	v_mfma_f32_32x32x16_bf16 v[188:203], v[220:223], v[128:131], v[188:203]
	v_exp_f32_e32 v114, v114
	v_exp_f32_e32 v115, v115
	s_waitcnt lgkmcnt(0)
	v_mfma_f32_32x32x16_bf16 v[204:219], v[224:227], v[128:131], v[204:219]
	v_pk_add_f32 v[150:151], v[150:151], v[112:113]
	v_pk_add_f32 v[150:151], v[150:151], v[114:115]
	v_cvt_pk_bf16_f32 v106, v112, v113
	v_cvt_pk_bf16_f32 v107, v114, v115
	s_mov_b32 s42, s10
	s_mov_b32 s10, s11
	s_mov_b32 s11, s31
	s_mov_b32 s31, s42
	s_add_u32 s8, s8, 0x40000
	s_addc_u32 s9, s9, 0
	s_add_i32 s35, s35, 64
	s_mov_b32 s38, s40
	s_waitcnt vmcnt(4) lgkmcnt(0)
	s_barrier
	s_cmp_eq_u32 s38, 0
	s_cbranch_scc1 .LatA_near_o

; __device__ __forceinline__ void attn_unit(LAS unsigned char* lds, const bf16_t* Z, bf16_t* A2, const float* tabg, int seq_base, int S, int h, int qb, float lam) {
;     ...
;             p0 = __builtin_amdgcn_mfma_f32_32x32x16_bf16(kf[0], qf[0], cblk, 0, 0, 0);
;             p1 = __builtin_amdgcn_mfma_f32_32x32x16_bf16(kf[1], qf[0], cblk, 0, 0, 0);
; #pragma unroll
;             for (int ds = 1; ds < 4; ++ds) {
;                 p0 = __builtin_amdgcn_mfma_f32_32x32x16_bf16(kf[2 * ds], qf[ds], p0, 0, 0, 0);
;                 p1 = __builtin_amdgcn_mfma_f32_32x32x16_bf16(kf[2 * ds + 1], qf[ds], p1, 0, 0, 0);
;             }
;         }
;     ...
;         const unsigned vbase = (unsigned)(size_t)Vt + vfo;
;         s16x4 va[8], vb[8];
;         VREADS1(va, 0);
;         if (near) {
;             const LAS float* tp = tab + (kv0 + 4 * hi - (qlo + r32) + 224);
; #pragma unroll
;             for (int r = 0; r < 16; ++r) { p0[r] += tp[(r & 3) + 8 * (r >> 2)]; p1[r] += tp[32 + (r & 3) + 8 * (r >> 2)]; }
;         }
;         float mx = max2f(max16f(p0), max16f(p1));
;         const bool first = (t == 0);
;         if (first || __any(mx > THR)) {
;             { auto rr = __builtin_amdgcn_permlane32_swap(__float_as_uint(mx), __float_as_uint(mx), false, false); mx = max2f(__uint_as_float(rr[0]), __uint_as_float(rr[1])); }
;             const float delta = first ? mx : fmaxf(mx, 0.f);
;             const float alpha = first ? 1.0f : __builtin_amdgcn_exp2f(-delta);
;             mu += delta; ls2 *= alpha;
;             if (!first) {
;                 asm volatile("" ::: "memory");
;                 scr[r32] = alpha;
;                 asm volatile("s_waitcnt lgkmcnt(0)" ::: "memory");
; #pragma unroll
;                 for (int g = 0; g < 4; ++g) { const f32x4 a4 = *(const LAS f32x4*)(scr + 8 * g + 4 * hi);
; #pragma unroll
;                     for (int d = 0; d < 4; ++d) { O[d][4 * g + 0] *= a4[0]; O[d][4 * g + 1] *= a4[1]; O[d][4 * g + 2] *= a4[2]; O[d][4 * g + 3] *= a4[3]; } }
;                 asm volatile("s_waitcnt lgkmcnt(0)" ::: "memory");
;             }
; #pragma unroll
;             for (int r = 0; r < 16; ++r) { p0[r] -= delta; p1[r] -= delta; }
;             asm volatile("" : "+v"(p0), "+v"(p1));
;         }
; #pragma unroll
;         for (int r = 0; r < 16; ++r) { p0[r] = __builtin_amdgcn_exp2f(p0[r]); p1[r] = __builtin_amdgcn_exp2f(p1[r]); }
; #pragma unroll
.LatA_rebuildret_o:
	s_waitcnt lgkmcnt(10)
	v_mfma_f32_32x32x16_bf16 v[20:35], v[84:87], v[132:135], v[20:35]
	ds_read_b64_tr_b16 v[132:133], v238 offset:4096
	ds_read_b64_tr_b16 v[134:135], v238 offset:6144
	v_exp_f32_e32 v188, v188
	v_exp_f32_e32 v189, v189
	s_waitcnt lgkmcnt(10)
	v_mfma_f32_32x32x16_bf16 v[36:51], v[84:87], v[136:139], v[36:51]
	ds_read_b64_tr_b16 v[136:137], v239 offset:4096
	ds_read_b64_tr_b16 v[138:139], v239 offset:6144
	v_exp_f32_e32 v190, v190
	v_exp_f32_e32 v191, v191
	s_waitcnt lgkmcnt(10)
	v_mfma_f32_32x32x16_bf16 v[52:67], v[84:87], v[140:143], v[52:67]
	ds_read_b64_tr_b16 v[140:141], v236 offset:8192
	ds_read_b64_tr_b16 v[142:143], v236 offset:10240
	v_pk_add_f32 v[150:151], v[150:151], v[188:189]
	v_pk_add_f32 v[150:151], v[150:151], v[190:191]
	v_exp_f32_e32 v192, v192
	s_waitcnt lgkmcnt(10)
	v_mfma_f32_32x32x16_bf16 v[68:83], v[84:87], v[144:147], v[68:83]
	ds_read_b64_tr_b16 v[144:145], v237 offset:8192
	ds_read_b64_tr_b16 v[146:147], v237 offset:10240
	s_add_u32 m0, s28, s10
	s_nop 0
	global_load_lds_dwordx4 v149, s[4:5]
	v_exp_f32_e32 v193, v193
	v_cvt_pk_bf16_f32 v188, v188, v189
	v_cvt_pk_bf16_f32 v189, v190, v191
	s_waitcnt lgkmcnt(10)
	v_mfma_f32_32x32x16_bf16 v[20:35], v[88:91], v[220:223], v[20:35]
	ds_read_b64_tr_b16 v[220:221], v238 offset:8192
	ds_read_b64_tr_b16 v[222:223], v238 offset:10240
	v_exp_f32_e32 v194, v194
	v_exp_f32_e32 v195, v195
	s_waitcnt lgkmcnt(10)
	v_mfma_f32_32x32x16_bf16 v[36:51], v[88:91], v[224:227], v[36:51]
	ds_read_b64_tr_b16 v[224:225], v239 offset:8192
	ds_read_b64_tr_b16 v[226:227], v239 offset:10240
	v_pk_add_f32 v[150:151], v[150:151], v[192:193]
	v_pk_add_f32 v[150:151], v[150:151], v[194:195]
	v_cvt_pk_bf16_f32 v190, v192, v193
	v_cvt_pk_bf16_f32 v191, v194, v195
	s_waitcnt lgkmcnt(10)
	v_mfma_f32_32x32x16_bf16 v[52:67], v[88:91], v[132:135], v[52:67]
	ds_read_b64_tr_b16 v[132:133], v236 offset:12288
	ds_read_b64_tr_b16 v[134:135], v236 offset:14336
	v_exp_f32_e32 v196, v196
	v_exp_f32_e32 v197, v197
	s_waitcnt lgkmcnt(10)
	v_mfma_f32_32x32x16_bf16 v[68:83], v[88:91], v[136:139], v[68:83]
	ds_read_b64_tr_b16 v[136:137], v237 offset:12288
	ds_read_b64_tr_b16 v[138:139], v237 offset:14336
	s_add_u32 m0, s29, s11
	s_nop 0
	global_load_lds_dwordx4 v160, s[8:9]
	v_exp_f32_e32 v198, v198
	v_exp_f32_e32 v199, v199
	s_waitcnt lgkmcnt(10)
	v_mfma_f32_32x32x16_bf16 v[20:35], v[100:103], v[140:143], v[20:35]
	ds_read_b64_tr_b16 v[140:141], v238 offset:12288
	ds_read_b64_tr_b16 v[142:143], v238 offset:14336
	v_pk_add_f32 v[150:151], v[150:151], v[196:197]
	v_pk_add_f32 v[150:151], v[150:151], v[198:199]
	v_exp_f32_e32 v200, v200
	s_waitcnt lgkmcnt(10)
	v_mfma_f32_32x32x16_bf16 v[36:51], v[100:103], v[144:147], v[36:51]
	ds_read_b64_tr_b16 v[144:145], v239 offset:12288
	ds_read_b64_tr_b16 v[146:147], v239 offset:14336
	v_exp_f32_e32 v201, v201
	v_cvt_pk_bf16_f32 v192, v196, v197
	v_cvt_pk_bf16_f32 v193, v198, v199
	s_waitcnt lgkmcnt(10)
	v_mfma_f32_32x32x16_bf16 v[52:67], v[100:103], v[220:223], v[52:67]
	ds_read_b128 v[220:223], v232
	v_exp_f32_e32 v202, v202
	v_exp_f32_e32 v203, v203
	s_waitcnt lgkmcnt(9)
	v_mfma_f32_32x32x16_bf16 v[68:83], v[100:103], v[224:227], v[68:83]
	ds_read_b128 v[224:227], v232 offset:8192
	s_add_u32 m0, s28, s10
	s_add_u32 m0, m0, 0x2000
	s_nop 0
	global_load_lds_dwordx4 v161, s[4:5]
	v_pk_add_f32 v[150:151], v[150:151], v[200:201]
	v_pk_add_f32 v[150:151], v[150:151], v[202:203]
	v_cvt_pk_bf16_f32 v194, v200, v201
	v_cvt_pk_bf16_f32 v195, v202, v203
	s_waitcnt lgkmcnt(8)
	v_mfma_f32_32x32x16_bf16 v[20:35], v[104:107], v[132:135], v[20:35]
	ds_read_b128 v[132:135], v233
	v_exp_f32_e32 v204, v204
	v_exp_f32_e32 v205, v205
	s_waitcnt lgkmcnt(7)
	v_mfma_f32_32x32x16_bf16 v[36:51], v[104:107], v[136:139], v[36:51]
	ds_read_b128 v[136:139], v233 offset:8192
	v_exp_f32_e32 v206, v206
	v_exp_f32_e32 v207, v207
	s_waitcnt lgkmcnt(6)
	v_mfma_f32_32x32x16_bf16 v[52:67], v[104:107], v[140:143], v[52:67]
	ds_read_b128 v[140:143], v234
	v_pk_add_f32 v[150:151], v[150:151], v[204:205]
	v_pk_add_f32 v[150:151], v[150:151], v[206:207]
	v_exp_f32_e32 v208, v208
	s_waitcnt lgkmcnt(5)
	v_mfma_f32_32x32x16_bf16 v[68:83], v[104:107], v[144:147], v[68:83]
	ds_read_b128 v[144:147], v234 offset:8192
	s_add_u32 m0, s29, s11
	s_add_u32 m0, m0, 0x2000
	s_nop 0
	global_load_lds_dwordx4 v176, s[8:9]
	v_exp_f32_e32 v209, v209
	v_cvt_pk_bf16_f32 v204, v204, v205
	v_cvt_pk_bf16_f32 v205, v206, v207
	s_waitcnt lgkmcnt(5)
	v_mfma_f32_32x32x16_bf16 v[84:99], v[220:223], v[116:119], v[2:17]
	ds_read_b128 v[220:223], v235
	v_exp_f32_e32 v210, v210
	v_exp_f32_e32 v211, v211
	s_waitcnt lgkmcnt(5)
	v_mfma_f32_32x32x16_bf16 v[100:115], v[224:227], v[116:119], v[2:17]
	ds_read_b128 v[224:227], v235 offset:8192
	v_pk_add_f32 v[150:151], v[150:151], v[208:209]
	v_pk_add_f32 v[150:151], v[150:151], v[210:211]
	v_cvt_pk_bf16_f32 v206, v208, v209
	v_cvt_pk_bf16_f32 v207, v210, v211
	s_waitcnt lgkmcnt(5)
	v_mfma_f32_32x32x16_bf16 v[84:99], v[132:135], v[120:123], v[84:99]
	v_exp_f32_e32 v212, v212
	v_exp_f32_e32 v213, v213
	s_waitcnt lgkmcnt(4)
	v_mfma_f32_32x32x16_bf16 v[100:115], v[136:139], v[120:123], v[100:115]
	v_exp_f32_e32 v214, v214
	v_exp_f32_e32 v215, v215
	s_waitcnt lgkmcnt(3)
	v_mfma_f32_32x32x16_bf16 v[84:99], v[140:143], v[124:127], v[84:99]
	v_pk_add_f32 v[150:151], v[150:151], v[212:213]
	v_pk_add_f32 v[150:151], v[150:151], v[214:215]
	v_exp_f32_e32 v216, v216
	s_waitcnt lgkmcnt(2)
	v_mfma_f32_32x32x16_bf16 v[100:115], v[144:147], v[124:127], v[100:115]
	v_exp_f32_e32 v217, v217
	v_cvt_pk_bf16_f32 v208, v212, v213
	v_cvt_pk_bf16_f32 v209, v214, v215
	s_waitcnt lgkmcnt(1)
	v_mfma_f32_32x32x16_bf16 v[84:99], v[220:223], v[128:131], v[84:99]
	v_exp_f32_e32 v218, v218
	v_exp_f32_e32 v219, v219
	s_waitcnt lgkmcnt(0)
	v_mfma_f32_32x32x16_bf16 v[100:115], v[224:227], v[128:131], v[100:115]
	v_pk_add_f32 v[150:151], v[150:151], v[216:217]
	v_pk_add_f32 v[150:151], v[150:151], v[218:219]
	v_cvt_pk_bf16_f32 v210, v216, v217
	v_cvt_pk_bf16_f32 v211, v218, v219
	s_mov_b32 s42, s10
	s_mov_b32 s10, s11
	s_mov_b32 s11, s31
	s_mov_b32 s31, s42
	s_add_u32 s8, s8, 0x40000
	s_addc_u32 s9, s9, 0
	s_add_i32 s35, s35, 64
	s_mov_b32 s38, s40
	s_waitcnt vmcnt(4) lgkmcnt(0)
	s_barrier
	s_add_i32 s37, s37, -1
	s_cmp_lg_u32 s37, 0
	s_cbranch_scc1 .LatA_loop
	s_cmp_eq_u32 s38, 0
	s_cbranch_scc1 .LatA_near_x4

; #define LAS __attribute__((address_space(3)))
; __device__ __forceinline__ float max2f(float a, float b) { float r; asm("v_max_f32_e32 %0, %1, %2" : "=v"(r) : "v"(a), "v"(b)); return r; }
; #define VREADS1(arr, d_) do { const unsigned ad_ = vbase ^ (unsigned)((d_) << 6); __builtin_amdgcn_sched_barrier(0); \
;         _Pragma("unroll") for (int ks_ = 0; ks_ < 4; ++ks_) { VTR(arr[ks_ * 2], ad_, ks_ * 4096); VTR(arr[ks_ * 2 + 1], ad_, ks_ * 4096 + 2048); } __builtin_amdgcn_sched_barrier(0); } while (0)
; __device__ __forceinline__ void attn_unit(LAS unsigned char* lds, const bf16_t* Z, bf16_t* A2, const float* tabg, int seq_base, int S, int h, int qb, float lam) {
;     ...
;         const unsigned vbase = (unsigned)(size_t)Vt + vfo;
;         s16x4 va[8], vb[8];
;         VREADS1(va, 0);
;         if (near) {
;             const LAS float* tp = tab + (kv0 + 4 * hi - (qlo + r32) + 224);
; #pragma unroll
;             for (int r = 0; r < 16; ++r) { p0[r] += tp[(r & 3) + 8 * (r >> 2)]; p1[r] += tp[32 + (r & 3) + 8 * (r >> 2)]; }
;         }
;         float mx = max2f(max16f(p0), max16f(p1));
;         const bool first = (t == 0);
;         if (first || __any(mx > THR)) {
.LatA_nearret_x3:
	v_add_u32_e32 v232, s11, v19
	v_add_u32_e32 v233, s11, v180
	v_add_u32_e32 v234, s11, v181
	v_add_u32_e32 v235, s11, v182
	v_add_u32_e32 v236, s31, v228
	v_add_u32_e32 v237, s31, v229
	v_add_u32_e32 v238, s31, v230
	v_add_u32_e32 v239, s31, v231
	ds_read_b64_tr_b16 v[132:133], v236 offset:0
	ds_read_b64_tr_b16 v[134:135], v236 offset:2048
	ds_read_b64_tr_b16 v[136:137], v237 offset:0
	ds_read_b64_tr_b16 v[138:139], v237 offset:2048
	ds_read_b64_tr_b16 v[140:141], v238 offset:0
	ds_read_b64_tr_b16 v[142:143], v238 offset:2048
	ds_read_b64_tr_b16 v[144:145], v239 offset:0
	ds_read_b64_tr_b16 v[146:147], v239 offset:2048
	ds_read_b64_tr_b16 v[220:221], v236 offset:4096
	ds_read_b64_tr_b16 v[222:223], v236 offset:6144
	ds_read_b64_tr_b16 v[224:225], v237 offset:4096
	ds_read_b64_tr_b16 v[226:227], v237 offset:6144
	v_max3_f32 v251, v188, v189, v190
	v_max3_f32 v252, v191, v192, v193
	v_max3_f32 v251, v251, v194, v195
	v_max3_f32 v252, v252, v196, v197
	v_max3_f32 v251, v251, v198, v199
	v_max3_f32 v252, v252, v200, v201
	v_max3_f32 v251, v251, v202, v203
	v_max3_f32 v252, v252, v204, v205
	v_max3_f32 v251, v251, v206, v207
	v_max3_f32 v252, v252, v208, v209
	v_max3_f32 v251, v251, v210, v211
	v_max3_f32 v252, v252, v212, v213
	v_max3_f32 v251, v251, v214, v215
	v_max3_f32 v252, v252, v216, v217
	v_max3_f32 v251, v251, v218, v219
	v_max_f32_e32 v251, v251, v252
	s_nop 0
	v_cmp_lt_f32_e32 vcc, 0x41000000, v251
	s_cbranch_vccnz .LatA_rare_x3

; __device__ __forceinline__ void attn_unit(LAS unsigned char* lds, const bf16_t* Z, bf16_t* A2, const float* tabg, int seq_base, int S, int h, int qb, float lam) {
;     ...
;             p0 = __builtin_amdgcn_mfma_f32_32x32x16_bf16(kf[0], qf[0], cblk, 0, 0, 0);
;             p1 = __builtin_amdgcn_mfma_f32_32x32x16_bf16(kf[1], qf[0], cblk, 0, 0, 0);
; #pragma unroll
;             for (int ds = 1; ds < 4; ++ds) {
;                 p0 = __builtin_amdgcn_mfma_f32_32x32x16_bf16(kf[2 * ds], qf[ds], p0, 0, 0, 0);
;                 p1 = __builtin_amdgcn_mfma_f32_32x32x16_bf16(kf[2 * ds + 1], qf[ds], p1, 0, 0, 0);
;             }
;         }
;     ...
;         const unsigned vbase = (unsigned)(size_t)Vt + vfo;
;         s16x4 va[8], vb[8];
;         VREADS1(va, 0);
;         if (near) {
;             const LAS float* tp = tab + (kv0 + 4 * hi - (qlo + r32) + 224);
; #pragma unroll
;             for (int r = 0; r < 16; ++r) { p0[r] += tp[(r & 3) + 8 * (r >> 2)]; p1[r] += tp[32 + (r & 3) + 8 * (r >> 2)]; }
;         }
;         float mx = max2f(max16f(p0), max16f(p1));
;         const bool first = (t == 0);
;         if (first || __any(mx > THR)) {
;             { auto rr = __builtin_amdgcn_permlane32_swap(__float_as_uint(mx), __float_as_uint(mx), false, false); mx = max2f(__uint_as_float(rr[0]), __uint_as_float(rr[1])); }
;             const float delta = first ? mx : fmaxf(mx, 0.f);
;             const float alpha = first ? 1.0f : __builtin_amdgcn_exp2f(-delta);
;             mu += delta; ls2 *= alpha;
;             if (!first) {
;                 asm volatile("" ::: "memory");
;                 scr[r32] = alpha;
;                 asm volatile("s_waitcnt lgkmcnt(0)" ::: "memory");
; #pragma unroll
;                 for (int g = 0; g < 4; ++g) { const f32x4 a4 = *(const LAS f32x4*)(scr + 8 * g + 4 * hi);
; #pragma unroll
;                     for (int d = 0; d < 4; ++d) { O[d][4 * g + 0] *= a4[0]; O[d][4 * g + 1] *= a4[1]; O[d][4 * g + 2] *= a4[2]; O[d][4 * g + 3] *= a4[3]; } }
;                 asm volatile("s_waitcnt lgkmcnt(0)" ::: "memory");
;             }
; #pragma unroll
;             for (int r = 0; r < 16; ++r) { p0[r] -= delta; p1[r] -= delta; }
;             asm volatile("" : "+v"(p0), "+v"(p1));
;         }
; #pragma unroll
;         for (int r = 0; r < 16; ++r) { p0[r] = __builtin_amdgcn_exp2f(p0[r]); p1[r] = __builtin_amdgcn_exp2f(p1[r]); }
; #pragma unroll
.LatA_rebuildret_x3:
	s_waitcnt lgkmcnt(10)
	v_mfma_f32_32x32x16_bf16 v[20:35], v[84:87], v[132:135], v[20:35]
	ds_read_b64_tr_b16 v[132:133], v238 offset:4096
	ds_read_b64_tr_b16 v[134:135], v238 offset:6144
	v_exp_f32_e32 v188, v188
	v_exp_f32_e32 v189, v189
	s_waitcnt lgkmcnt(10)
	v_mfma_f32_32x32x16_bf16 v[36:51], v[84:87], v[136:139], v[36:51]
	ds_read_b64_tr_b16 v[136:137], v239 offset:4096
	ds_read_b64_tr_b16 v[138:139], v239 offset:6144
	v_exp_f32_e32 v190, v190
	v_exp_f32_e32 v191, v191
	s_waitcnt lgkmcnt(10)
	v_mfma_f32_32x32x16_bf16 v[52:67], v[84:87], v[140:143], v[52:67]
	ds_read_b64_tr_b16 v[140:141], v236 offset:8192
	ds_read_b64_tr_b16 v[142:143], v236 offset:10240
	v_pk_add_f32 v[150:151], v[150:151], v[188:189]
	v_pk_add_f32 v[150:151], v[150:151], v[190:191]
	v_exp_f32_e32 v192, v192
	s_waitcnt lgkmcnt(10)
	v_mfma_f32_32x32x16_bf16 v[68:83], v[84:87], v[144:147], v[68:83]
	ds_read_b64_tr_b16 v[144:145], v237 offset:8192
	ds_read_b64_tr_b16 v[146:147], v237 offset:10240
	v_exp_f32_e32 v193, v193
	v_cvt_pk_bf16_f32 v188, v188, v189
	v_cvt_pk_bf16_f32 v189, v190, v191
	s_waitcnt lgkmcnt(10)
	v_mfma_f32_32x32x16_bf16 v[20:35], v[88:91], v[220:223], v[20:35]
	ds_read_b64_tr_b16 v[220:221], v238 offset:8192
	ds_read_b64_tr_b16 v[222:223], v238 offset:10240
	v_exp_f32_e32 v194, v194
	v_exp_f32_e32 v195, v195
	s_waitcnt lgkmcnt(10)
	v_mfma_f32_32x32x16_bf16 v[36:51], v[88:91], v[224:227], v[36:51]
	ds_read_b64_tr_b16 v[224:225], v239 offset:8192
	ds_read_b64_tr_b16 v[226:227], v239 offset:10240
	v_pk_add_f32 v[150:151], v[150:151], v[192:193]
	v_pk_add_f32 v[150:151], v[150:151], v[194:195]
	v_cvt_pk_bf16_f32 v190, v192, v193
	v_cvt_pk_bf16_f32 v191, v194, v195
	s_waitcnt lgkmcnt(10)
	v_mfma_f32_32x32x16_bf16 v[52:67], v[88:91], v[132:135], v[52:67]
	ds_read_b64_tr_b16 v[132:133], v236 offset:12288
	ds_read_b64_tr_b16 v[134:135], v236 offset:14336
	v_exp_f32_e32 v196, v196
	v_exp_f32_e32 v197, v197
	s_waitcnt lgkmcnt(10)
	v_mfma_f32_32x32x16_bf16 v[68:83], v[88:91], v[136:139], v[68:83]
	ds_read_b64_tr_b16 v[136:137], v237 offset:12288
	ds_read_b64_tr_b16 v[138:139], v237 offset:14336
	s_add_u32 m0, s29, s11
	s_nop 0
	global_load_lds_dwordx4 v160, s[8:9]
	v_exp_f32_e32 v198, v198
	v_exp_f32_e32 v199, v199
	s_waitcnt lgkmcnt(10)
	v_mfma_f32_32x32x16_bf16 v[20:35], v[100:103], v[140:143], v[20:35]
	ds_read_b64_tr_b16 v[140:141], v238 offset:12288
	ds_read_b64_tr_b16 v[142:143], v238 offset:14336
	v_pk_add_f32 v[150:151], v[150:151], v[196:197]
	v_pk_add_f32 v[150:151], v[150:151], v[198:199]
	v_exp_f32_e32 v200, v200
	s_waitcnt lgkmcnt(10)
	v_mfma_f32_32x32x16_bf16 v[36:51], v[100:103], v[144:147], v[36:51]
	ds_read_b64_tr_b16 v[144:145], v239 offset:12288
	ds_read_b64_tr_b16 v[146:147], v239 offset:14336
	v_exp_f32_e32 v201, v201
	v_cvt_pk_bf16_f32 v192, v196, v197
	v_cvt_pk_bf16_f32 v193, v198, v199
	s_waitcnt lgkmcnt(10)
	v_mfma_f32_32x32x16_bf16 v[52:67], v[100:103], v[220:223], v[52:67]
	ds_read_b128 v[220:223], v232
	v_exp_f32_e32 v202, v202
	v_exp_f32_e32 v203, v203
	s_waitcnt lgkmcnt(9)
	v_mfma_f32_32x32x16_bf16 v[68:83], v[100:103], v[224:227], v[68:83]
	ds_read_b128 v[224:227], v232 offset:8192
	v_pk_add_f32 v[150:151], v[150:151], v[200:201]
	v_pk_add_f32 v[150:151], v[150:151], v[202:203]
	v_cvt_pk_bf16_f32 v194, v200, v201
	v_cvt_pk_bf16_f32 v195, v202, v203
	s_waitcnt lgkmcnt(8)
	v_mfma_f32_32x32x16_bf16 v[20:35], v[104:107], v[132:135], v[20:35]
	ds_read_b128 v[132:135], v233
	v_exp_f32_e32 v204, v204
	v_exp_f32_e32 v205, v205
	s_waitcnt lgkmcnt(7)
	v_mfma_f32_32x32x16_bf16 v[36:51], v[104:107], v[136:139], v[36:51]
	ds_read_b128 v[136:139], v233 offset:8192
	v_exp_f32_e32 v206, v206
	v_exp_f32_e32 v207, v207
	s_waitcnt lgkmcnt(6)
	v_mfma_f32_32x32x16_bf16 v[52:67], v[104:107], v[140:143], v[52:67]
	ds_read_b128 v[140:143], v234
	v_pk_add_f32 v[150:151], v[150:151], v[204:205]
	v_pk_add_f32 v[150:151], v[150:151], v[206:207]
	v_exp_f32_e32 v208, v208
	s_waitcnt lgkmcnt(5)
	v_mfma_f32_32x32x16_bf16 v[68:83], v[104:107], v[144:147], v[68:83]
	ds_read_b128 v[144:147], v234 offset:8192
	s_add_u32 m0, s29, s11
	s_add_u32 m0, m0, 0x2000
	s_nop 0
	global_load_lds_dwordx4 v176, s[8:9]
	v_exp_f32_e32 v209, v209
	v_cvt_pk_bf16_f32 v204, v204, v205
	v_cvt_pk_bf16_f32 v205, v206, v207
	s_waitcnt lgkmcnt(5)
	v_mfma_f32_32x32x16_bf16 v[84:99], v[220:223], v[116:119], v[2:17]
	ds_read_b128 v[220:223], v235
	v_exp_f32_e32 v210, v210
	v_exp_f32_e32 v211, v211
	s_waitcnt lgkmcnt(5)
	v_mfma_f32_32x32x16_bf16 v[100:115], v[224:227], v[116:119], v[2:17]
	ds_read_b128 v[224:227], v235 offset:8192
	v_pk_add_f32 v[150:151], v[150:151], v[208:209]
	v_pk_add_f32 v[150:151], v[150:151], v[210:211]
	v_cvt_pk_bf16_f32 v206, v208, v209
	v_cvt_pk_bf16_f32 v207, v210, v211
	s_waitcnt lgkmcnt(5)
	v_mfma_f32_32x32x16_bf16 v[84:99], v[132:135], v[120:123], v[84:99]
	v_exp_f32_e32 v212, v212
	v_exp_f32_e32 v213, v213
	s_waitcnt lgkmcnt(4)
	v_mfma_f32_32x32x16_bf16 v[100:115], v[136:139], v[120:123], v[100:115]
	v_exp_f32_e32 v214, v214
	v_exp_f32_e32 v215, v215
	s_waitcnt lgkmcnt(3)
	v_mfma_f32_32x32x16_bf16 v[84:99], v[140:143], v[124:127], v[84:99]
	v_pk_add_f32 v[150:151], v[150:151], v[212:213]
	v_pk_add_f32 v[150:151], v[150:151], v[214:215]
	v_exp_f32_e32 v216, v216
	s_waitcnt lgkmcnt(2)
	v_mfma_f32_32x32x16_bf16 v[100:115], v[144:147], v[124:127], v[100:115]
	v_exp_f32_e32 v217, v217
	v_cvt_pk_bf16_f32 v208, v212, v213
	v_cvt_pk_bf16_f32 v209, v214, v215
	s_waitcnt lgkmcnt(1)
	v_mfma_f32_32x32x16_bf16 v[84:99], v[220:223], v[128:131], v[84:99]
	v_exp_f32_e32 v218, v218
	v_exp_f32_e32 v219, v219
	s_waitcnt lgkmcnt(0)
	v_mfma_f32_32x32x16_bf16 v[100:115], v[224:227], v[128:131], v[100:115]
	v_pk_add_f32 v[150:151], v[150:151], v[216:217]
	v_pk_add_f32 v[150:151], v[150:151], v[218:219]
	v_cvt_pk_bf16_f32 v210, v216, v217
	v_cvt_pk_bf16_f32 v211, v218, v219
	s_mov_b32 s42, s10
	s_mov_b32 s10, s11
	s_mov_b32 s11, s31
	s_mov_b32 s31, s42
	s_add_u32 s8, s8, 0x40000
	s_addc_u32 s9, s9, 0
	s_add_i32 s35, s35, 64
	s_mov_b32 s38, s40
	s_waitcnt vmcnt(2) lgkmcnt(0)
	s_barrier
	s_cmp_eq_u32 s38, 0
	s_cbranch_scc1 .LatA_near_x2
; #define LAS __attribute__((address_space(3)))
; __device__ __forceinline__ float max2f(float a, float b) { float r; asm("v_max_f32_e32 %0, %1, %2" : "=v"(r) : "v"(a), "v"(b)); return r; }
; #define VREADS1(arr, d_) do { const unsigned ad_ = vbase ^ (unsigned)((d_) << 6); __builtin_amdgcn_sched_barrier(0); \
;         _Pragma("unroll") for (int ks_ = 0; ks_ < 4; ++ks_) { VTR(arr[ks_ * 2], ad_, ks_ * 4096); VTR(arr[ks_ * 2 + 1], ad_, ks_ * 4096 + 2048); } __builtin_amdgcn_sched_barrier(0); } while (0)
; __device__ __forceinline__ void attn_unit(LAS unsigned char* lds, const bf16_t* Z, bf16_t* A2, const float* tabg, int seq_base, int S, int h, int qb, float lam) {
;     ...
;         const unsigned vbase = (unsigned)(size_t)Vt + vfo;
;         s16x4 va[8], vb[8];
;         VREADS1(va, 0);
;         if (near) {
;             const LAS float* tp = tab + (kv0 + 4 * hi - (qlo + r32) + 224);
; #pragma unroll
;             for (int r = 0; r < 16; ++r) { p0[r] += tp[(r & 3) + 8 * (r >> 2)]; p1[r] += tp[32 + (r & 3) + 8 * (r >> 2)]; }
;         }
;         float mx = max2f(max16f(p0), max16f(p1));
;         const bool first = (t == 0);
;         if (first || __any(mx > THR)) {
.LatA_nearret_x2:
	v_add_u32_e32 v232, s11, v19
	v_add_u32_e32 v233, s11, v180
	v_add_u32_e32 v234, s11, v181
	v_add_u32_e32 v235, s11, v182
	v_add_u32_e32 v236, s31, v228
	v_add_u32_e32 v237, s31, v229
	v_add_u32_e32 v238, s31, v230
	v_add_u32_e32 v239, s31, v231
	ds_read_b64_tr_b16 v[132:133], v236 offset:0
	ds_read_b64_tr_b16 v[134:135], v236 offset:2048
	ds_read_b64_tr_b16 v[136:137], v237 offset:0
	ds_read_b64_tr_b16 v[138:139], v237 offset:2048
	ds_read_b64_tr_b16 v[140:141], v238 offset:0
	ds_read_b64_tr_b16 v[142:143], v238 offset:2048
	ds_read_b64_tr_b16 v[144:145], v239 offset:0
	ds_read_b64_tr_b16 v[146:147], v239 offset:2048
	ds_read_b64_tr_b16 v[220:221], v236 offset:4096
	ds_read_b64_tr_b16 v[222:223], v236 offset:6144
	ds_read_b64_tr_b16 v[224:225], v237 offset:4096
	ds_read_b64_tr_b16 v[226:227], v237 offset:6144
	v_max3_f32 v251, v84, v85, v86
	v_max3_f32 v252, v87, v88, v89
	v_max3_f32 v251, v251, v90, v91
	v_max3_f32 v252, v252, v92, v93
	v_max3_f32 v251, v251, v94, v95
	v_max3_f32 v252, v252, v96, v97
	v_max3_f32 v251, v251, v98, v99
	v_max3_f32 v252, v252, v100, v101
	v_max3_f32 v251, v251, v102, v103
	v_max3_f32 v252, v252, v104, v105
	v_max3_f32 v251, v251, v106, v107
	v_max3_f32 v252, v252, v108, v109
	v_max3_f32 v251, v251, v110, v111
	v_max3_f32 v252, v252, v112, v113
	v_max3_f32 v251, v251, v114, v115
	v_max_f32_e32 v251, v251, v252
	s_nop 0
	v_cmp_lt_f32_e32 vcc, 0x41000000, v251
	s_cbranch_vccnz .LatA_rare_x2

; __device__ __forceinline__ void attn_unit(LAS unsigned char* lds, const bf16_t* Z, bf16_t* A2, const float* tabg, int seq_base, int S, int h, int qb, float lam) {
;     ...
;             p0 = __builtin_amdgcn_mfma_f32_32x32x16_bf16(kf[0], qf[0], cblk, 0, 0, 0);
;             p1 = __builtin_amdgcn_mfma_f32_32x32x16_bf16(kf[1], qf[0], cblk, 0, 0, 0);
; #pragma unroll
;             for (int ds = 1; ds < 4; ++ds) {
;                 p0 = __builtin_amdgcn_mfma_f32_32x32x16_bf16(kf[2 * ds], qf[ds], p0, 0, 0, 0);
;                 p1 = __builtin_amdgcn_mfma_f32_32x32x16_bf16(kf[2 * ds + 1], qf[ds], p1, 0, 0, 0);
;             }
;         }
;     ...
;         const unsigned vbase = (unsigned)(size_t)Vt + vfo;
;         s16x4 va[8], vb[8];
;         VREADS1(va, 0);
;         if (near) {
;             const LAS float* tp = tab + (kv0 + 4 * hi - (qlo + r32) + 224);
; #pragma unroll
;             for (int r = 0; r < 16; ++r) { p0[r] += tp[(r & 3) + 8 * (r >> 2)]; p1[r] += tp[32 + (r & 3) + 8 * (r >> 2)]; }
;         }
;         float mx = max2f(max16f(p0), max16f(p1));
;         const bool first = (t == 0);
;         if (first || __any(mx > THR)) {
;             { auto rr = __builtin_amdgcn_permlane32_swap(__float_as_uint(mx), __float_as_uint(mx), false, false); mx = max2f(__uint_as_float(rr[0]), __uint_as_float(rr[1])); }
;             const float delta = first ? mx : fmaxf(mx, 0.f);
;             const float alpha = first ? 1.0f : __builtin_amdgcn_exp2f(-delta);
;             mu += delta; ls2 *= alpha;
;             if (!first) {
;                 asm volatile("" ::: "memory");
;                 scr[r32] = alpha;
;                 asm volatile("s_waitcnt lgkmcnt(0)" ::: "memory");
; #pragma unroll
;                 for (int g = 0; g < 4; ++g) { const f32x4 a4 = *(const LAS f32x4*)(scr + 8 * g + 4 * hi);
; #pragma unroll
;                     for (int d = 0; d < 4; ++d) { O[d][4 * g + 0] *= a4[0]; O[d][4 * g + 1] *= a4[1]; O[d][4 * g + 2] *= a4[2]; O[d][4 * g + 3] *= a4[3]; } }
;                 asm volatile("s_waitcnt lgkmcnt(0)" ::: "memory");
;             }
; #pragma unroll
;             for (int r = 0; r < 16; ++r) { p0[r] -= delta; p1[r] -= delta; }
;             asm volatile("" : "+v"(p0), "+v"(p1));
;         }
; #pragma unroll
;         for (int r = 0; r < 16; ++r) { p0[r] = __builtin_amdgcn_exp2f(p0[r]); p1[r] = __builtin_amdgcn_exp2f(p1[r]); }
; #pragma unroll
.LatA_rebuildret_x2:
	s_waitcnt lgkmcnt(10)
	v_mfma_f32_32x32x16_bf16 v[20:35], v[188:191], v[132:135], v[20:35]
	ds_read_b64_tr_b16 v[132:133], v238 offset:4096
	ds_read_b64_tr_b16 v[134:135], v238 offset:6144
	v_exp_f32_e32 v84, v84
	v_exp_f32_e32 v85, v85
	s_waitcnt lgkmcnt(10)
	v_mfma_f32_32x32x16_bf16 v[36:51], v[188:191], v[136:139], v[36:51]
	ds_read_b64_tr_b16 v[136:137], v239 offset:4096
	ds_read_b64_tr_b16 v[138:139], v239 offset:6144
	v_exp_f32_e32 v86, v86
	v_exp_f32_e32 v87, v87
	s_waitcnt lgkmcnt(10)
	v_mfma_f32_32x32x16_bf16 v[52:67], v[188:191], v[140:143], v[52:67]
	ds_read_b64_tr_b16 v[140:141], v236 offset:8192
	ds_read_b64_tr_b16 v[142:143], v236 offset:10240
	v_pk_add_f32 v[150:151], v[150:151], v[84:85]
	v_pk_add_f32 v[150:151], v[150:151], v[86:87]
	v_exp_f32_e32 v88, v88
	s_waitcnt lgkmcnt(10)
	v_mfma_f32_32x32x16_bf16 v[68:83], v[188:191], v[144:147], v[68:83]
	ds_read_b64_tr_b16 v[144:145], v237 offset:8192
	ds_read_b64_tr_b16 v[146:147], v237 offset:10240
	v_exp_f32_e32 v89, v89
	v_cvt_pk_bf16_f32 v84, v84, v85
	v_cvt_pk_bf16_f32 v85, v86, v87
	s_waitcnt lgkmcnt(10)
	v_mfma_f32_32x32x16_bf16 v[20:35], v[192:195], v[220:223], v[20:35]
	ds_read_b64_tr_b16 v[220:221], v238 offset:8192
	ds_read_b64_tr_b16 v[222:223], v238 offset:10240
	v_exp_f32_e32 v90, v90
	v_exp_f32_e32 v91, v91
	s_waitcnt lgkmcnt(10)
	v_mfma_f32_32x32x16_bf16 v[36:51], v[192:195], v[224:227], v[36:51]
	ds_read_b64_tr_b16 v[224:225], v239 offset:8192
	ds_read_b64_tr_b16 v[226:227], v239 offset:10240
	v_pk_add_f32 v[150:151], v[150:151], v[88:89]
	v_pk_add_f32 v[150:151], v[150:151], v[90:91]
	v_cvt_pk_bf16_f32 v86, v88, v89
	v_cvt_pk_bf16_f32 v87, v90, v91
	s_waitcnt lgkmcnt(10)
	v_mfma_f32_32x32x16_bf16 v[52:67], v[192:195], v[132:135], v[52:67]
	ds_read_b64_tr_b16 v[132:133], v236 offset:12288
	ds_read_b64_tr_b16 v[134:135], v236 offset:14336
	v_exp_f32_e32 v92, v92
	v_exp_f32_e32 v93, v93
	s_waitcnt lgkmcnt(10)
	v_mfma_f32_32x32x16_bf16 v[68:83], v[192:195], v[136:139], v[68:83]
	ds_read_b64_tr_b16 v[136:137], v237 offset:12288
	ds_read_b64_tr_b16 v[138:139], v237 offset:14336
	s_add_u32 m0, s29, s11
	s_nop 0
	global_load_lds_dwordx4 v160, s[8:9]
	v_exp_f32_e32 v94, v94
	v_exp_f32_e32 v95, v95
	s_waitcnt lgkmcnt(10)
	v_mfma_f32_32x32x16_bf16 v[20:35], v[204:207], v[140:143], v[20:35]
	ds_read_b64_tr_b16 v[140:141], v238 offset:12288
	ds_read_b64_tr_b16 v[142:143], v238 offset:14336
	v_pk_add_f32 v[150:151], v[150:151], v[92:93]
	v_pk_add_f32 v[150:151], v[150:151], v[94:95]
	v_exp_f32_e32 v96, v96
	s_waitcnt lgkmcnt(10)
	v_mfma_f32_32x32x16_bf16 v[36:51], v[204:207], v[144:147], v[36:51]
	ds_read_b64_tr_b16 v[144:145], v239 offset:12288
	ds_read_b64_tr_b16 v[146:147], v239 offset:14336
	v_exp_f32_e32 v97, v97
	v_cvt_pk_bf16_f32 v88, v92, v93
	v_cvt_pk_bf16_f32 v89, v94, v95
	s_waitcnt lgkmcnt(10)
	v_mfma_f32_32x32x16_bf16 v[52:67], v[204:207], v[220:223], v[52:67]
	ds_read_b128 v[220:223], v232
	v_exp_f32_e32 v98, v98
	v_exp_f32_e32 v99, v99
	s_waitcnt lgkmcnt(9)
	v_mfma_f32_32x32x16_bf16 v[68:83], v[204:207], v[224:227], v[68:83]
	ds_read_b128 v[224:227], v232 offset:8192
	v_pk_add_f32 v[150:151], v[150:151], v[96:97]
	v_pk_add_f32 v[150:151], v[150:151], v[98:99]
	v_cvt_pk_bf16_f32 v90, v96, v97
	v_cvt_pk_bf16_f32 v91, v98, v99
	s_waitcnt lgkmcnt(8)
	v_mfma_f32_32x32x16_bf16 v[20:35], v[208:211], v[132:135], v[20:35]
	ds_read_b128 v[132:135], v233
	v_exp_f32_e32 v100, v100
	v_exp_f32_e32 v101, v101
	s_waitcnt lgkmcnt(7)
	v_mfma_f32_32x32x16_bf16 v[36:51], v[208:211], v[136:139], v[36:51]
	ds_read_b128 v[136:139], v233 offset:8192
	v_exp_f32_e32 v102, v102
	v_exp_f32_e32 v103, v103
	s_waitcnt lgkmcnt(6)
	v_mfma_f32_32x32x16_bf16 v[52:67], v[208:211], v[140:143], v[52:67]
	ds_read_b128 v[140:143], v234
	v_pk_add_f32 v[150:151], v[150:151], v[100:101]
	v_pk_add_f32 v[150:151], v[150:151], v[102:103]
	v_exp_f32_e32 v104, v104
	s_waitcnt lgkmcnt(5)
	v_mfma_f32_32x32x16_bf16 v[68:83], v[208:211], v[144:147], v[68:83]
	ds_read_b128 v[144:147], v234 offset:8192
	s_add_u32 m0, s29, s11
	s_add_u32 m0, m0, 0x2000
	s_nop 0
	global_load_lds_dwordx4 v176, s[8:9]
	v_exp_f32_e32 v105, v105
	v_cvt_pk_bf16_f32 v100, v100, v101
	v_cvt_pk_bf16_f32 v101, v102, v103
	s_waitcnt lgkmcnt(5)
	v_mfma_f32_32x32x16_bf16 v[188:203], v[220:223], v[116:119], v[2:17]
	ds_read_b128 v[220:223], v235
	v_exp_f32_e32 v106, v106
	v_exp_f32_e32 v107, v107
	s_waitcnt lgkmcnt(5)
	v_mfma_f32_32x32x16_bf16 v[204:219], v[224:227], v[116:119], v[2:17]
	ds_read_b128 v[224:227], v235 offset:8192
	v_pk_add_f32 v[150:151], v[150:151], v[104:105]
	v_pk_add_f32 v[150:151], v[150:151], v[106:107]
	v_cvt_pk_bf16_f32 v102, v104, v105
	v_cvt_pk_bf16_f32 v103, v106, v107
	s_waitcnt lgkmcnt(5)
	v_mfma_f32_32x32x16_bf16 v[188:203], v[132:135], v[120:123], v[188:203]
	v_exp_f32_e32 v108, v108
	v_exp_f32_e32 v109, v109
	s_waitcnt lgkmcnt(4)
	v_mfma_f32_32x32x16_bf16 v[204:219], v[136:139], v[120:123], v[204:219]
	v_exp_f32_e32 v110, v110
	v_exp_f32_e32 v111, v111
	s_waitcnt lgkmcnt(3)
	v_mfma_f32_32x32x16_bf16 v[188:203], v[140:143], v[124:127], v[188:203]
	v_pk_add_f32 v[150:151], v[150:151], v[108:109]
	v_pk_add_f32 v[150:151], v[150:151], v[110:111]
	v_exp_f32_e32 v112, v112
	s_waitcnt lgkmcnt(2)
	v_mfma_f32_32x32x16_bf16 v[204:219], v[144:147], v[124:127], v[204:219]
	v_exp_f32_e32 v113, v113
	v_cvt_pk_bf16_f32 v104, v108, v109
	v_cvt_pk_bf16_f32 v105, v110, v111
	s_waitcnt lgkmcnt(1)
	v_mfma_f32_32x32x16_bf16 v[188:203], v[220:223], v[128:131], v[188:203]
	v_exp_f32_e32 v114, v114
	v_exp_f32_e32 v115, v115
	s_waitcnt lgkmcnt(0)
	v_mfma_f32_32x32x16_bf16 v[204:219], v[224:227], v[128:131], v[204:219]
	v_pk_add_f32 v[150:151], v[150:151], v[112:113]
	v_pk_add_f32 v[150:151], v[150:151], v[114:115]
	v_cvt_pk_bf16_f32 v106, v112, v113
	v_cvt_pk_bf16_f32 v107, v114, v115
	s_mov_b32 s42, s10
	s_mov_b32 s10, s11
	s_mov_b32 s11, s31
	s_mov_b32 s31, s42
	s_add_u32 s8, s8, 0x40000
	s_addc_u32 s9, s9, 0
	s_add_i32 s35, s35, 64
	s_mov_b32 s38, s40
	s_waitcnt vmcnt(2) lgkmcnt(0)
	s_barrier
	s_cmp_eq_u32 s38, 0
	s_cbranch_scc1 .LatA_near_x1
; #define LAS __attribute__((address_space(3)))
; __device__ __forceinline__ void attn_unit(LAS unsigned char* lds, const bf16_t* Z, bf16_t* A2, const float* tabg, int seq_base, int S, int h, int qb, float lam) {
;     ...
;         const unsigned vbase = (unsigned)(size_t)Vt + vfo;
;         s16x4 va[8], vb[8];
;         VREADS1(va, 0);
;         if (near) {
;             const LAS float* tp = tab + (kv0 + 4 * hi - (qlo + r32) + 224);
; #pragma unroll
;             for (int r = 0; r < 16; ++r) { p0[r] += tp[(r & 3) + 8 * (r >> 2)]; p1[r] += tp[32 + (r & 3) + 8 * (r >> 2)]; }
;         }
;         float mx = max2f(max16f(p0), max16f(p1));
;         const bool first = (t == 0);
;         if (first || __any(mx > THR)) {
;             { auto rr = __builtin_amdgcn_permlane32_swap(__float_as_uint(mx), __float_as_uint(mx), false, false); mx = max2f(__uint_as_float(rr[0]), __uint_as_float(rr[1])); }
;             const float delta = first ? mx : fmaxf(mx, 0.f);
;             const float alpha = first ? 1.0f : __builtin_amdgcn_exp2f(-delta);
;             mu += delta; ls2 *= alpha;
;             if (!first) {
;                 asm volatile("" ::: "memory");
;                 scr[r32] = alpha;
;                 asm volatile("s_waitcnt lgkmcnt(0)" ::: "memory");
; #pragma unroll
;                 for (int g = 0; g < 4; ++g) { const f32x4 a4 = *(const LAS f32x4*)(scr + 8 * g + 4 * hi);
; #pragma unroll
;                     for (int d = 0; d < 4; ++d) { O[d][4 * g + 0] *= a4[0]; O[d][4 * g + 1] *= a4[1]; O[d][4 * g + 2] *= a4[2]; O[d][4 * g + 3] *= a4[3]; } }
;                 asm volatile("s_waitcnt lgkmcnt(0)" ::: "memory");
;             }
; #pragma unroll
;             for (int r = 0; r < 16; ++r) { p0[r] -= delta; p1[r] -= delta; }
;             asm volatile("" : "+v"(p0), "+v"(p1));
;         }
; #pragma unroll
;         for (int r = 0; r < 16; ++r) { p0[r] = __builtin_amdgcn_exp2f(p0[r]); p1[r] = __builtin_amdgcn_exp2f(p1[r]); }
; #pragma unroll
;         for (int r = 0; r < 16; r += 2) { ls2 += (f32x2){p0[r], p0[r + 1]}; ls2 += (f32x2){p1[r], p1[r + 1]}; }
;         bf16x8 pa[4]; pa[0] = pack8(p0, 0); pa[1] = pack8(p0, 8); pa[2] = pack8(p1, 0); pa[3] = pack8(p1, 8);
;         LGKM0(); VREADS1(vb, 1); PV1(va, 0); LGKM0(); VREADS1(va, 2); PV1(vb, 1); LGKM0(); VREADS1(vb, 3); PV1(va, 2); LGKM0(); PV1(vb, 3);
.LatA_nearret_x1:
	v_add_u32_e32 v236, s31, v228
	v_add_u32_e32 v237, s31, v229
	v_add_u32_e32 v238, s31, v230
	v_add_u32_e32 v239, s31, v231
	ds_read_b64_tr_b16 v[132:133], v236 offset:0
	ds_read_b64_tr_b16 v[134:135], v236 offset:2048
	ds_read_b64_tr_b16 v[136:137], v237 offset:0
	ds_read_b64_tr_b16 v[138:139], v237 offset:2048
	ds_read_b64_tr_b16 v[140:141], v238 offset:0
	ds_read_b64_tr_b16 v[142:143], v238 offset:2048
	ds_read_b64_tr_b16 v[144:145], v239 offset:0
	ds_read_b64_tr_b16 v[146:147], v239 offset:2048
	ds_read_b64_tr_b16 v[220:221], v236 offset:4096
	ds_read_b64_tr_b16 v[222:223], v236 offset:6144
	ds_read_b64_tr_b16 v[224:225], v237 offset:4096
	ds_read_b64_tr_b16 v[226:227], v237 offset:6144
	v_max3_f32 v251, v188, v189, v190
	v_max3_f32 v252, v191, v192, v193
	v_max3_f32 v251, v251, v194, v195
	v_max3_f32 v252, v252, v196, v197
	v_max3_f32 v251, v251, v198, v199
	v_max3_f32 v252, v252, v200, v201
	v_max3_f32 v251, v251, v202, v203
	v_max3_f32 v252, v252, v204, v205
	v_max3_f32 v251, v251, v206, v207
	v_max3_f32 v252, v252, v208, v209
	v_max3_f32 v251, v251, v210, v211
	v_max3_f32 v252, v252, v212, v213
	v_max3_f32 v251, v251, v214, v215
	v_max3_f32 v252, v252, v216, v217
	v_max3_f32 v251, v251, v218, v219
	v_max_f32_e32 v251, v251, v252
	s_nop 0
	v_cmp_lt_f32_e32 vcc, 0x41000000, v251
	s_cbranch_vccnz .LatA_rare_x1
.LatA_rareret_x1:
	s_waitcnt lgkmcnt(10)
	v_mfma_f32_32x32x16_bf16 v[20:35], v[84:87], v[132:135], v[20:35]
	ds_read_b64_tr_b16 v[132:133], v238 offset:4096
	ds_read_b64_tr_b16 v[134:135], v238 offset:6144
	v_exp_f32_e32 v188, v188
	v_exp_f32_e32 v189, v189
	v_exp_f32_e32 v190, v190
	s_waitcnt lgkmcnt(10)
	v_mfma_f32_32x32x16_bf16 v[36:51], v[84:87], v[136:139], v[36:51]
	ds_read_b64_tr_b16 v[136:137], v239 offset:4096
	ds_read_b64_tr_b16 v[138:139], v239 offset:6144
	v_exp_f32_e32 v191, v191
	v_pk_add_f32 v[150:151], v[150:151], v[188:189]
	v_pk_add_f32 v[150:151], v[150:151], v[190:191]
	v_exp_f32_e32 v192, v192
	s_waitcnt lgkmcnt(10)
	v_mfma_f32_32x32x16_bf16 v[52:67], v[84:87], v[140:143], v[52:67]
	ds_read_b64_tr_b16 v[140:141], v236 offset:8192
	ds_read_b64_tr_b16 v[142:143], v236 offset:10240
	v_exp_f32_e32 v193, v193
	v_cvt_pk_bf16_f32 v188, v188, v189
	v_cvt_pk_bf16_f32 v189, v190, v191
	v_exp_f32_e32 v194, v194
	s_waitcnt lgkmcnt(10)
	v_mfma_f32_32x32x16_bf16 v[68:83], v[84:87], v[144:147], v[68:83]
	ds_read_b64_tr_b16 v[144:145], v237 offset:8192
	ds_read_b64_tr_b16 v[146:147], v237 offset:10240
	v_exp_f32_e32 v195, v195
	v_pk_add_f32 v[150:151], v[150:151], v[192:193]
	v_pk_add_f32 v[150:151], v[150:151], v[194:195]
	v_cvt_pk_bf16_f32 v190, v192, v193
	v_cvt_pk_bf16_f32 v191, v194, v195
	s_waitcnt lgkmcnt(10)
	v_mfma_f32_32x32x16_bf16 v[20:35], v[88:91], v[220:223], v[20:35]
	ds_read_b64_tr_b16 v[220:221], v238 offset:8192
	ds_read_b64_tr_b16 v[222:223], v238 offset:10240
	v_exp_f32_e32 v196, v196
	v_exp_f32_e32 v197, v197
	v_exp_f32_e32 v198, v198
	s_waitcnt lgkmcnt(10)
	v_mfma_f32_32x32x16_bf16 v[36:51], v[88:91], v[224:227], v[36:51]
	ds_read_b64_tr_b16 v[224:225], v239 offset:8192
	ds_read_b64_tr_b16 v[226:227], v239 offset:10240
	v_exp_f32_e32 v199, v199
	v_pk_add_f32 v[150:151], v[150:151], v[196:197]
	v_pk_add_f32 v[150:151], v[150:151], v[198:199]
	v_exp_f32_e32 v200, v200
	s_waitcnt lgkmcnt(10)
	v_mfma_f32_32x32x16_bf16 v[52:67], v[88:91], v[132:135], v[52:67]
	ds_read_b64_tr_b16 v[132:133], v236 offset:12288
	ds_read_b64_tr_b16 v[134:135], v236 offset:14336
	v_exp_f32_e32 v201, v201
	v_cvt_pk_bf16_f32 v192, v196, v197
	v_cvt_pk_bf16_f32 v193, v198, v199
	v_exp_f32_e32 v202, v202
	s_waitcnt lgkmcnt(10)
	v_mfma_f32_32x32x16_bf16 v[68:83], v[88:91], v[136:139], v[68:83]
	ds_read_b64_tr_b16 v[136:137], v237 offset:12288
	ds_read_b64_tr_b16 v[138:139], v237 offset:14336
	v_exp_f32_e32 v203, v203
	v_pk_add_f32 v[150:151], v[150:151], v[200:201]
	v_pk_add_f32 v[150:151], v[150:151], v[202:203]
	v_cvt_pk_bf16_f32 v194, v200, v201
	v_cvt_pk_bf16_f32 v195, v202, v203
	s_waitcnt lgkmcnt(10)
	v_mfma_f32_32x32x16_bf16 v[20:35], v[100:103], v[140:143], v[20:35]
	ds_read_b64_tr_b16 v[140:141], v238 offset:12288
	ds_read_b64_tr_b16 v[142:143], v238 offset:14336
	v_exp_f32_e32 v204, v204
	v_exp_f32_e32 v205, v205
	v_exp_f32_e32 v206, v206
	s_waitcnt lgkmcnt(10)
	v_mfma_f32_32x32x16_bf16 v[36:51], v[100:103], v[144:147], v[36:51]
	ds_read_b64_tr_b16 v[144:145], v239 offset:12288
	ds_read_b64_tr_b16 v[146:147], v239 offset:14336
	v_exp_f32_e32 v207, v207
	v_pk_add_f32 v[150:151], v[150:151], v[204:205]
	v_pk_add_f32 v[150:151], v[150:151], v[206:207]
	v_exp_f32_e32 v208, v208
	s_waitcnt lgkmcnt(10)
	v_mfma_f32_32x32x16_bf16 v[52:67], v[100:103], v[220:223], v[52:67]
	v_exp_f32_e32 v209, v209
	v_cvt_pk_bf16_f32 v204, v204, v205
	v_cvt_pk_bf16_f32 v205, v206, v207
	v_exp_f32_e32 v210, v210
	s_waitcnt lgkmcnt(8)
	v_mfma_f32_32x32x16_bf16 v[68:83], v[100:103], v[224:227], v[68:83]
	v_exp_f32_e32 v211, v211
	v_pk_add_f32 v[150:151], v[150:151], v[208:209]
	v_pk_add_f32 v[150:151], v[150:151], v[210:211]
	v_cvt_pk_bf16_f32 v206, v208, v209
	v_cvt_pk_bf16_f32 v207, v210, v211
	s_waitcnt lgkmcnt(6)
	v_mfma_f32_32x32x16_bf16 v[20:35], v[104:107], v[132:135], v[20:35]
	v_exp_f32_e32 v212, v212
	v_exp_f32_e32 v213, v213
	v_exp_f32_e32 v214, v214
	s_waitcnt lgkmcnt(4)
	v_mfma_f32_32x32x16_bf16 v[36:51], v[104:107], v[136:139], v[36:51]
	v_exp_f32_e32 v215, v215
	v_pk_add_f32 v[150:151], v[150:151], v[212:213]
	v_pk_add_f32 v[150:151], v[150:151], v[214:215]
	v_exp_f32_e32 v216, v216
	s_waitcnt lgkmcnt(2)
	v_mfma_f32_32x32x16_bf16 v[52:67], v[104:107], v[140:143], v[52:67]
	v_exp_f32_e32 v217, v217
	v_cvt_pk_bf16_f32 v208, v212, v213
	v_cvt_pk_bf16_f32 v209, v214, v215
	v_exp_f32_e32 v218, v218
	s_waitcnt lgkmcnt(0)
	v_mfma_f32_32x32x16_bf16 v[68:83], v[104:107], v[144:147], v[68:83]
	v_exp_f32_e32 v219, v219
	v_pk_add_f32 v[150:151], v[150:151], v[216:217]
	v_pk_add_f32 v[150:151], v[150:151], v[218:219]
	v_cvt_pk_bf16_f32 v210, v216, v217
	v_cvt_pk_bf16_f32 v211, v218, v219
	s_mov_b32 s42, s10
	s_mov_b32 s10, s11
	s_mov_b32 s11, s31
	s_mov_b32 s31, s42
	s_add_u32 s8, s8, 0x40000
	s_addc_u32 s9, s9, 0
	s_add_i32 s35, s35, 64
	s_mov_b32 s38, s40
	s_waitcnt vmcnt(0) lgkmcnt(0)
	s_barrier
; #define VREADS1(arr, d_) do { const unsigned ad_ = vbase ^ (unsigned)((d_) << 6); __builtin_amdgcn_sched_barrier(0); \
;         _Pragma("unroll") for (int ks_ = 0; ks_ < 4; ++ks_) { VTR(arr[ks_ * 2], ad_, ks_ * 4096); VTR(arr[ks_ * 2 + 1], ad_, ks_ * 4096 + 2048); } __builtin_amdgcn_sched_barrier(0); } while (0)
; #define PV1(arr, d_) do { _Pragma("unroll") for (int ks_ = 0; ks_ < 4; ++ks_) { const s16x4 lo_ = arr[ks_ * 2], hh_ = arr[ks_ * 2 + 1]; \
;         const bf16x8 bv_ = (bf16x8){lo_[0], lo_[1], lo_[2], lo_[3], hh_[0], hh_[1], hh_[2], hh_[3]}; \
;         O[d_] = __builtin_amdgcn_mfma_f32_32x32x16_bf16(pa[ks_], bv_, O[d_], 0, 0, 0); } __builtin_amdgcn_sched_barrier(0); } while (0)
; #define LGKM0() do { __builtin_amdgcn_sched_barrier(0); asm volatile("s_waitcnt lgkmcnt(0)" ::: "memory"); __builtin_amdgcn_sched_barrier(0); } while (0)
; __device__ __forceinline__ void attn_unit(LAS unsigned char* lds, const bf16_t* Z, bf16_t* A2, const float* tabg, int seq_base, int S, int h, int qb, float lam) {
;     ...
;         if (kv0 - (qlo + 31) >= 128) { near = false; cc = tabR; } else if (qlo - (kv0 + 63) >= 128) { near = false; cc = tabL; }
;         { const float coff = cc - mu;
;           if (__any(!(coff == coff_cur))) { coff_cur = coff;
; #pragma unroll
;               for (int r = 0; r < 16; ++r) cblk[r] = coff;
;               asm volatile("" : "+v"(cblk)); } }
;     ...
;         LGKM0(); VREADS1(vb, 1); PV1(va, 0); LGKM0(); VREADS1(va, 2); PV1(vb, 1); LGKM0(); VREADS1(vb, 3); PV1(va, 2); LGKM0(); PV1(vb, 3);
;     ...
;         if (t + 2 < NT) asm volatile("s_waitcnt vmcnt(4) lgkmcnt(0)" ::: "memory"); else asm volatile("s_waitcnt vmcnt(0) lgkmcnt(0)" ::: "memory");
;         __builtin_amdgcn_s_barrier(); asm volatile("" ::: "memory");
	v_add_u32_e32 v236, s31, v228
	v_add_u32_e32 v237, s31, v229
	v_add_u32_e32 v238, s31, v230
	v_add_u32_e32 v239, s31, v231
	ds_read_b64_tr_b16 v[132:133], v236 offset:0
	ds_read_b64_tr_b16 v[134:135], v236 offset:2048
	ds_read_b64_tr_b16 v[136:137], v237 offset:0
	ds_read_b64_tr_b16 v[138:139], v237 offset:2048
	ds_read_b64_tr_b16 v[140:141], v238 offset:0
	ds_read_b64_tr_b16 v[142:143], v238 offset:2048
	ds_read_b64_tr_b16 v[144:145], v239 offset:0
	ds_read_b64_tr_b16 v[146:147], v239 offset:2048
	ds_read_b64_tr_b16 v[220:221], v236 offset:4096
	ds_read_b64_tr_b16 v[222:223], v236 offset:6144
	ds_read_b64_tr_b16 v[224:225], v237 offset:4096
	ds_read_b64_tr_b16 v[226:227], v237 offset:6144
	s_waitcnt lgkmcnt(10)
	v_mfma_f32_32x32x16_bf16 v[20:35], v[188:191], v[132:135], v[20:35]
	ds_read_b64_tr_b16 v[132:133], v238 offset:4096
	ds_read_b64_tr_b16 v[134:135], v238 offset:6144
	s_waitcnt lgkmcnt(10)
	v_mfma_f32_32x32x16_bf16 v[36:51], v[188:191], v[136:139], v[36:51]
	ds_read_b64_tr_b16 v[136:137], v239 offset:4096
	ds_read_b64_tr_b16 v[138:139], v239 offset:6144
	s_waitcnt lgkmcnt(10)
	v_mfma_f32_32x32x16_bf16 v[52:67], v[188:191], v[140:143], v[52:67]
	ds_read_b64_tr_b16 v[140:141], v236 offset:8192
	ds_read_b64_tr_b16 v[142:143], v236 offset:10240
	s_waitcnt lgkmcnt(10)
	v_mfma_f32_32x32x16_bf16 v[68:83], v[188:191], v[144:147], v[68:83]
	ds_read_b64_tr_b16 v[144:145], v237 offset:8192
	ds_read_b64_tr_b16 v[146:147], v237 offset:10240
	s_waitcnt lgkmcnt(10)
	v_mfma_f32_32x32x16_bf16 v[20:35], v[192:195], v[220:223], v[20:35]
	ds_read_b64_tr_b16 v[220:221], v238 offset:8192
	ds_read_b64_tr_b16 v[222:223], v238 offset:10240
	s_waitcnt lgkmcnt(10)
	v_mfma_f32_32x32x16_bf16 v[36:51], v[192:195], v[224:227], v[36:51]
	ds_read_b64_tr_b16 v[224:225], v239 offset:8192
	ds_read_b64_tr_b16 v[226:227], v239 offset:10240
	s_waitcnt lgkmcnt(10)
	v_mfma_f32_32x32x16_bf16 v[52:67], v[192:195], v[132:135], v[52:67]
	ds_read_b64_tr_b16 v[132:133], v236 offset:12288
	ds_read_b64_tr_b16 v[134:135], v236 offset:14336
	s_waitcnt lgkmcnt(10)
	v_mfma_f32_32x32x16_bf16 v[68:83], v[192:195], v[136:139], v[68:83]
	ds_read_b64_tr_b16 v[136:137], v237 offset:12288
	ds_read_b64_tr_b16 v[138:139], v237 offset:14336
	s_waitcnt lgkmcnt(10)
	v_mfma_f32_32x32x16_bf16 v[20:35], v[204:207], v[140:143], v[20:35]
	ds_read_b64_tr_b16 v[140:141], v238 offset:12288
	ds_read_b64_tr_b16 v[142:143], v238 offset:14336
	s_waitcnt lgkmcnt(10)
	v_mfma_f32_32x32x16_bf16 v[36:51], v[204:207], v[144:147], v[36:51]
	ds_read_b64_tr_b16 v[144:145], v239 offset:12288
	ds_read_b64_tr_b16 v[146:147], v239 offset:14336
	s_waitcnt lgkmcnt(10)
	v_mfma_f32_32x32x16_bf16 v[52:67], v[204:207], v[220:223], v[52:67]
	s_waitcnt lgkmcnt(8)
	v_mfma_f32_32x32x16_bf16 v[68:83], v[204:207], v[224:227], v[68:83]
	s_waitcnt lgkmcnt(6)
	v_mfma_f32_32x32x16_bf16 v[20:35], v[208:211], v[132:135], v[20:35]
	s_waitcnt lgkmcnt(4)
	v_mfma_f32_32x32x16_bf16 v[36:51], v[208:211], v[136:139], v[36:51]
	s_waitcnt lgkmcnt(2)
	v_mfma_f32_32x32x16_bf16 v[52:67], v[208:211], v[140:143], v[52:67]
	s_waitcnt lgkmcnt(0)
	v_mfma_f32_32x32x16_bf16 v[68:83], v[208:211], v[144:147], v[68:83]
	s_waitcnt lgkmcnt(0)
	s_barrier
	s_mov_b32 m0, s32
	s_nop 15
	s_branch .LatA_done
.LatA_rebuild_p0:
	s_mov_b32 s36, s40
	v_mov_b32_e32 v251, 0
	s_cmp_eq_u32 s40, 1
	s_cselect_b64 vcc, -1, 0
	v_cndmask_b32_e32 v251, v251, v177, vcc
	s_cmp_eq_u32 s40, 2
	s_cselect_b64 vcc, -1, 0
	v_cndmask_b32_e32 v251, v251, v178, vcc
	v_sub_f32_e32 v2, v251, v186
	v_mov_b32_e32 v3, v2
	v_mov_b64_e32 v[4:5], v[2:3]
	v_mov_b64_e32 v[6:7], v[2:3]
	v_mov_b64_e32 v[8:9], v[2:3]
	v_mov_b64_e32 v[10:11], v[2:3]
	v_mov_b64_e32 v[12:13], v[2:3]
	v_mov_b64_e32 v[14:15], v[2:3]
	v_mov_b64_e32 v[16:17], v[2:3]
	s_branch .LatA_rebuildret_p0
; #define LAS __attribute__((address_space(3)))
; __device__ __forceinline__ float max2f(float a, float b) { float r; asm("v_max_f32_e32 %0, %1, %2" : "=v"(r) : "v"(a), "v"(b)); return r; }
; __device__ __forceinline__ void attn_unit(LAS unsigned char* lds, const bf16_t* Z, bf16_t* A2, const float* tabg, int seq_base, int S, int h, int qb, float lam) {
;     ...
;         if (near) {
;             const LAS float* tp = tab + (kv0 + 4 * hi - (qlo + r32) + 224);
; #pragma unroll
;             for (int r = 0; r < 16; ++r) { p0[r] += tp[(r & 3) + 8 * (r >> 2)]; p1[r] += tp[32 + (r & 3) + 8 * (r >> 2)]; }
;         }
;         float mx = max2f(max16f(p0), max16f(p1));
;         const bool first = (t == 0);
;         if (first || __any(mx > THR)) {
;             { auto rr = __builtin_amdgcn_permlane32_swap(__float_as_uint(mx), __float_as_uint(mx), false, false); mx = max2f(__uint_as_float(rr[0]), __uint_as_float(rr[1])); }
;             const float delta = first ? mx : fmaxf(mx, 0.f);
;             const float alpha = first ? 1.0f : __builtin_amdgcn_exp2f(-delta);
;             mu += delta; ls2 *= alpha;
;             if (!first) {
;                 asm volatile("" ::: "memory");
;                 scr[r32] = alpha;
;                 asm volatile("s_waitcnt lgkmcnt(0)" ::: "memory");
; #pragma unroll
;                 for (int g = 0; g < 4; ++g) { const f32x4 a4 = *(const LAS f32x4*)(scr + 8 * g + 4 * hi);
; #pragma unroll
;                     for (int d = 0; d < 4; ++d) { O[d][4 * g + 0] *= a4[0]; O[d][4 * g + 1] *= a4[1]; O[d][4 * g + 2] *= a4[2]; O[d][4 * g + 3] *= a4[3]; } }
;                 asm volatile("s_waitcnt lgkmcnt(0)" ::: "memory");
;             }
; #pragma unroll
;             for (int r = 0; r < 16; ++r) { p0[r] -= delta; p1[r] -= delta; }
.LatA_near_p0:
	s_lshl_b32 s42, s35, 2
	s_add_i32 s42, s42, 0x18b80
	v_add_u32_e32 v187, s42, v162
	ds_read2_b32 v[132:133], v187 offset0:0 offset1:1
	ds_read2_b32 v[134:135], v187 offset0:2 offset1:3
	ds_read2_b32 v[136:137], v187 offset0:8 offset1:9
	ds_read2_b32 v[138:139], v187 offset0:10 offset1:11
	s_waitcnt lgkmcnt(0)
	v_pk_add_f32 v[84:85], v[84:85], v[132:133]
	v_pk_add_f32 v[86:87], v[86:87], v[134:135]
	v_pk_add_f32 v[88:89], v[88:89], v[136:137]
	v_pk_add_f32 v[90:91], v[90:91], v[138:139]
	ds_read2_b32 v[132:133], v187 offset0:16 offset1:17
	ds_read2_b32 v[134:135], v187 offset0:18 offset1:19
	ds_read2_b32 v[136:137], v187 offset0:24 offset1:25
	ds_read2_b32 v[138:139], v187 offset0:26 offset1:27
	s_waitcnt lgkmcnt(0)
	v_pk_add_f32 v[92:93], v[92:93], v[132:133]
	v_pk_add_f32 v[94:95], v[94:95], v[134:135]
	v_pk_add_f32 v[96:97], v[96:97], v[136:137]
	v_pk_add_f32 v[98:99], v[98:99], v[138:139]
	ds_read2_b32 v[132:133], v187 offset0:32 offset1:33
	ds_read2_b32 v[134:135], v187 offset0:34 offset1:35
	ds_read2_b32 v[136:137], v187 offset0:40 offset1:41
	ds_read2_b32 v[138:139], v187 offset0:42 offset1:43
	s_waitcnt lgkmcnt(0)
	v_pk_add_f32 v[100:101], v[100:101], v[132:133]
	v_pk_add_f32 v[102:103], v[102:103], v[134:135]
	v_pk_add_f32 v[104:105], v[104:105], v[136:137]
	v_pk_add_f32 v[106:107], v[106:107], v[138:139]
	ds_read2_b32 v[132:133], v187 offset0:48 offset1:49
	ds_read2_b32 v[134:135], v187 offset0:50 offset1:51
	ds_read2_b32 v[136:137], v187 offset0:56 offset1:57
	ds_read2_b32 v[138:139], v187 offset0:58 offset1:59
	s_waitcnt lgkmcnt(0)
	v_pk_add_f32 v[108:109], v[108:109], v[132:133]
	v_pk_add_f32 v[110:111], v[110:111], v[134:135]
	v_pk_add_f32 v[112:113], v[112:113], v[136:137]
	v_pk_add_f32 v[114:115], v[114:115], v[138:139]
	s_branch .LatA_nearret_p0
.LatA_rare_t0:
	v_mov_b32_e32 v252, v251
	s_nop 1
	v_permlane32_swap_b32_e32 v251, v252
	v_max_f32_e32 v251, v251, v252
	v_max_f32_e32 v253, 0, v251
	v_exp_f32_e64 v254, -v253
	v_add_f32_e32 v186, v186, v253
	s_nop 0
	v_mul_f32_e32 v150, v150, v254
	v_mul_f32_e32 v151, v151, v254
	ds_write_b32 v184, v254
	s_waitcnt lgkmcnt(0)
	ds_read_b128 v[196:199], v185
	ds_read_b128 v[200:203], v185 offset:32
	ds_read_b128 v[212:215], v185 offset:64
	ds_read_b128 v[216:219], v185 offset:96
	s_waitcnt lgkmcnt(0)
	s_nop 15
	s_nop 15
	v_mul_f32_e32 v20, v20, v196
	v_mul_f32_e32 v21, v21, v197
	v_mul_f32_e32 v22, v22, v198
	v_mul_f32_e32 v23, v23, v199
	v_mul_f32_e32 v24, v24, v200
	v_mul_f32_e32 v25, v25, v201
	v_mul_f32_e32 v26, v26, v202
	v_mul_f32_e32 v27, v27, v203
	v_mul_f32_e32 v28, v28, v212
	v_mul_f32_e32 v29, v29, v213
	v_mul_f32_e32 v30, v30, v214
	v_mul_f32_e32 v31, v31, v215
	v_mul_f32_e32 v32, v32, v216
	v_mul_f32_e32 v33, v33, v217
	v_mul_f32_e32 v34, v34, v218
	v_mul_f32_e32 v35, v35, v219
	v_mul_f32_e32 v36, v36, v196
	v_mul_f32_e32 v37, v37, v197
	v_mul_f32_e32 v38, v38, v198
	v_mul_f32_e32 v39, v39, v199
	v_mul_f32_e32 v40, v40, v200
	v_mul_f32_e32 v41, v41, v201
	v_mul_f32_e32 v42, v42, v202
	v_mul_f32_e32 v43, v43, v203
	v_mul_f32_e32 v44, v44, v212
	v_mul_f32_e32 v45, v45, v213
	v_mul_f32_e32 v46, v46, v214
	v_mul_f32_e32 v47, v47, v215
	v_mul_f32_e32 v48, v48, v216
	v_mul_f32_e32 v49, v49, v217
	v_mul_f32_e32 v50, v50, v218
	v_mul_f32_e32 v51, v51, v219
	v_mul_f32_e32 v52, v52, v196
	v_mul_f32_e32 v53, v53, v197
	v_mul_f32_e32 v54, v54, v198
	v_mul_f32_e32 v55, v55, v199
	v_mul_f32_e32 v56, v56, v200
	v_mul_f32_e32 v57, v57, v201
	v_mul_f32_e32 v58, v58, v202
	v_mul_f32_e32 v59, v59, v203
	v_mul_f32_e32 v60, v60, v212
	v_mul_f32_e32 v61, v61, v213
	v_mul_f32_e32 v62, v62, v214
	v_mul_f32_e32 v63, v63, v215
	v_mul_f32_e32 v64, v64, v216
	v_mul_f32_e32 v65, v65, v217
	v_mul_f32_e32 v66, v66, v218
	v_mul_f32_e32 v67, v67, v219
	v_mul_f32_e32 v68, v68, v196
	v_mul_f32_e32 v69, v69, v197
	v_mul_f32_e32 v70, v70, v198
	v_mul_f32_e32 v71, v71, v199
	v_mul_f32_e32 v72, v72, v200
	v_mul_f32_e32 v73, v73, v201
	v_mul_f32_e32 v74, v74, v202
	v_mul_f32_e32 v75, v75, v203
	v_mul_f32_e32 v76, v76, v212
	v_mul_f32_e32 v77, v77, v213
	v_mul_f32_e32 v78, v78, v214
	v_mul_f32_e32 v79, v79, v215
	v_mul_f32_e32 v80, v80, v216
	v_mul_f32_e32 v81, v81, v217
	v_mul_f32_e32 v82, v82, v218
	v_mul_f32_e32 v83, v83, v219
	v_sub_f32_e32 v84, v84, v253
	v_sub_f32_e32 v85, v85, v253
	v_sub_f32_e32 v86, v86, v253
	v_sub_f32_e32 v87, v87, v253
	v_sub_f32_e32 v88, v88, v253
	v_sub_f32_e32 v89, v89, v253
	v_sub_f32_e32 v90, v90, v253
	v_sub_f32_e32 v91, v91, v253
	v_sub_f32_e32 v92, v92, v253
	v_sub_f32_e32 v93, v93, v253
	v_sub_f32_e32 v94, v94, v253
	v_sub_f32_e32 v95, v95, v253
	v_sub_f32_e32 v96, v96, v253
	v_sub_f32_e32 v97, v97, v253
	v_sub_f32_e32 v98, v98, v253
	v_sub_f32_e32 v99, v99, v253
	v_sub_f32_e32 v100, v100, v253
	v_sub_f32_e32 v101, v101, v253
	v_sub_f32_e32 v102, v102, v253
	v_sub_f32_e32 v103, v103, v253
	v_sub_f32_e32 v104, v104, v253
	v_sub_f32_e32 v105, v105, v253
	v_sub_f32_e32 v106, v106, v253
	v_sub_f32_e32 v107, v107, v253
	v_sub_f32_e32 v108, v108, v253
	v_sub_f32_e32 v109, v109, v253
	v_sub_f32_e32 v110, v110, v253
	v_sub_f32_e32 v111, v111, v253
	v_sub_f32_e32 v112, v112, v253
	v_sub_f32_e32 v113, v113, v253
	v_sub_f32_e32 v114, v114, v253
	v_sub_f32_e32 v115, v115, v253
	s_mov_b32 s36, -1
	s_branch .LatA_rareret_t0

; #define LAS __attribute__((address_space(3)))
; __device__ __forceinline__ void attn_unit(LAS unsigned char* lds, const bf16_t* Z, bf16_t* A2, const float* tabg, int seq_base, int S, int h, int qb, float lam) {
;     ...
;         if (near) {
;             const LAS float* tp = tab + (kv0 + 4 * hi - (qlo + r32) + 224);
; #pragma unroll
;             for (int r = 0; r < 16; ++r) { p0[r] += tp[(r & 3) + 8 * (r >> 2)]; p1[r] += tp[32 + (r & 3) + 8 * (r >> 2)]; }
;         }
.LatA_near_t1:
	s_lshl_b32 s42, s35, 2
	s_add_i32 s42, s42, 0x18b80
	v_add_u32_e32 v187, s42, v162
	ds_read2_b32 v[132:133], v187 offset0:0 offset1:1
	ds_read2_b32 v[134:135], v187 offset0:2 offset1:3
	ds_read2_b32 v[136:137], v187 offset0:8 offset1:9
	ds_read2_b32 v[138:139], v187 offset0:10 offset1:11
	s_waitcnt lgkmcnt(0)
	v_pk_add_f32 v[188:189], v[188:189], v[132:133]
	v_pk_add_f32 v[190:191], v[190:191], v[134:135]
	v_pk_add_f32 v[192:193], v[192:193], v[136:137]
	v_pk_add_f32 v[194:195], v[194:195], v[138:139]
	ds_read2_b32 v[132:133], v187 offset0:16 offset1:17
	ds_read2_b32 v[134:135], v187 offset0:18 offset1:19
	ds_read2_b32 v[136:137], v187 offset0:24 offset1:25
	ds_read2_b32 v[138:139], v187 offset0:26 offset1:27
	s_waitcnt lgkmcnt(0)
	v_pk_add_f32 v[196:197], v[196:197], v[132:133]
	v_pk_add_f32 v[198:199], v[198:199], v[134:135]
	v_pk_add_f32 v[200:201], v[200:201], v[136:137]
	v_pk_add_f32 v[202:203], v[202:203], v[138:139]
	ds_read2_b32 v[132:133], v187 offset0:32 offset1:33
	ds_read2_b32 v[134:135], v187 offset0:34 offset1:35
	ds_read2_b32 v[136:137], v187 offset0:40 offset1:41
	ds_read2_b32 v[138:139], v187 offset0:42 offset1:43
	s_waitcnt lgkmcnt(0)
	v_pk_add_f32 v[204:205], v[204:205], v[132:133]
	v_pk_add_f32 v[206:207], v[206:207], v[134:135]
	v_pk_add_f32 v[208:209], v[208:209], v[136:137]
	v_pk_add_f32 v[210:211], v[210:211], v[138:139]
	ds_read2_b32 v[132:133], v187 offset0:48 offset1:49
	ds_read2_b32 v[134:135], v187 offset0:50 offset1:51
	ds_read2_b32 v[136:137], v187 offset0:56 offset1:57
	ds_read2_b32 v[138:139], v187 offset0:58 offset1:59
	s_waitcnt lgkmcnt(0)
	v_pk_add_f32 v[212:213], v[212:213], v[132:133]
	v_pk_add_f32 v[214:215], v[214:215], v[134:135]
	v_pk_add_f32 v[216:217], v[216:217], v[136:137]
	v_pk_add_f32 v[218:219], v[218:219], v[138:139]
	s_branch .LatA_nearret_t1
; #define LAS __attribute__((address_space(3)))
; __device__ __forceinline__ float max2f(float a, float b) { float r; asm("v_max_f32_e32 %0, %1, %2" : "=v"(r) : "v"(a), "v"(b)); return r; }
; #define VREADS1(arr, d_) do { const unsigned ad_ = vbase ^ (unsigned)((d_) << 6); __builtin_amdgcn_sched_barrier(0); \
;         _Pragma("unroll") for (int ks_ = 0; ks_ < 4; ++ks_) { VTR(arr[ks_ * 2], ad_, ks_ * 4096); VTR(arr[ks_ * 2 + 1], ad_, ks_ * 4096 + 2048); } __builtin_amdgcn_sched_barrier(0); } while (0)
; __device__ __forceinline__ void attn_unit(LAS unsigned char* lds, const bf16_t* Z, bf16_t* A2, const float* tabg, int seq_base, int S, int h, int qb, float lam) {
;     ...
;         if (first || __any(mx > THR)) {
;             { auto rr = __builtin_amdgcn_permlane32_swap(__float_as_uint(mx), __float_as_uint(mx), false, false); mx = max2f(__uint_as_float(rr[0]), __uint_as_float(rr[1])); }
;             const float delta = first ? mx : fmaxf(mx, 0.f);
;             const float alpha = first ? 1.0f : __builtin_amdgcn_exp2f(-delta);
;             mu += delta; ls2 *= alpha;
;             if (!first) {
;                 asm volatile("" ::: "memory");
;                 scr[r32] = alpha;
;                 asm volatile("s_waitcnt lgkmcnt(0)" ::: "memory");
; #pragma unroll
;                 for (int g = 0; g < 4; ++g) { const f32x4 a4 = *(const LAS f32x4*)(scr + 8 * g + 4 * hi);
; #pragma unroll
;                     for (int d = 0; d < 4; ++d) { O[d][4 * g + 0] *= a4[0]; O[d][4 * g + 1] *= a4[1]; O[d][4 * g + 2] *= a4[2]; O[d][4 * g + 3] *= a4[3]; } }
;                 asm volatile("s_waitcnt lgkmcnt(0)" ::: "memory");
;             }
; #pragma unroll
;             for (int r = 0; r < 16; ++r) { p0[r] -= delta; p1[r] -= delta; }
;             asm volatile("" : "+v"(p0), "+v"(p1));
;         }
; #pragma unroll
;         for (int r = 0; r < 16; ++r) { p0[r] = __builtin_amdgcn_exp2f(p0[r]); p1[r] = __builtin_amdgcn_exp2f(p1[r]); }
; #pragma unroll
;         for (int r = 0; r < 16; r += 2) { ls2 += (f32x2){p0[r], p0[r + 1]}; ls2 += (f32x2){p1[r], p1[r + 1]}; }
;         bf16x8 pa[4]; pa[0] = pack8(p0, 0); pa[1] = pack8(p0, 8); pa[2] = pack8(p1, 0); pa[3] = pack8(p1, 8);
;         LGKM0(); VREADS1(vb, 1); PV1(va, 0); LGKM0(); VREADS1(va, 2); PV1(vb, 1); LGKM0(); VREADS1(vb, 3); PV1(va, 2); LGKM0(); PV1(vb, 3);
.LatA_rare_t1:
	v_mov_b32_e32 v252, v251
	s_nop 1
	v_permlane32_swap_b32_e32 v251, v252
	v_max_f32_e32 v251, v251, v252
	v_max_f32_e32 v253, 0, v251
	v_exp_f32_e64 v254, -v253
	v_add_f32_e32 v186, v186, v253
	s_nop 0
	v_mul_f32_e32 v150, v150, v254
	v_mul_f32_e32 v151, v151, v254
	ds_write_b32 v184, v254
	s_waitcnt lgkmcnt(0)
	v_mfma_f32_32x32x16_bf16 v[20:35], v[84:87], v[132:135], v[20:35]
	v_mfma_f32_32x32x16_bf16 v[36:51], v[84:87], v[136:139], v[36:51]
	v_mfma_f32_32x32x16_bf16 v[52:67], v[84:87], v[140:143], v[52:67]
	v_mfma_f32_32x32x16_bf16 v[68:83], v[84:87], v[144:147], v[68:83]
	v_mfma_f32_32x32x16_bf16 v[20:35], v[88:91], v[220:223], v[20:35]
	v_mfma_f32_32x32x16_bf16 v[36:51], v[88:91], v[224:227], v[36:51]
	ds_read_b64_tr_b16 v[132:133], v238 offset:4096
	ds_read_b64_tr_b16 v[134:135], v238 offset:6144
	ds_read_b64_tr_b16 v[136:137], v239 offset:4096
	ds_read_b64_tr_b16 v[138:139], v239 offset:6144
	ds_read_b64_tr_b16 v[140:141], v236 offset:8192
	ds_read_b64_tr_b16 v[142:143], v236 offset:10240
	ds_read_b64_tr_b16 v[144:145], v237 offset:8192
	ds_read_b64_tr_b16 v[146:147], v237 offset:10240
	ds_read_b64_tr_b16 v[220:221], v238 offset:8192
	ds_read_b64_tr_b16 v[222:223], v238 offset:10240
	ds_read_b64_tr_b16 v[224:225], v239 offset:8192
	ds_read_b64_tr_b16 v[226:227], v239 offset:10240
	s_waitcnt lgkmcnt(0)
	v_mfma_f32_32x32x16_bf16 v[52:67], v[88:91], v[132:135], v[52:67]
	v_mfma_f32_32x32x16_bf16 v[68:83], v[88:91], v[136:139], v[68:83]
	v_mfma_f32_32x32x16_bf16 v[20:35], v[100:103], v[140:143], v[20:35]
	v_mfma_f32_32x32x16_bf16 v[36:51], v[100:103], v[144:147], v[36:51]
	v_mfma_f32_32x32x16_bf16 v[52:67], v[100:103], v[220:223], v[52:67]
	v_mfma_f32_32x32x16_bf16 v[68:83], v[100:103], v[224:227], v[68:83]
	ds_read_b64_tr_b16 v[132:133], v236 offset:12288
	ds_read_b64_tr_b16 v[134:135], v236 offset:14336
	ds_read_b64_tr_b16 v[136:137], v237 offset:12288
	ds_read_b64_tr_b16 v[138:139], v237 offset:14336
	ds_read_b64_tr_b16 v[140:141], v238 offset:12288
	ds_read_b64_tr_b16 v[142:143], v238 offset:14336
	ds_read_b64_tr_b16 v[144:145], v239 offset:12288
	ds_read_b64_tr_b16 v[146:147], v239 offset:14336
	s_waitcnt lgkmcnt(0)
	v_mfma_f32_32x32x16_bf16 v[20:35], v[104:107], v[132:135], v[20:35]
	v_mfma_f32_32x32x16_bf16 v[36:51], v[104:107], v[136:139], v[36:51]
	v_mfma_f32_32x32x16_bf16 v[52:67], v[104:107], v[140:143], v[52:67]
	v_mfma_f32_32x32x16_bf16 v[68:83], v[104:107], v[144:147], v[68:83]
	ds_read_b128 v[92:95], v185
	ds_read_b128 v[96:99], v185 offset:32
	ds_read_b128 v[108:111], v185 offset:64
	ds_read_b128 v[112:115], v185 offset:96
	s_waitcnt lgkmcnt(0)
	s_nop 15
	s_nop 15
	v_mul_f32_e32 v20, v20, v92
	v_mul_f32_e32 v21, v21, v93
	v_mul_f32_e32 v22, v22, v94
	v_mul_f32_e32 v23, v23, v95
	v_mul_f32_e32 v24, v24, v96
	v_mul_f32_e32 v25, v25, v97
	v_mul_f32_e32 v26, v26, v98
	v_mul_f32_e32 v27, v27, v99
	v_mul_f32_e32 v28, v28, v108
	v_mul_f32_e32 v29, v29, v109
	v_mul_f32_e32 v30, v30, v110
	v_mul_f32_e32 v31, v31, v111
	v_mul_f32_e32 v32, v32, v112
	v_mul_f32_e32 v33, v33, v113
	v_mul_f32_e32 v34, v34, v114
	v_mul_f32_e32 v35, v35, v115
	v_mul_f32_e32 v36, v36, v92
	v_mul_f32_e32 v37, v37, v93
	v_mul_f32_e32 v38, v38, v94
	v_mul_f32_e32 v39, v39, v95
	v_mul_f32_e32 v40, v40, v96
	v_mul_f32_e32 v41, v41, v97
	v_mul_f32_e32 v42, v42, v98
	v_mul_f32_e32 v43, v43, v99
	v_mul_f32_e32 v44, v44, v108
	v_mul_f32_e32 v45, v45, v109
	v_mul_f32_e32 v46, v46, v110
	v_mul_f32_e32 v47, v47, v111
	v_mul_f32_e32 v48, v48, v112
	v_mul_f32_e32 v49, v49, v113
	v_mul_f32_e32 v50, v50, v114
	v_mul_f32_e32 v51, v51, v115
	v_mul_f32_e32 v52, v52, v92
	v_mul_f32_e32 v53, v53, v93
	v_mul_f32_e32 v54, v54, v94
	v_mul_f32_e32 v55, v55, v95
	v_mul_f32_e32 v56, v56, v96
	v_mul_f32_e32 v57, v57, v97
	v_mul_f32_e32 v58, v58, v98
	v_mul_f32_e32 v59, v59, v99
	v_mul_f32_e32 v60, v60, v108
	v_mul_f32_e32 v61, v61, v109
	v_mul_f32_e32 v62, v62, v110
	v_mul_f32_e32 v63, v63, v111
	v_mul_f32_e32 v64, v64, v112
	v_mul_f32_e32 v65, v65, v113
	v_mul_f32_e32 v66, v66, v114
	v_mul_f32_e32 v67, v67, v115
	v_mul_f32_e32 v68, v68, v92
	v_mul_f32_e32 v69, v69, v93
	v_mul_f32_e32 v70, v70, v94
	v_mul_f32_e32 v71, v71, v95
	v_mul_f32_e32 v72, v72, v96
	v_mul_f32_e32 v73, v73, v97
	v_mul_f32_e32 v74, v74, v98
	v_mul_f32_e32 v75, v75, v99
	v_mul_f32_e32 v76, v76, v108
	v_mul_f32_e32 v77, v77, v109
	v_mul_f32_e32 v78, v78, v110
	v_mul_f32_e32 v79, v79, v111
	v_mul_f32_e32 v80, v80, v112
	v_mul_f32_e32 v81, v81, v113
	v_mul_f32_e32 v82, v82, v114
	v_mul_f32_e32 v83, v83, v115
	v_sub_f32_e32 v188, v188, v253
	v_sub_f32_e32 v189, v189, v253
	v_sub_f32_e32 v190, v190, v253
	v_sub_f32_e32 v191, v191, v253
	v_sub_f32_e32 v192, v192, v253
	v_sub_f32_e32 v193, v193, v253
	v_sub_f32_e32 v194, v194, v253
	v_sub_f32_e32 v195, v195, v253
	v_sub_f32_e32 v196, v196, v253
	v_sub_f32_e32 v197, v197, v253
	v_sub_f32_e32 v198, v198, v253
	v_sub_f32_e32 v199, v199, v253
	v_sub_f32_e32 v200, v200, v253
	v_sub_f32_e32 v201, v201, v253
	v_sub_f32_e32 v202, v202, v253
	v_sub_f32_e32 v203, v203, v253
	v_sub_f32_e32 v204, v204, v253
	v_sub_f32_e32 v205, v205, v253
	v_sub_f32_e32 v206, v206, v253
	v_sub_f32_e32 v207, v207, v253
	v_sub_f32_e32 v208, v208, v253
	v_sub_f32_e32 v209, v209, v253
	v_sub_f32_e32 v210, v210, v253
	v_sub_f32_e32 v211, v211, v253
	v_sub_f32_e32 v212, v212, v253
	v_sub_f32_e32 v213, v213, v253
	v_sub_f32_e32 v214, v214, v253
	v_sub_f32_e32 v215, v215, v253
	v_sub_f32_e32 v216, v216, v253
	v_sub_f32_e32 v217, v217, v253
	v_sub_f32_e32 v218, v218, v253
	v_sub_f32_e32 v219, v219, v253
	v_mov_b32_e32 v84, 0
	v_mov_b32_e32 v85, 0
	v_mov_b32_e32 v86, 0
	v_mov_b32_e32 v87, 0
	v_mov_b32_e32 v88, 0
	v_mov_b32_e32 v89, 0
	v_mov_b32_e32 v90, 0
	v_mov_b32_e32 v91, 0
	v_mov_b32_e32 v100, 0
	v_mov_b32_e32 v101, 0
	v_mov_b32_e32 v102, 0
	v_mov_b32_e32 v103, 0
	v_mov_b32_e32 v104, 0
	v_mov_b32_e32 v105, 0
	v_mov_b32_e32 v106, 0
	v_mov_b32_e32 v107, 0
	s_mov_b32 s36, -1
	s_branch .LatA_rareret_t1

; #define LAS __attribute__((address_space(3)))
; __device__ __forceinline__ float max2f(float a, float b) { float r; asm("v_max_f32_e32 %0, %1, %2" : "=v"(r) : "v"(a), "v"(b)); return r; }
; #define VREADS1(arr, d_) do { const unsigned ad_ = vbase ^ (unsigned)((d_) << 6); __builtin_amdgcn_sched_barrier(0); \
;         _Pragma("unroll") for (int ks_ = 0; ks_ < 4; ++ks_) { VTR(arr[ks_ * 2], ad_, ks_ * 4096); VTR(arr[ks_ * 2 + 1], ad_, ks_ * 4096 + 2048); } __builtin_amdgcn_sched_barrier(0); } while (0)
; __device__ __forceinline__ void attn_unit(LAS unsigned char* lds, const bf16_t* Z, bf16_t* A2, const float* tabg, int seq_base, int S, int h, int qb, float lam) {
;     ...
;         if (first || __any(mx > THR)) {
;             { auto rr = __builtin_amdgcn_permlane32_swap(__float_as_uint(mx), __float_as_uint(mx), false, false); mx = max2f(__uint_as_float(rr[0]), __uint_as_float(rr[1])); }
;             const float delta = first ? mx : fmaxf(mx, 0.f);
;             const float alpha = first ? 1.0f : __builtin_amdgcn_exp2f(-delta);
;             mu += delta; ls2 *= alpha;
;             if (!first) {
;                 asm volatile("" ::: "memory");
;                 scr[r32] = alpha;
;                 asm volatile("s_waitcnt lgkmcnt(0)" ::: "memory");
; #pragma unroll
;                 for (int g = 0; g < 4; ++g) { const f32x4 a4 = *(const LAS f32x4*)(scr + 8 * g + 4 * hi);
; #pragma unroll
;                     for (int d = 0; d < 4; ++d) { O[d][4 * g + 0] *= a4[0]; O[d][4 * g + 1] *= a4[1]; O[d][4 * g + 2] *= a4[2]; O[d][4 * g + 3] *= a4[3]; } }
;                 asm volatile("s_waitcnt lgkmcnt(0)" ::: "memory");
;             }
; #pragma unroll
;             for (int r = 0; r < 16; ++r) { p0[r] -= delta; p1[r] -= delta; }
;             asm volatile("" : "+v"(p0), "+v"(p1));
;         }
; #pragma unroll
;         for (int r = 0; r < 16; ++r) { p0[r] = __builtin_amdgcn_exp2f(p0[r]); p1[r] = __builtin_amdgcn_exp2f(p1[r]); }
; #pragma unroll
;         for (int r = 0; r < 16; r += 2) { ls2 += (f32x2){p0[r], p0[r + 1]}; ls2 += (f32x2){p1[r], p1[r + 1]}; }
;         bf16x8 pa[4]; pa[0] = pack8(p0, 0); pa[1] = pack8(p0, 8); pa[2] = pack8(p1, 0); pa[3] = pack8(p1, 8);
;         LGKM0(); VREADS1(vb, 1); PV1(va, 0); LGKM0(); VREADS1(va, 2); PV1(vb, 1); LGKM0(); VREADS1(vb, 3); PV1(va, 2); LGKM0(); PV1(vb, 3);
.LatA_rare_e:
	v_mov_b32_e32 v252, v251
	s_nop 1
	v_permlane32_swap_b32_e32 v251, v252
	v_max_f32_e32 v251, v251, v252
	v_max_f32_e32 v253, 0, v251
	v_exp_f32_e64 v254, -v253
	v_add_f32_e32 v186, v186, v253
	s_nop 0
	v_mul_f32_e32 v150, v150, v254
	v_mul_f32_e32 v151, v151, v254
	ds_write_b32 v184, v254
	s_waitcnt lgkmcnt(0)
	v_mfma_f32_32x32x16_bf16 v[20:35], v[188:191], v[132:135], v[20:35]
	v_mfma_f32_32x32x16_bf16 v[36:51], v[188:191], v[136:139], v[36:51]
	v_mfma_f32_32x32x16_bf16 v[52:67], v[188:191], v[140:143], v[52:67]
	v_mfma_f32_32x32x16_bf16 v[68:83], v[188:191], v[144:147], v[68:83]
	v_mfma_f32_32x32x16_bf16 v[20:35], v[192:195], v[220:223], v[20:35]
	v_mfma_f32_32x32x16_bf16 v[36:51], v[192:195], v[224:227], v[36:51]
	ds_read_b64_tr_b16 v[132:133], v238 offset:4096
	ds_read_b64_tr_b16 v[134:135], v238 offset:6144
	ds_read_b64_tr_b16 v[136:137], v239 offset:4096
	ds_read_b64_tr_b16 v[138:139], v239 offset:6144
	ds_read_b64_tr_b16 v[140:141], v236 offset:8192
	ds_read_b64_tr_b16 v[142:143], v236 offset:10240
	ds_read_b64_tr_b16 v[144:145], v237 offset:8192
	ds_read_b64_tr_b16 v[146:147], v237 offset:10240
	ds_read_b64_tr_b16 v[220:221], v238 offset:8192
	ds_read_b64_tr_b16 v[222:223], v238 offset:10240
	ds_read_b64_tr_b16 v[224:225], v239 offset:8192
	ds_read_b64_tr_b16 v[226:227], v239 offset:10240
	s_waitcnt lgkmcnt(0)
	v_mfma_f32_32x32x16_bf16 v[52:67], v[192:195], v[132:135], v[52:67]
	v_mfma_f32_32x32x16_bf16 v[68:83], v[192:195], v[136:139], v[68:83]
	v_mfma_f32_32x32x16_bf16 v[20:35], v[204:207], v[140:143], v[20:35]
	v_mfma_f32_32x32x16_bf16 v[36:51], v[204:207], v[144:147], v[36:51]
	v_mfma_f32_32x32x16_bf16 v[52:67], v[204:207], v[220:223], v[52:67]
	v_mfma_f32_32x32x16_bf16 v[68:83], v[204:207], v[224:227], v[68:83]
	ds_read_b64_tr_b16 v[132:133], v236 offset:12288
	ds_read_b64_tr_b16 v[134:135], v236 offset:14336
	ds_read_b64_tr_b16 v[136:137], v237 offset:12288
	ds_read_b64_tr_b16 v[138:139], v237 offset:14336
	ds_read_b64_tr_b16 v[140:141], v238 offset:12288
	ds_read_b64_tr_b16 v[142:143], v238 offset:14336
	ds_read_b64_tr_b16 v[144:145], v239 offset:12288
	ds_read_b64_tr_b16 v[146:147], v239 offset:14336
	s_waitcnt lgkmcnt(0)
	v_mfma_f32_32x32x16_bf16 v[20:35], v[208:211], v[132:135], v[20:35]
	v_mfma_f32_32x32x16_bf16 v[36:51], v[208:211], v[136:139], v[36:51]
	v_mfma_f32_32x32x16_bf16 v[52:67], v[208:211], v[140:143], v[52:67]
	v_mfma_f32_32x32x16_bf16 v[68:83], v[208:211], v[144:147], v[68:83]
	ds_read_b128 v[196:199], v185
	ds_read_b128 v[200:203], v185 offset:32
	ds_read_b128 v[212:215], v185 offset:64
	ds_read_b128 v[216:219], v185 offset:96
	s_waitcnt lgkmcnt(0)
	s_nop 15
	s_nop 15
	v_mul_f32_e32 v20, v20, v196
	v_mul_f32_e32 v21, v21, v197
	v_mul_f32_e32 v22, v22, v198
	v_mul_f32_e32 v23, v23, v199
	v_mul_f32_e32 v24, v24, v200
	v_mul_f32_e32 v25, v25, v201
	v_mul_f32_e32 v26, v26, v202
	v_mul_f32_e32 v27, v27, v203
	v_mul_f32_e32 v28, v28, v212
	v_mul_f32_e32 v29, v29, v213
	v_mul_f32_e32 v30, v30, v214
	v_mul_f32_e32 v31, v31, v215
	v_mul_f32_e32 v32, v32, v216
	v_mul_f32_e32 v33, v33, v217
	v_mul_f32_e32 v34, v34, v218
	v_mul_f32_e32 v35, v35, v219
	v_mul_f32_e32 v36, v36, v196
	v_mul_f32_e32 v37, v37, v197
	v_mul_f32_e32 v38, v38, v198
	v_mul_f32_e32 v39, v39, v199
	v_mul_f32_e32 v40, v40, v200
	v_mul_f32_e32 v41, v41, v201
	v_mul_f32_e32 v42, v42, v202
	v_mul_f32_e32 v43, v43, v203
	v_mul_f32_e32 v44, v44, v212
	v_mul_f32_e32 v45, v45, v213
	v_mul_f32_e32 v46, v46, v214
	v_mul_f32_e32 v47, v47, v215
	v_mul_f32_e32 v48, v48, v216
	v_mul_f32_e32 v49, v49, v217
	v_mul_f32_e32 v50, v50, v218
	v_mul_f32_e32 v51, v51, v219
	v_mul_f32_e32 v52, v52, v196
	v_mul_f32_e32 v53, v53, v197
	v_mul_f32_e32 v54, v54, v198
	v_mul_f32_e32 v55, v55, v199
	v_mul_f32_e32 v56, v56, v200
	v_mul_f32_e32 v57, v57, v201
	v_mul_f32_e32 v58, v58, v202
	v_mul_f32_e32 v59, v59, v203
	v_mul_f32_e32 v60, v60, v212
	v_mul_f32_e32 v61, v61, v213
	v_mul_f32_e32 v62, v62, v214
	v_mul_f32_e32 v63, v63, v215
	v_mul_f32_e32 v64, v64, v216
	v_mul_f32_e32 v65, v65, v217
	v_mul_f32_e32 v66, v66, v218
	v_mul_f32_e32 v67, v67, v219
	v_mul_f32_e32 v68, v68, v196
	v_mul_f32_e32 v69, v69, v197
	v_mul_f32_e32 v70, v70, v198
	v_mul_f32_e32 v71, v71, v199
	v_mul_f32_e32 v72, v72, v200
	v_mul_f32_e32 v73, v73, v201
	v_mul_f32_e32 v74, v74, v202
	v_mul_f32_e32 v75, v75, v203
	v_mul_f32_e32 v76, v76, v212
	v_mul_f32_e32 v77, v77, v213
	v_mul_f32_e32 v78, v78, v214
	v_mul_f32_e32 v79, v79, v215
	v_mul_f32_e32 v80, v80, v216
	v_mul_f32_e32 v81, v81, v217
	v_mul_f32_e32 v82, v82, v218
	v_mul_f32_e32 v83, v83, v219
	v_sub_f32_e32 v84, v84, v253
	v_sub_f32_e32 v85, v85, v253
	v_sub_f32_e32 v86, v86, v253
	v_sub_f32_e32 v87, v87, v253
	v_sub_f32_e32 v88, v88, v253
	v_sub_f32_e32 v89, v89, v253
	v_sub_f32_e32 v90, v90, v253
	v_sub_f32_e32 v91, v91, v253
	v_sub_f32_e32 v92, v92, v253
	v_sub_f32_e32 v93, v93, v253
	v_sub_f32_e32 v94, v94, v253
	v_sub_f32_e32 v95, v95, v253
	v_sub_f32_e32 v96, v96, v253
	v_sub_f32_e32 v97, v97, v253
	v_sub_f32_e32 v98, v98, v253
	v_sub_f32_e32 v99, v99, v253
	v_sub_f32_e32 v100, v100, v253
	v_sub_f32_e32 v101, v101, v253
	v_sub_f32_e32 v102, v102, v253
	v_sub_f32_e32 v103, v103, v253
	v_sub_f32_e32 v104, v104, v253
	v_sub_f32_e32 v105, v105, v253
	v_sub_f32_e32 v106, v106, v253
	v_sub_f32_e32 v107, v107, v253
	v_sub_f32_e32 v108, v108, v253
	v_sub_f32_e32 v109, v109, v253
	v_sub_f32_e32 v110, v110, v253
	v_sub_f32_e32 v111, v111, v253
	v_sub_f32_e32 v112, v112, v253
	v_sub_f32_e32 v113, v113, v253
	v_sub_f32_e32 v114, v114, v253
	v_sub_f32_e32 v115, v115, v253
	v_mov_b32_e32 v188, 0
	v_mov_b32_e32 v189, 0
	v_mov_b32_e32 v190, 0
	v_mov_b32_e32 v191, 0
	v_mov_b32_e32 v192, 0
	v_mov_b32_e32 v193, 0
	v_mov_b32_e32 v194, 0
	v_mov_b32_e32 v195, 0
	v_mov_b32_e32 v204, 0
	v_mov_b32_e32 v205, 0
	v_mov_b32_e32 v206, 0
	v_mov_b32_e32 v207, 0
	v_mov_b32_e32 v208, 0
	v_mov_b32_e32 v209, 0
	v_mov_b32_e32 v210, 0
	v_mov_b32_e32 v211, 0
	s_mov_b32 s36, -1
	s_branch .LatA_rareret_e

; #define VREADS1(arr, d_) do { const unsigned ad_ = vbase ^ (unsigned)((d_) << 6); __builtin_amdgcn_sched_barrier(0); \
;         _Pragma("unroll") for (int ks_ = 0; ks_ < 4; ++ks_) { VTR(arr[ks_ * 2], ad_, ks_ * 4096); VTR(arr[ks_ * 2 + 1], ad_, ks_ * 4096 + 2048); } __builtin_amdgcn_sched_barrier(0); } while (0)
; #define PV1(arr, d_) do { _Pragma("unroll") for (int ks_ = 0; ks_ < 4; ++ks_) { const s16x4 lo_ = arr[ks_ * 2], hh_ = arr[ks_ * 2 + 1]; \
;         const bf16x8 bv_ = (bf16x8){lo_[0], lo_[1], lo_[2], lo_[3], hh_[0], hh_[1], hh_[2], hh_[3]}; \
;         O[d_] = __builtin_amdgcn_mfma_f32_32x32x16_bf16(pa[ks_], bv_, O[d_], 0, 0, 0); } __builtin_amdgcn_sched_barrier(0); } while (0)
; #define LGKM0() do { __builtin_amdgcn_sched_barrier(0); asm volatile("s_waitcnt lgkmcnt(0)" ::: "memory"); __builtin_amdgcn_sched_barrier(0); } while (0)
; __device__ __forceinline__ void attn_unit(LAS unsigned char* lds, const bf16_t* Z, bf16_t* A2, const float* tabg, int seq_base, int S, int h, int qb, float lam) {
;     ...
;         for (int r = 0; r < 16; ++r) { p0[r] = __builtin_amdgcn_exp2f(p0[r]); p1[r] = __builtin_amdgcn_exp2f(p1[r]); }
; #pragma unroll
;         for (int r = 0; r < 16; r += 2) { ls2 += (f32x2){p0[r], p0[r + 1]}; ls2 += (f32x2){p1[r], p1[r + 1]}; }
;         bf16x8 pa[4]; pa[0] = pack8(p0, 0); pa[1] = pack8(p0, 8); pa[2] = pack8(p1, 0); pa[3] = pack8(p1, 8);
;         LGKM0(); VREADS1(vb, 1); PV1(va, 0); LGKM0(); VREADS1(va, 2); PV1(vb, 1); LGKM0(); VREADS1(vb, 3); PV1(va, 2); LGKM0(); PV1(vb, 3);
;     ...
;         if (t + 2 < NT) asm volatile("s_waitcnt vmcnt(4) lgkmcnt(0)" ::: "memory"); else asm volatile("s_waitcnt vmcnt(0) lgkmcnt(0)" ::: "memory");
;         __builtin_amdgcn_s_barrier(); asm volatile("" ::: "memory");
;         bc = (bc == NST - 1) ? 0 : bc + 1; bn = (bn == NST - 1) ? 0 : bn + 1;
;     }
;     const float ls = ls2[0] + ls2[1];
.LatA_done:


; __device__ __forceinline__ void attn_unit(LAS unsigned char* lds, const bf16_t* Z, bf16_t* A2, const float* tabg, int seq_base, int S, int h, int qb, float lam) {
;     ...
;     const int qlo = qb * 128 + rg * 32;
;     bf16x8 qf[4];
;     { const bf16_t* qrow = Z + (size_t)(seq_base + qlo + r32) * NZ + h * 128 + m * 64 + 8 * hi;
; #pragma unroll
;       for (int ds = 0; ds < 4; ++ds) qf[ds] = *(const bf16x8*)(qrow + 16 * ds); }
;     const char* kvbase = (const char*)(Z + (size_t)seq_base * NZ + h * 128);
;     unsigned koff[2], voff[2];
; #pragma unroll
;     for (int i = 0; i < 2; ++i) { const int row = (i * 8 + w) * 4 + (lane >> 4), cp = lane & 15;
;         koff[i] = (unsigned)(row * NZ + 512 + ((cp ^ (row & 15)) << 3)) * 2u; voff[i] = (unsigned)(row * NZ + 1024 + ((cp ^ (4 * (row & 3))) << 3)) * 2u; }
;     const unsigned kb_u = (unsigned)(size_t)Kb + (unsigned)w * 1024u, vb_u = (unsigned)(size_t)Vb + (unsigned)w * 1024u;
;     ...
;     ATT_STAGE(0, 0); ATT_STAGE(1, 1);
;     asm volatile("s_waitcnt vmcnt(4) lgkmcnt(0)" ::: "memory"); __builtin_amdgcn_s_barrier(); asm volatile("" ::: "memory");
; #pragma unroll
;     for (int ds = 0; ds < 4; ++ds) asm volatile("" : "+v"(qf[ds]));
;     const float tabL = tab[0], tabR = tab[448];
;     f32x16 O[4];
; #pragma unroll
;     for (int d = 0; d < 4; ++d)
; #pragma unroll
;         for (int r = 0; r < 16; ++r) O[d][r] = 0.f;
;     float mu = 0.f; f32x2 ls2 = {0.f, 0.f};
;     f32x16 cblk; float coff_cur = __builtin_nanf("");
; #pragma unroll
;     for (int r = 0; r < 16; ++r) cblk[r] = 0.f;
;     const int NT = S >> 6;
;     const unsigned kfo = r32 * 256 + ((unsigned)((m * 8 + hi) ^ (r32 & 15)) << 4);
;     const unsigned vj = (i16 >> 2) & 3;
;     const unsigned vfo = (4 * hi + (i16 >> 2)) * 256 + (vj << 6) + 32 * (g4 & 1) + 8 * (i16 & 3);
;     int bc = 0, bn = 2;
.LBB0_325:
	s_or_b64 exec, exec, s[8:9]
	s_lshl_b32 s9, s21, 6
	s_and_b32 s8, s25, 32
	s_and_b32 s9, s9, 64
	s_or_b32 s8, s9, s8
	s_ashr_i32 s15, s26, 6
	s_or_b32 s8, s8, s23
	s_and_b32 s17, s15, 3
	s_lshl_b32 s8, s8, 7
	s_waitcnt lgkmcnt(0)
	s_lshl_b32 s10, s17, 5
	s_or_b32 s11, s10, s8
	v_and_b32_e32 v148, 31, v68
	s_or_b32 s14, s11, 0x4000
	v_or_b32_e32 v2, s14, v148
	s_ashr_i32 s16, s26, 8
	v_lshlrev_b32_e32 v162, 12, v2
	v_lshl_add_u64 v[2:3], s[4:5], 0, v[162:163]
	s_lshl_b32 s48, s28, 8
	s_lshl_b32 s8, s16, 6
	v_bfe_u32 v159, v68, 5, 1
	v_lshl_add_u64 v[2:3], v[2:3], 0, s[48:49]
	s_ashr_i32 s9, s8, 31
	v_lshl_add_u64 v[2:3], s[8:9], 1, v[2:3]
	v_lshlrev_b32_e32 v162, 4, v159
	v_lshl_add_u64 v[2:3], v[2:3], 0, v[162:163]
	s_mov_b64 s[8:9], 0x7800000
	v_lshl_add_u64 v[4:5], v[2:3], 0, s[8:9]
	s_mov_b32 s8, 0x7800000
	v_add_co_u32_e32 v2, vcc, s8, v2
	v_readlane_b32 s8, v255, 29
	s_nop 0
	v_addc_co_u32_e32 v3, vcc, 0, v3, vcc
	global_load_dwordx4 v[116:119], v[2:3], off
	global_load_dwordx4 v[120:123], v[4:5], off offset:32
	global_load_dwordx4 v[124:127], v[4:5], off offset:64
	global_load_dwordx4 v[128:131], v[4:5], off offset:96
	v_mov_b32_e32 v3, s8
	v_readlane_b32 s8, v255, 30
	v_bfe_u32 v2, v68, 4, 2
	v_lshlrev_b32_e32 v35, 5, v2
	v_mov_b32_e32 v4, s8
	s_lshl_b32 s8, s15, 2
	v_or_b32_e32 v6, s8, v2
	v_bitop3_b32 v2, s8, v68, v2 bitop3:0x36
	s_add_u32 s29, s4, s48
	v_and_b32_e32 v34, 15, v68
	v_lshlrev_b32_e32 v6, 11, v6
	v_lshlrev_b32_e32 v2, 3, v2
	s_addc_u32 s30, s5, 0
	v_lshlrev_b32_e32 v5, 3, v34
	v_and_b32_e32 v2, 0x78, v2
	v_add_u32_e32 v8, 0x10000, v6
	s_add_u32 s8, s29, 0xb800000
	v_bitop3_b32 v7, v6, v35, v5 bitop3:0xf6
	v_or_b32_e32 v6, v2, v6
	v_or_b32_e32 v2, v2, v8
	v_bitop3_b32 v5, v8, v35, v5 bitop3:0xf6
	s_addc_u32 s9, s30, 0
	s_lshl_b32 s27, s15, 10
	s_add_i32 s15, 0, 0xc000
	v_lshl_or_b32 v149, v7, 1, v250
	v_lshl_or_b32 v160, v6, 1, v249
	v_lshl_or_b32 v161, v2, 1, v249
	v_lshl_or_b32 v176, v5, 1, v250
	s_add_i32 s25, s27, 0
	s_add_i32 s27, s27, s15
	s_mov_b32 s31, m0
	s_mov_b32 m0, s25
	s_nop 0
	global_load_lds_dwordx4 v160, s[8:9]
	s_mov_b32 m0, s27
	s_nop 0
	global_load_lds_dwordx4 v149, s[8:9]
	s_add_u32 m0, s25, 0x2000
	s_nop 0
	global_load_lds_dwordx4 v161, s[8:9]
	s_add_u32 m0, s27, 0x2000
	s_nop 0
	global_load_lds_dwordx4 v176, s[8:9]
	s_mov_b32 m0, s31
	s_add_u32 s8, s29, 0xb840000
	s_addc_u32 s9, s30, 0
	s_add_i32 s31, s25, 0x4000
	s_add_i32 s33, s27, 0x4000
	s_mov_b32 s34, m0
	s_mov_b32 m0, s31
	s_nop 0
	global_load_lds_dwordx4 v160, s[8:9]
	s_mov_b32 m0, s33
	s_nop 0
	global_load_lds_dwordx4 v149, s[8:9]
	s_add_u32 m0, s31, 0x2000
	s_nop 0
	global_load_lds_dwordx4 v161, s[8:9]
	s_add_u32 m0, s33, 0x2000
	s_nop 0
	global_load_lds_dwordx4 v176, s[8:9]
	s_mov_b32 m0, s34
	s_mov_b32 s32, m0
	s_add_u32 s8, s29, 0xb840000
	s_addc_u32 s9, s30, 0
	s_add_u32 s4, s8, 0x40000
	s_addc_u32 s5, s9, 0
	s_lshl_b32 s15, s28, 7
	s_and_b32 s30, s26, 0x3fffffc0
	s_lshl_b32 s30, s30, 2
	s_add_i32 s28, s30, 0x18000
	v_and_b32_e32 v183, 63, v68
	v_lshl_add_u32 v185, v159, 4, s28
	v_lshl_add_u32 v184, v148, 2, s28
	s_add_i32 s33, s11, 0x9f
	v_add_lshl_u32 v251, s11, v148, 2
	v_lshlrev_b32_e32 v252, 4, v159
	v_sub_u32_e32 v162, v252, v251
	s_add_i32 s34, s11, 0xffffff41
	s_lshl_b32 s30, s16, 3
	v_lshlrev_b32_e32 v19, 8, v148
	v_bitop3_b32 v251, s30, v34, v159 bitop3:0x36
	v_lshlrev_b32_e32 v252, 2, v159
	v_lshrrev_b32_e32 v253, 2, v34
	v_lshlrev_b32_e32 v254, 3, v68
	v_lshl_add_u32 v19, v251, 4, v19
	v_or_b32_e32 v252, v252, v253
	v_and_b32_e32 v254, 24, v254
	v_and_b32_e32 v251, 32, v35
	v_lshlrev_b32_e32 v252, 8, v252
	v_lshl_or_b32 v253, v253, 6, v254
	v_xor_b32_e32 v180, 32, v19
	v_or3_b32 v179, v252, v251, v253
	v_xor_b32_e32 v181, 64, v19
	v_xor_b32_e32 v182, 0x60, v19
	v_add_u32_e32 v228, 0xc000, v179
	v_xor_b32_e32 v229, 0x40, v179
	v_add_u32_e32 v229, 0xc000, v229
	v_xor_b32_e32 v230, 0x80, v179
	v_add_u32_e32 v230, 0xc000, v230
	v_xor_b32_e32 v231, 0xc0, v179
	v_add_u32_e32 v231, 0xc000, v231
	s_add_u32 m0, s25, 0x8000
	s_nop 0
	global_load_lds_dwordx4 v160, s[4:5]
	s_add_u32 m0, s25, 0xa000
	s_nop 0
	global_load_lds_dwordx4 v161, s[4:5]
	s_mov_b32 s10, 0
	s_movk_i32 s35, 0x4000
	s_mov_b32 s31, 0x8000
	s_mov_b32 s36, 0
	v_mov_b64_e32 v[20:21], 0
	v_mov_b64_e32 v[22:23], 0
	v_mov_b64_e32 v[24:25], 0
	v_mov_b64_e32 v[26:27], 0
	v_mov_b64_e32 v[28:29], 0
	v_mov_b64_e32 v[30:31], 0
	v_mov_b64_e32 v[32:33], 0
	v_mov_b64_e32 v[34:35], 0
	v_mov_b64_e32 v[36:37], 0
	v_mov_b64_e32 v[38:39], 0
	v_mov_b64_e32 v[40:41], 0
	v_mov_b64_e32 v[42:43], 0
	v_mov_b64_e32 v[44:45], 0
	v_mov_b64_e32 v[46:47], 0
	v_mov_b64_e32 v[48:49], 0
	v_mov_b64_e32 v[50:51], 0
	v_mov_b64_e32 v[52:53], 0
	v_mov_b64_e32 v[54:55], 0
	v_mov_b64_e32 v[56:57], 0
	v_mov_b64_e32 v[58:59], 0
	v_mov_b64_e32 v[60:61], 0
	v_mov_b64_e32 v[62:63], 0
	v_mov_b64_e32 v[64:65], 0
	v_mov_b64_e32 v[66:67], 0
	v_mov_b64_e32 v[68:69], 0
	v_mov_b64_e32 v[70:71], 0
	v_mov_b64_e32 v[72:73], 0
	v_mov_b64_e32 v[74:75], 0
	v_mov_b64_e32 v[76:77], 0
	v_mov_b64_e32 v[78:79], 0
	v_mov_b64_e32 v[80:81], 0
	v_mov_b64_e32 v[82:83], 0
	v_mov_b64_e32 v[150:151], 0
	v_mov_b32_e32 v186, 0
	s_cmp_lt_u32 s36, s33
	s_cselect_b32 s11, 0, 2
	s_cmp_gt_i32 s36, s34
	s_cselect_b32 s30, 0, 1
	s_or_b32 s29, s30, s11
	s_mov_b32 s24, s29
	s_waitcnt vmcnt(6) lgkmcnt(0)
	s_barrier
	v_mov_b32_e32 v187, 0x18800
	ds_read_b32 v177, v187
	ds_read_b32 v178, v187 offset:1792
	ds_read_b128 v[132:135], v19
	ds_read_b128 v[136:139], v19 offset:8192
	ds_read_b128 v[140:143], v180
	ds_read_b128 v[144:147], v180 offset:8192
	ds_read_b128 v[220:223], v181
	ds_read_b128 v[224:227], v181 offset:8192
	ds_read_b128 v[232:235], v182
	ds_read_b128 v[236:239], v182 offset:8192
	s_waitcnt lgkmcnt(8)
	s_branch .LatB_rebuild_p0
; #define LAS __attribute__((address_space(3)))
; __device__ __forceinline__ void attn_unit(LAS unsigned char* lds, const bf16_t* Z, bf16_t* A2, const float* tabg, int seq_base, int S, int h, int qb, float lam) {
;     ...
;             for (int ds = 0; ds < 4; ++ds) { kf[2 * ds] = *(const LAS bf16x8*)(Kt + (kfo ^ (unsigned)(ds << 5))); kf[2 * ds + 1] = *(const LAS bf16x8*)(Kt + 32 * 256 + (kfo ^ (unsigned)(ds << 5))); }
;             __builtin_amdgcn_sched_barrier(0);
;             p0 = __builtin_amdgcn_mfma_f32_32x32x16_bf16(kf[0], qf[0], cblk, 0, 0, 0);
;             p1 = __builtin_amdgcn_mfma_f32_32x32x16_bf16(kf[1], qf[0], cblk, 0, 0, 0);
; #pragma unroll
;             for (int ds = 1; ds < 4; ++ds) {
;                 p0 = __builtin_amdgcn_mfma_f32_32x32x16_bf16(kf[2 * ds], qf[ds], p0, 0, 0, 0);
;                 p1 = __builtin_amdgcn_mfma_f32_32x32x16_bf16(kf[2 * ds + 1], qf[ds], p1, 0, 0, 0);
;             }
;         }
;     ...
;         const unsigned vbase = (unsigned)(size_t)Vt + vfo;
;         s16x4 va[8], vb[8];
;         VREADS1(va, 0);
;         if (near) {
;             const LAS float* tp = tab + (kv0 + 4 * hi - (qlo + r32) + 224);
; #pragma unroll
;             for (int r = 0; r < 16; ++r) { p0[r] += tp[(r & 3) + 8 * (r >> 2)]; p1[r] += tp[32 + (r & 3) + 8 * (r >> 2)]; }
;         }
;         float mx = max2f(max16f(p0), max16f(p1));
;         const bool first = (t == 0);
;         if (first || __any(mx > THR)) {
;             { auto rr = __builtin_amdgcn_permlane32_swap(__float_as_uint(mx), __float_as_uint(mx), false, false); mx = max2f(__uint_as_float(rr[0]), __uint_as_float(rr[1])); }
;             const float delta = first ? mx : fmaxf(mx, 0.f);
;             const float alpha = first ? 1.0f : __builtin_amdgcn_exp2f(-delta);
;             mu += delta; ls2 *= alpha;
;             if (!first) {
;                 asm volatile("" ::: "memory");
;                 scr[r32] = alpha;
;                 asm volatile("s_waitcnt lgkmcnt(0)" ::: "memory");
; #pragma unroll
;                 for (int g = 0; g < 4; ++g) { const f32x4 a4 = *(const LAS f32x4*)(scr + 8 * g + 4 * hi);
; #pragma unroll
;                     for (int d = 0; d < 4; ++d) { O[d][4 * g + 0] *= a4[0]; O[d][4 * g + 1] *= a4[1]; O[d][4 * g + 2] *= a4[2]; O[d][4 * g + 3] *= a4[3]; } }
;                 asm volatile("s_waitcnt lgkmcnt(0)" ::: "memory");
;             }
; #pragma unroll
.LatB_rebuildret_p0:
	s_waitcnt lgkmcnt(7)
	v_mfma_f32_32x32x16_bf16 v[84:99], v[132:135], v[116:119], v[2:17]
	s_waitcnt lgkmcnt(6)
	v_mfma_f32_32x32x16_bf16 v[100:115], v[136:139], v[116:119], v[2:17]
	s_waitcnt lgkmcnt(5)
	v_mfma_f32_32x32x16_bf16 v[84:99], v[140:143], v[120:123], v[84:99]
	s_waitcnt lgkmcnt(4)
	v_mfma_f32_32x32x16_bf16 v[100:115], v[144:147], v[120:123], v[100:115]
	s_waitcnt lgkmcnt(3)
	v_mfma_f32_32x32x16_bf16 v[84:99], v[220:223], v[124:127], v[84:99]
	s_waitcnt lgkmcnt(2)
	v_mfma_f32_32x32x16_bf16 v[100:115], v[224:227], v[124:127], v[100:115]
	s_waitcnt lgkmcnt(1)
	v_mfma_f32_32x32x16_bf16 v[84:99], v[232:235], v[128:131], v[84:99]
	s_waitcnt lgkmcnt(0)
	v_mfma_f32_32x32x16_bf16 v[100:115], v[236:239], v[128:131], v[100:115]
	s_nop 15
	s_nop 15
	s_cmp_eq_u32 s24, 0
	s_cbranch_scc1 .LatB_near_p0
.LatB_nearret_p0:
	v_max3_f32 v251, v84, v85, v86
	v_max3_f32 v252, v87, v88, v89
	v_max3_f32 v251, v251, v90, v91
	v_max3_f32 v252, v252, v92, v93
	v_max3_f32 v251, v251, v94, v95
	v_max3_f32 v252, v252, v96, v97
	v_max3_f32 v251, v251, v98, v99
	v_max3_f32 v252, v252, v100, v101
	v_max3_f32 v251, v251, v102, v103
	v_max3_f32 v252, v252, v104, v105
	v_max3_f32 v251, v251, v106, v107
	v_max3_f32 v252, v252, v108, v109
	v_max3_f32 v251, v251, v110, v111
	v_max3_f32 v252, v252, v112, v113
	v_max3_f32 v251, v251, v114, v115
	v_max_f32_e32 v251, v251, v252
	v_mov_b32_e32 v252, v251
	s_nop 1
	v_permlane32_swap_b32_e32 v251, v252
	v_max_f32_e32 v186, v251, v252
	v_sub_f32_e32 v84, v84, v186
	v_sub_f32_e32 v85, v85, v186
	v_sub_f32_e32 v86, v86, v186
	v_sub_f32_e32 v87, v87, v186
	v_sub_f32_e32 v88, v88, v186
	v_sub_f32_e32 v89, v89, v186
	v_sub_f32_e32 v90, v90, v186
	v_sub_f32_e32 v91, v91, v186
	v_sub_f32_e32 v92, v92, v186
	v_sub_f32_e32 v93, v93, v186
	v_sub_f32_e32 v94, v94, v186
	v_sub_f32_e32 v95, v95, v186
	v_sub_f32_e32 v96, v96, v186
	v_sub_f32_e32 v97, v97, v186
	v_sub_f32_e32 v98, v98, v186
	v_sub_f32_e32 v99, v99, v186
	v_sub_f32_e32 v100, v100, v186
	v_sub_f32_e32 v101, v101, v186
	v_sub_f32_e32 v102, v102, v186
	v_sub_f32_e32 v103, v103, v186
	v_sub_f32_e32 v104, v104, v186
	v_sub_f32_e32 v105, v105, v186
	v_sub_f32_e32 v106, v106, v186
	v_sub_f32_e32 v107, v107, v186
	v_sub_f32_e32 v108, v108, v186
	v_sub_f32_e32 v109, v109, v186
	v_sub_f32_e32 v110, v110, v186
	v_sub_f32_e32 v111, v111, v186
	v_sub_f32_e32 v112, v112, v186
	v_sub_f32_e32 v113, v113, v186
	v_sub_f32_e32 v114, v114, v186
	v_sub_f32_e32 v115, v115, v186
	s_mov_b32 s22, -1
	s_waitcnt vmcnt(0)
	s_barrier
	v_add_u32_e32 v232, s35, v19
	v_add_u32_e32 v233, s35, v180
	v_add_u32_e32 v234, s35, v181
	v_add_u32_e32 v235, s35, v182
	s_add_u32 s4, s8, 0x80000
	s_addc_u32 s5, s9, 0
	ds_read_b128 v[220:223], v232
	ds_read_b128 v[224:227], v232 offset:8192
	ds_read_b128 v[132:135], v233
	ds_read_b128 v[136:139], v233 offset:8192
	ds_read_b128 v[140:143], v234
	ds_read_b128 v[144:147], v234 offset:8192
	v_max3_f32 v251, v84, v85, v86
	v_max3_f32 v252, v87, v88, v89
	v_max3_f32 v251, v251, v90, v91
	v_max3_f32 v252, v252, v92, v93
	v_max3_f32 v251, v251, v94, v95
	v_max3_f32 v252, v252, v96, v97
	v_max3_f32 v251, v251, v98, v99
	v_max3_f32 v252, v252, v100, v101
	v_max3_f32 v251, v251, v102, v103
	v_max3_f32 v252, v252, v104, v105
	v_max3_f32 v251, v251, v106, v107
	v_max3_f32 v252, v252, v108, v109
	v_max3_f32 v251, v251, v110, v111
	v_max3_f32 v252, v252, v112, v113
	v_max3_f32 v251, v251, v114, v115
	v_max_f32_e32 v251, v251, v252
	s_nop 0
	v_cmp_lt_f32_e32 vcc, 0x41000000, v251
	s_cbranch_vccnz .LatB_rare_t0
.LatB_rareret_t0:
	s_add_i32 s30, s36, 64
	s_cmp_lt_u32 s30, s33
	s_cselect_b32 s11, 0, 2
	s_cmp_gt_i32 s30, s34
	s_cselect_b32 s30, 0, 1
	s_or_b32 s29, s30, s11
	s_cmp_lg_u32 s29, s22
	s_cbranch_scc1 .LatB_rebuild_t0
; __device__ __forceinline__ void attn_unit(LAS unsigned char* lds, const bf16_t* Z, bf16_t* A2, const float* tabg, int seq_base, int S, int h, int qb, float lam) {
;     ...
;             p0 = __builtin_amdgcn_mfma_f32_32x32x16_bf16(kf[0], qf[0], cblk, 0, 0, 0);
;             p1 = __builtin_amdgcn_mfma_f32_32x32x16_bf16(kf[1], qf[0], cblk, 0, 0, 0);
; #pragma unroll
;             for (int ds = 1; ds < 4; ++ds) {
;                 p0 = __builtin_amdgcn_mfma_f32_32x32x16_bf16(kf[2 * ds], qf[ds], p0, 0, 0, 0);
;                 p1 = __builtin_amdgcn_mfma_f32_32x32x16_bf16(kf[2 * ds + 1], qf[ds], p1, 0, 0, 0);
;             }
;         }
;     ...
;         const unsigned vbase = (unsigned)(size_t)Vt + vfo;
;         s16x4 va[8], vb[8];
;         VREADS1(va, 0);
;         if (near) {
;             const LAS float* tp = tab + (kv0 + 4 * hi - (qlo + r32) + 224);
; #pragma unroll
;             for (int r = 0; r < 16; ++r) { p0[r] += tp[(r & 3) + 8 * (r >> 2)]; p1[r] += tp[32 + (r & 3) + 8 * (r >> 2)]; }
;         }
;         float mx = max2f(max16f(p0), max16f(p1));
;         const bool first = (t == 0);
;         if (first || __any(mx > THR)) {
;             { auto rr = __builtin_amdgcn_permlane32_swap(__float_as_uint(mx), __float_as_uint(mx), false, false); mx = max2f(__uint_as_float(rr[0]), __uint_as_float(rr[1])); }
;             const float delta = first ? mx : fmaxf(mx, 0.f);
;             const float alpha = first ? 1.0f : __builtin_amdgcn_exp2f(-delta);
;             mu += delta; ls2 *= alpha;
;             if (!first) {
;                 asm volatile("" ::: "memory");
;                 scr[r32] = alpha;
;                 asm volatile("s_waitcnt lgkmcnt(0)" ::: "memory");
; #pragma unroll
;                 for (int g = 0; g < 4; ++g) { const f32x4 a4 = *(const LAS f32x4*)(scr + 8 * g + 4 * hi);
; #pragma unroll
;                     for (int d = 0; d < 4; ++d) { O[d][4 * g + 0] *= a4[0]; O[d][4 * g + 1] *= a4[1]; O[d][4 * g + 2] *= a4[2]; O[d][4 * g + 3] *= a4[3]; } }
;                 asm volatile("s_waitcnt lgkmcnt(0)" ::: "memory");
;             }
; #pragma unroll
;             for (int r = 0; r < 16; ++r) { p0[r] -= delta; p1[r] -= delta; }
;             asm volatile("" : "+v"(p0), "+v"(p1));
;         }
; #pragma unroll
;         for (int r = 0; r < 16; ++r) { p0[r] = __builtin_amdgcn_exp2f(p0[r]); p1[r] = __builtin_amdgcn_exp2f(p1[r]); }
; #pragma unroll
.LatB_rebuildret_t0:
	s_waitcnt lgkmcnt(5)
	v_mfma_f32_32x32x16_bf16 v[188:203], v[220:223], v[116:119], v[2:17]
	ds_read_b128 v[220:223], v235
	v_exp_f32_e32 v84, v84
	v_exp_f32_e32 v85, v85
	v_exp_f32_e32 v86, v86
	v_exp_f32_e32 v87, v87
	v_pk_add_f32 v[150:151], v[150:151], v[84:85]
	v_pk_add_f32 v[150:151], v[150:151], v[86:87]
	v_exp_f32_e32 v88, v88
	s_waitcnt lgkmcnt(5)
	v_mfma_f32_32x32x16_bf16 v[204:219], v[224:227], v[116:119], v[2:17]
	ds_read_b128 v[224:227], v235 offset:8192
	s_add_u32 m0, s25, s10
	s_nop 0
	global_load_lds_dwordx4 v160, s[4:5]
	v_exp_f32_e32 v89, v89
	v_cvt_pk_bf16_f32 v84, v84, v85
	v_cvt_pk_bf16_f32 v85, v86, v87
	v_exp_f32_e32 v90, v90
	v_exp_f32_e32 v91, v91
	v_pk_add_f32 v[150:151], v[150:151], v[88:89]
	v_pk_add_f32 v[150:151], v[150:151], v[90:91]
	v_cvt_pk_bf16_f32 v86, v88, v89
	v_cvt_pk_bf16_f32 v87, v90, v91
	s_waitcnt lgkmcnt(5)
	v_mfma_f32_32x32x16_bf16 v[188:203], v[132:135], v[120:123], v[188:203]
	v_exp_f32_e32 v92, v92
	v_exp_f32_e32 v93, v93
	v_exp_f32_e32 v94, v94
	v_exp_f32_e32 v95, v95
	v_pk_add_f32 v[150:151], v[150:151], v[92:93]
	v_pk_add_f32 v[150:151], v[150:151], v[94:95]
	v_exp_f32_e32 v96, v96
	s_waitcnt lgkmcnt(4)
	v_mfma_f32_32x32x16_bf16 v[204:219], v[136:139], v[120:123], v[204:219]
	s_add_u32 m0, s25, s10
	s_add_u32 m0, m0, 0x2000
	s_nop 0
	global_load_lds_dwordx4 v161, s[4:5]
	v_exp_f32_e32 v97, v97
	v_cvt_pk_bf16_f32 v88, v92, v93
	v_cvt_pk_bf16_f32 v89, v94, v95
	v_exp_f32_e32 v98, v98
	v_exp_f32_e32 v99, v99
	v_pk_add_f32 v[150:151], v[150:151], v[96:97]
	v_pk_add_f32 v[150:151], v[150:151], v[98:99]
	v_cvt_pk_bf16_f32 v90, v96, v97
	v_cvt_pk_bf16_f32 v91, v98, v99
	s_waitcnt lgkmcnt(3)
	v_mfma_f32_32x32x16_bf16 v[188:203], v[140:143], v[124:127], v[188:203]
	v_exp_f32_e32 v100, v100
	v_exp_f32_e32 v101, v101
	v_exp_f32_e32 v102, v102
	v_exp_f32_e32 v103, v103
	v_pk_add_f32 v[150:151], v[150:151], v[100:101]
	v_pk_add_f32 v[150:151], v[150:151], v[102:103]
	v_exp_f32_e32 v104, v104
	s_waitcnt lgkmcnt(2)
	v_mfma_f32_32x32x16_bf16 v[204:219], v[144:147], v[124:127], v[204:219]
	v_exp_f32_e32 v105, v105
	v_cvt_pk_bf16_f32 v100, v100, v101
	v_cvt_pk_bf16_f32 v101, v102, v103
	v_exp_f32_e32 v106, v106
	v_exp_f32_e32 v107, v107
	v_pk_add_f32 v[150:151], v[150:151], v[104:105]
	v_pk_add_f32 v[150:151], v[150:151], v[106:107]
	v_cvt_pk_bf16_f32 v102, v104, v105
	v_cvt_pk_bf16_f32 v103, v106, v107
	s_waitcnt lgkmcnt(1)
	v_mfma_f32_32x32x16_bf16 v[188:203], v[220:223], v[128:131], v[188:203]
	v_exp_f32_e32 v108, v108
	v_exp_f32_e32 v109, v109
	v_exp_f32_e32 v110, v110
	v_exp_f32_e32 v111, v111
	v_pk_add_f32 v[150:151], v[150:151], v[108:109]
	v_pk_add_f32 v[150:151], v[150:151], v[110:111]
	v_exp_f32_e32 v112, v112
	s_waitcnt lgkmcnt(0)
	v_mfma_f32_32x32x16_bf16 v[204:219], v[224:227], v[128:131], v[204:219]
	v_exp_f32_e32 v113, v113
	v_cvt_pk_bf16_f32 v104, v108, v109
	v_cvt_pk_bf16_f32 v105, v110, v111
	v_exp_f32_e32 v114, v114
	v_exp_f32_e32 v115, v115
	v_pk_add_f32 v[150:151], v[150:151], v[112:113]
	v_pk_add_f32 v[150:151], v[150:151], v[114:115]
	v_cvt_pk_bf16_f32 v106, v112, v113
	v_cvt_pk_bf16_f32 v107, v114, v115
	s_mov_b32 s30, s10
	s_mov_b32 s10, s35
	s_mov_b32 s35, s31
	s_mov_b32 s31, s30
	s_add_u32 s8, s8, 0x40000
	s_addc_u32 s9, s9, 0
	s_add_i32 s36, s36, 64
	s_mov_b32 s24, s29
	s_waitcnt vmcnt(2) lgkmcnt(0)
	s_barrier
	s_cmp_eq_u32 s24, 0
	s_cbranch_scc1 .LatB_near_t1
.LatB_nearret_t1:
	v_add_u32_e32 v232, s35, v19
	v_add_u32_e32 v233, s35, v180
	v_add_u32_e32 v234, s35, v181
	v_add_u32_e32 v235, s35, v182
	v_add_u32_e32 v236, s31, v228
	v_add_u32_e32 v237, s31, v229
	v_add_u32_e32 v238, s31, v230
	v_add_u32_e32 v239, s31, v231
	s_add_u32 s4, s8, 0x80000
	s_addc_u32 s5, s9, 0
	ds_read_b64_tr_b16 v[132:133], v236 offset:0
	ds_read_b64_tr_b16 v[134:135], v236 offset:2048
	ds_read_b64_tr_b16 v[136:137], v237 offset:0
	ds_read_b64_tr_b16 v[138:139], v237 offset:2048
	ds_read_b64_tr_b16 v[140:141], v238 offset:0
	ds_read_b64_tr_b16 v[142:143], v238 offset:2048
	ds_read_b64_tr_b16 v[144:145], v239 offset:0
	ds_read_b64_tr_b16 v[146:147], v239 offset:2048
	ds_read_b64_tr_b16 v[220:221], v236 offset:4096
	ds_read_b64_tr_b16 v[222:223], v236 offset:6144
	ds_read_b64_tr_b16 v[224:225], v237 offset:4096
	ds_read_b64_tr_b16 v[226:227], v237 offset:6144
	v_max3_f32 v251, v188, v189, v190
	v_max3_f32 v252, v191, v192, v193
	v_max3_f32 v251, v251, v194, v195
	v_max3_f32 v252, v252, v196, v197
	v_max3_f32 v251, v251, v198, v199
	v_max3_f32 v252, v252, v200, v201
	v_max3_f32 v251, v251, v202, v203
	v_max3_f32 v252, v252, v204, v205
	v_max3_f32 v251, v251, v206, v207
	v_max3_f32 v252, v252, v208, v209
	v_max3_f32 v251, v251, v210, v211
	v_max3_f32 v252, v252, v212, v213
	v_max3_f32 v251, v251, v214, v215
	v_max3_f32 v252, v252, v216, v217
	v_max3_f32 v251, v251, v218, v219
	v_max_f32_e32 v251, v251, v252
	s_nop 0
	v_cmp_lt_f32_e32 vcc, 0x41000000, v251
	s_cbranch_vccnz .LatB_rare_t1

; __device__ __forceinline__ void attn_unit(LAS unsigned char* lds, const bf16_t* Z, bf16_t* A2, const float* tabg, int seq_base, int S, int h, int qb, float lam) {
;     ...
;             p0 = __builtin_amdgcn_mfma_f32_32x32x16_bf16(kf[0], qf[0], cblk, 0, 0, 0);
;             p1 = __builtin_amdgcn_mfma_f32_32x32x16_bf16(kf[1], qf[0], cblk, 0, 0, 0);
; #pragma unroll
;             for (int ds = 1; ds < 4; ++ds) {
;                 p0 = __builtin_amdgcn_mfma_f32_32x32x16_bf16(kf[2 * ds], qf[ds], p0, 0, 0, 0);
;                 p1 = __builtin_amdgcn_mfma_f32_32x32x16_bf16(kf[2 * ds + 1], qf[ds], p1, 0, 0, 0);
;             }
;         }
;     ...
;         const unsigned vbase = (unsigned)(size_t)Vt + vfo;
;         s16x4 va[8], vb[8];
;         VREADS1(va, 0);
;         if (near) {
;             const LAS float* tp = tab + (kv0 + 4 * hi - (qlo + r32) + 224);
; #pragma unroll
;             for (int r = 0; r < 16; ++r) { p0[r] += tp[(r & 3) + 8 * (r >> 2)]; p1[r] += tp[32 + (r & 3) + 8 * (r >> 2)]; }
;         }
;         float mx = max2f(max16f(p0), max16f(p1));
;         const bool first = (t == 0);
;         if (first || __any(mx > THR)) {
;             { auto rr = __builtin_amdgcn_permlane32_swap(__float_as_uint(mx), __float_as_uint(mx), false, false); mx = max2f(__uint_as_float(rr[0]), __uint_as_float(rr[1])); }
;             const float delta = first ? mx : fmaxf(mx, 0.f);
;             const float alpha = first ? 1.0f : __builtin_amdgcn_exp2f(-delta);
;             mu += delta; ls2 *= alpha;
;             if (!first) {
;                 asm volatile("" ::: "memory");
;                 scr[r32] = alpha;
;                 asm volatile("s_waitcnt lgkmcnt(0)" ::: "memory");
; #pragma unroll
;                 for (int g = 0; g < 4; ++g) { const f32x4 a4 = *(const LAS f32x4*)(scr + 8 * g + 4 * hi);
; #pragma unroll
;                     for (int d = 0; d < 4; ++d) { O[d][4 * g + 0] *= a4[0]; O[d][4 * g + 1] *= a4[1]; O[d][4 * g + 2] *= a4[2]; O[d][4 * g + 3] *= a4[3]; } }
;                 asm volatile("s_waitcnt lgkmcnt(0)" ::: "memory");
;             }
; #pragma unroll
;             for (int r = 0; r < 16; ++r) { p0[r] -= delta; p1[r] -= delta; }
;             asm volatile("" : "+v"(p0), "+v"(p1));
;         }
; #pragma unroll
;         for (int r = 0; r < 16; ++r) { p0[r] = __builtin_amdgcn_exp2f(p0[r]); p1[r] = __builtin_amdgcn_exp2f(p1[r]); }
; #pragma unroll
.LatB_rebuildret_t1:
	s_waitcnt lgkmcnt(10)
	v_mfma_f32_32x32x16_bf16 v[20:35], v[84:87], v[132:135], v[20:35]
	ds_read_b64_tr_b16 v[132:133], v238 offset:4096
	ds_read_b64_tr_b16 v[134:135], v238 offset:6144
	v_exp_f32_e32 v188, v188
	v_exp_f32_e32 v189, v189
	s_waitcnt lgkmcnt(10)
	v_mfma_f32_32x32x16_bf16 v[36:51], v[84:87], v[136:139], v[36:51]
	ds_read_b64_tr_b16 v[136:137], v239 offset:4096
	ds_read_b64_tr_b16 v[138:139], v239 offset:6144
	v_exp_f32_e32 v190, v190
	v_exp_f32_e32 v191, v191
	s_waitcnt lgkmcnt(10)
	v_mfma_f32_32x32x16_bf16 v[52:67], v[84:87], v[140:143], v[52:67]
	ds_read_b64_tr_b16 v[140:141], v236 offset:8192
	ds_read_b64_tr_b16 v[142:143], v236 offset:10240
	v_pk_add_f32 v[150:151], v[150:151], v[188:189]
	v_pk_add_f32 v[150:151], v[150:151], v[190:191]
	v_exp_f32_e32 v192, v192
	s_waitcnt lgkmcnt(10)
	v_mfma_f32_32x32x16_bf16 v[68:83], v[84:87], v[144:147], v[68:83]
	ds_read_b64_tr_b16 v[144:145], v237 offset:8192
	ds_read_b64_tr_b16 v[146:147], v237 offset:10240
	s_add_u32 m0, s25, s10
	s_nop 0
	global_load_lds_dwordx4 v160, s[4:5]
	v_exp_f32_e32 v193, v193
	v_cvt_pk_bf16_f32 v188, v188, v189
	v_cvt_pk_bf16_f32 v189, v190, v191
	s_waitcnt lgkmcnt(10)
	v_mfma_f32_32x32x16_bf16 v[20:35], v[88:91], v[220:223], v[20:35]
	ds_read_b64_tr_b16 v[220:221], v238 offset:8192
	ds_read_b64_tr_b16 v[222:223], v238 offset:10240
	v_exp_f32_e32 v194, v194
	v_exp_f32_e32 v195, v195
	s_waitcnt lgkmcnt(10)
	v_mfma_f32_32x32x16_bf16 v[36:51], v[88:91], v[224:227], v[36:51]
	ds_read_b64_tr_b16 v[224:225], v239 offset:8192
	ds_read_b64_tr_b16 v[226:227], v239 offset:10240
	v_pk_add_f32 v[150:151], v[150:151], v[192:193]
	v_pk_add_f32 v[150:151], v[150:151], v[194:195]
	v_cvt_pk_bf16_f32 v190, v192, v193
	v_cvt_pk_bf16_f32 v191, v194, v195
	s_waitcnt lgkmcnt(10)
	v_mfma_f32_32x32x16_bf16 v[52:67], v[88:91], v[132:135], v[52:67]
	ds_read_b64_tr_b16 v[132:133], v236 offset:12288
	ds_read_b64_tr_b16 v[134:135], v236 offset:14336
	v_exp_f32_e32 v196, v196
	v_exp_f32_e32 v197, v197
	s_waitcnt lgkmcnt(10)
	v_mfma_f32_32x32x16_bf16 v[68:83], v[88:91], v[136:139], v[68:83]
	ds_read_b64_tr_b16 v[136:137], v237 offset:12288
	ds_read_b64_tr_b16 v[138:139], v237 offset:14336
	s_add_u32 m0, s27, s35
	s_nop 0
	global_load_lds_dwordx4 v149, s[8:9]
	v_exp_f32_e32 v198, v198
	v_exp_f32_e32 v199, v199
	s_waitcnt lgkmcnt(10)
	v_mfma_f32_32x32x16_bf16 v[20:35], v[100:103], v[140:143], v[20:35]
	ds_read_b64_tr_b16 v[140:141], v238 offset:12288
	ds_read_b64_tr_b16 v[142:143], v238 offset:14336
	v_pk_add_f32 v[150:151], v[150:151], v[196:197]
	v_pk_add_f32 v[150:151], v[150:151], v[198:199]
	v_exp_f32_e32 v200, v200
	s_waitcnt lgkmcnt(10)
	v_mfma_f32_32x32x16_bf16 v[36:51], v[100:103], v[144:147], v[36:51]
	ds_read_b64_tr_b16 v[144:145], v239 offset:12288
	ds_read_b64_tr_b16 v[146:147], v239 offset:14336
	v_exp_f32_e32 v201, v201
	v_cvt_pk_bf16_f32 v192, v196, v197
	v_cvt_pk_bf16_f32 v193, v198, v199
	s_waitcnt lgkmcnt(10)
	v_mfma_f32_32x32x16_bf16 v[52:67], v[100:103], v[220:223], v[52:67]
	ds_read_b128 v[220:223], v232
	v_exp_f32_e32 v202, v202
	v_exp_f32_e32 v203, v203
	s_waitcnt lgkmcnt(9)
	v_mfma_f32_32x32x16_bf16 v[68:83], v[100:103], v[224:227], v[68:83]
	ds_read_b128 v[224:227], v232 offset:8192
	s_add_u32 m0, s25, s10
	s_add_u32 m0, m0, 0x2000
	s_nop 0
	global_load_lds_dwordx4 v161, s[4:5]
	v_pk_add_f32 v[150:151], v[150:151], v[200:201]
	v_pk_add_f32 v[150:151], v[150:151], v[202:203]
	v_cvt_pk_bf16_f32 v194, v200, v201
	v_cvt_pk_bf16_f32 v195, v202, v203
	s_waitcnt lgkmcnt(8)
	v_mfma_f32_32x32x16_bf16 v[20:35], v[104:107], v[132:135], v[20:35]
	ds_read_b128 v[132:135], v233
	v_exp_f32_e32 v204, v204
	v_exp_f32_e32 v205, v205
	s_waitcnt lgkmcnt(7)
	v_mfma_f32_32x32x16_bf16 v[36:51], v[104:107], v[136:139], v[36:51]
	ds_read_b128 v[136:139], v233 offset:8192
	v_exp_f32_e32 v206, v206
	v_exp_f32_e32 v207, v207
	s_waitcnt lgkmcnt(6)
	v_mfma_f32_32x32x16_bf16 v[52:67], v[104:107], v[140:143], v[52:67]
	ds_read_b128 v[140:143], v234
	v_pk_add_f32 v[150:151], v[150:151], v[204:205]
	v_pk_add_f32 v[150:151], v[150:151], v[206:207]
	v_exp_f32_e32 v208, v208
	s_waitcnt lgkmcnt(5)
	v_mfma_f32_32x32x16_bf16 v[68:83], v[104:107], v[144:147], v[68:83]
	ds_read_b128 v[144:147], v234 offset:8192
	s_add_u32 m0, s27, s35
	s_add_u32 m0, m0, 0x2000
	s_nop 0
	global_load_lds_dwordx4 v176, s[8:9]
	v_exp_f32_e32 v209, v209
	v_cvt_pk_bf16_f32 v204, v204, v205
	v_cvt_pk_bf16_f32 v205, v206, v207
	s_waitcnt lgkmcnt(5)
	v_mfma_f32_32x32x16_bf16 v[84:99], v[220:223], v[116:119], v[2:17]
	ds_read_b128 v[220:223], v235
	v_exp_f32_e32 v210, v210
	v_exp_f32_e32 v211, v211
	s_waitcnt lgkmcnt(5)
	v_mfma_f32_32x32x16_bf16 v[100:115], v[224:227], v[116:119], v[2:17]
	ds_read_b128 v[224:227], v235 offset:8192
	v_pk_add_f32 v[150:151], v[150:151], v[208:209]
	v_pk_add_f32 v[150:151], v[150:151], v[210:211]
	v_cvt_pk_bf16_f32 v206, v208, v209
	v_cvt_pk_bf16_f32 v207, v210, v211
	s_waitcnt lgkmcnt(5)
	v_mfma_f32_32x32x16_bf16 v[84:99], v[132:135], v[120:123], v[84:99]
	v_exp_f32_e32 v212, v212
	v_exp_f32_e32 v213, v213
	s_waitcnt lgkmcnt(4)
	v_mfma_f32_32x32x16_bf16 v[100:115], v[136:139], v[120:123], v[100:115]
	v_exp_f32_e32 v214, v214
	v_exp_f32_e32 v215, v215
	s_waitcnt lgkmcnt(3)
	v_mfma_f32_32x32x16_bf16 v[84:99], v[140:143], v[124:127], v[84:99]
	v_pk_add_f32 v[150:151], v[150:151], v[212:213]
	v_pk_add_f32 v[150:151], v[150:151], v[214:215]
	v_exp_f32_e32 v216, v216
	s_waitcnt lgkmcnt(2)
	v_mfma_f32_32x32x16_bf16 v[100:115], v[144:147], v[124:127], v[100:115]
	v_exp_f32_e32 v217, v217
	v_cvt_pk_bf16_f32 v208, v212, v213
	v_cvt_pk_bf16_f32 v209, v214, v215
	s_waitcnt lgkmcnt(1)
	v_mfma_f32_32x32x16_bf16 v[84:99], v[220:223], v[128:131], v[84:99]
	v_exp_f32_e32 v218, v218
	v_exp_f32_e32 v219, v219
	s_waitcnt lgkmcnt(0)
	v_mfma_f32_32x32x16_bf16 v[100:115], v[224:227], v[128:131], v[100:115]
	v_pk_add_f32 v[150:151], v[150:151], v[216:217]
	v_pk_add_f32 v[150:151], v[150:151], v[218:219]
	v_cvt_pk_bf16_f32 v210, v216, v217
	v_cvt_pk_bf16_f32 v211, v218, v219
	s_mov_b32 s30, s10
	s_mov_b32 s10, s35
	s_mov_b32 s35, s31
	s_mov_b32 s31, s30
	s_add_u32 s8, s8, 0x40000
	s_addc_u32 s9, s9, 0
	s_add_i32 s36, s36, 64
	s_mov_b32 s24, s29
	s_waitcnt vmcnt(4) lgkmcnt(0)
	s_barrier
	s_movk_i32 s23, 125
; #define LAS __attribute__((address_space(3)))
; __device__ __forceinline__ float max2f(float a, float b) { float r; asm("v_max_f32_e32 %0, %1, %2" : "=v"(r) : "v"(a), "v"(b)); return r; }
; #define VREADS1(arr, d_) do { const unsigned ad_ = vbase ^ (unsigned)((d_) << 6); __builtin_amdgcn_sched_barrier(0); \
;         _Pragma("unroll") for (int ks_ = 0; ks_ < 4; ++ks_) { VTR(arr[ks_ * 2], ad_, ks_ * 4096); VTR(arr[ks_ * 2 + 1], ad_, ks_ * 4096 + 2048); } __builtin_amdgcn_sched_barrier(0); } while (0)
; __device__ __forceinline__ void attn_unit(LAS unsigned char* lds, const bf16_t* Z, bf16_t* A2, const float* tabg, int seq_base, int S, int h, int qb, float lam) {
;     ...
;         const unsigned vbase = (unsigned)(size_t)Vt + vfo;
;         s16x4 va[8], vb[8];
;         VREADS1(va, 0);
;         if (near) {
;             const LAS float* tp = tab + (kv0 + 4 * hi - (qlo + r32) + 224);
; #pragma unroll
;             for (int r = 0; r < 16; ++r) { p0[r] += tp[(r & 3) + 8 * (r >> 2)]; p1[r] += tp[32 + (r & 3) + 8 * (r >> 2)]; }
;         }
;         float mx = max2f(max16f(p0), max16f(p1));
;         const bool first = (t == 0);
;         if (first || __any(mx > THR)) {
.LatB_loop:
	s_cmp_eq_u32 s24, 0
	s_cbranch_scc1 .LatB_near_e
.LatB_nearret_e:
	v_add_u32_e32 v232, s35, v19
	v_add_u32_e32 v233, s35, v180
	v_add_u32_e32 v234, s35, v181
	v_add_u32_e32 v235, s35, v182
	v_add_u32_e32 v236, s31, v228
	v_add_u32_e32 v237, s31, v229
	v_add_u32_e32 v238, s31, v230
	v_add_u32_e32 v239, s31, v231
	s_add_u32 s4, s8, 0x80000
	s_addc_u32 s5, s9, 0
	ds_read_b64_tr_b16 v[132:133], v236 offset:0
	ds_read_b64_tr_b16 v[134:135], v236 offset:2048
	ds_read_b64_tr_b16 v[136:137], v237 offset:0
	ds_read_b64_tr_b16 v[138:139], v237 offset:2048
	ds_read_b64_tr_b16 v[140:141], v238 offset:0
	ds_read_b64_tr_b16 v[142:143], v238 offset:2048
	ds_read_b64_tr_b16 v[144:145], v239 offset:0
	ds_read_b64_tr_b16 v[146:147], v239 offset:2048
	ds_read_b64_tr_b16 v[220:221], v236 offset:4096
	ds_read_b64_tr_b16 v[222:223], v236 offset:6144
	ds_read_b64_tr_b16 v[224:225], v237 offset:4096
	ds_read_b64_tr_b16 v[226:227], v237 offset:6144
	v_max3_f32 v251, v84, v85, v86
	v_max3_f32 v252, v87, v88, v89
	v_max3_f32 v251, v251, v90, v91
	v_max3_f32 v252, v252, v92, v93
	v_max3_f32 v251, v251, v94, v95
	v_max3_f32 v252, v252, v96, v97
	v_max3_f32 v251, v251, v98, v99
	v_max3_f32 v252, v252, v100, v101
	v_max3_f32 v251, v251, v102, v103
	v_max3_f32 v252, v252, v104, v105
	v_max3_f32 v251, v251, v106, v107
	v_max3_f32 v252, v252, v108, v109
	v_max3_f32 v251, v251, v110, v111
	v_max3_f32 v252, v252, v112, v113
	v_max3_f32 v251, v251, v114, v115
	v_max_f32_e32 v251, v251, v252
	s_nop 0
	v_cmp_lt_f32_e32 vcc, 0x41000000, v251
	s_cbranch_vccnz .LatB_rare_e

; __device__ __forceinline__ void attn_unit(LAS unsigned char* lds, const bf16_t* Z, bf16_t* A2, const float* tabg, int seq_base, int S, int h, int qb, float lam) {
;     ...
;             p0 = __builtin_amdgcn_mfma_f32_32x32x16_bf16(kf[0], qf[0], cblk, 0, 0, 0);
;             p1 = __builtin_amdgcn_mfma_f32_32x32x16_bf16(kf[1], qf[0], cblk, 0, 0, 0);
; #pragma unroll
;             for (int ds = 1; ds < 4; ++ds) {
;                 p0 = __builtin_amdgcn_mfma_f32_32x32x16_bf16(kf[2 * ds], qf[ds], p0, 0, 0, 0);
;                 p1 = __builtin_amdgcn_mfma_f32_32x32x16_bf16(kf[2 * ds + 1], qf[ds], p1, 0, 0, 0);
;             }
;         }
;     ...
;         const unsigned vbase = (unsigned)(size_t)Vt + vfo;
;         s16x4 va[8], vb[8];
;         VREADS1(va, 0);
;         if (near) {
;             const LAS float* tp = tab + (kv0 + 4 * hi - (qlo + r32) + 224);
; #pragma unroll
;             for (int r = 0; r < 16; ++r) { p0[r] += tp[(r & 3) + 8 * (r >> 2)]; p1[r] += tp[32 + (r & 3) + 8 * (r >> 2)]; }
;         }
;         float mx = max2f(max16f(p0), max16f(p1));
;         const bool first = (t == 0);
;         if (first || __any(mx > THR)) {
;             { auto rr = __builtin_amdgcn_permlane32_swap(__float_as_uint(mx), __float_as_uint(mx), false, false); mx = max2f(__uint_as_float(rr[0]), __uint_as_float(rr[1])); }
;             const float delta = first ? mx : fmaxf(mx, 0.f);
;             const float alpha = first ? 1.0f : __builtin_amdgcn_exp2f(-delta);
;             mu += delta; ls2 *= alpha;
;             if (!first) {
;                 asm volatile("" ::: "memory");
;                 scr[r32] = alpha;
;                 asm volatile("s_waitcnt lgkmcnt(0)" ::: "memory");
; #pragma unroll
;                 for (int g = 0; g < 4; ++g) { const f32x4 a4 = *(const LAS f32x4*)(scr + 8 * g + 4 * hi);
; #pragma unroll
;                     for (int d = 0; d < 4; ++d) { O[d][4 * g + 0] *= a4[0]; O[d][4 * g + 1] *= a4[1]; O[d][4 * g + 2] *= a4[2]; O[d][4 * g + 3] *= a4[3]; } }
;                 asm volatile("s_waitcnt lgkmcnt(0)" ::: "memory");
;             }
; #pragma unroll
;             for (int r = 0; r < 16; ++r) { p0[r] -= delta; p1[r] -= delta; }
;             asm volatile("" : "+v"(p0), "+v"(p1));
;         }
; #pragma unroll
;         for (int r = 0; r < 16; ++r) { p0[r] = __builtin_amdgcn_exp2f(p0[r]); p1[r] = __builtin_amdgcn_exp2f(p1[r]); }
; #pragma unroll
.LatB_rebuildret_e:
	s_waitcnt lgkmcnt(10)
	v_mfma_f32_32x32x16_bf16 v[20:35], v[188:191], v[132:135], v[20:35]
	ds_read_b64_tr_b16 v[132:133], v238 offset:4096
	ds_read_b64_tr_b16 v[134:135], v238 offset:6144
	v_exp_f32_e32 v84, v84
	v_exp_f32_e32 v85, v85
	s_waitcnt lgkmcnt(10)
	v_mfma_f32_32x32x16_bf16 v[36:51], v[188:191], v[136:139], v[36:51]
	ds_read_b64_tr_b16 v[136:137], v239 offset:4096
	ds_read_b64_tr_b16 v[138:139], v239 offset:6144
	v_exp_f32_e32 v86, v86
	v_exp_f32_e32 v87, v87
	s_waitcnt lgkmcnt(10)
	v_mfma_f32_32x32x16_bf16 v[52:67], v[188:191], v[140:143], v[52:67]
	ds_read_b64_tr_b16 v[140:141], v236 offset:8192
	ds_read_b64_tr_b16 v[142:143], v236 offset:10240
	v_pk_add_f32 v[150:151], v[150:151], v[84:85]
	v_pk_add_f32 v[150:151], v[150:151], v[86:87]
	v_exp_f32_e32 v88, v88
	s_waitcnt lgkmcnt(10)
	v_mfma_f32_32x32x16_bf16 v[68:83], v[188:191], v[144:147], v[68:83]
	ds_read_b64_tr_b16 v[144:145], v237 offset:8192
	ds_read_b64_tr_b16 v[146:147], v237 offset:10240
	s_add_u32 m0, s25, s10
	s_nop 0
	global_load_lds_dwordx4 v160, s[4:5]
	v_exp_f32_e32 v89, v89
	v_cvt_pk_bf16_f32 v84, v84, v85
	v_cvt_pk_bf16_f32 v85, v86, v87
	s_waitcnt lgkmcnt(10)
	v_mfma_f32_32x32x16_bf16 v[20:35], v[192:195], v[220:223], v[20:35]
	ds_read_b64_tr_b16 v[220:221], v238 offset:8192
	ds_read_b64_tr_b16 v[222:223], v238 offset:10240
	v_exp_f32_e32 v90, v90
	v_exp_f32_e32 v91, v91
	s_waitcnt lgkmcnt(10)
	v_mfma_f32_32x32x16_bf16 v[36:51], v[192:195], v[224:227], v[36:51]
	ds_read_b64_tr_b16 v[224:225], v239 offset:8192
	ds_read_b64_tr_b16 v[226:227], v239 offset:10240
	v_pk_add_f32 v[150:151], v[150:151], v[88:89]
	v_pk_add_f32 v[150:151], v[150:151], v[90:91]
	v_cvt_pk_bf16_f32 v86, v88, v89
	v_cvt_pk_bf16_f32 v87, v90, v91
	s_waitcnt lgkmcnt(10)
	v_mfma_f32_32x32x16_bf16 v[52:67], v[192:195], v[132:135], v[52:67]
	ds_read_b64_tr_b16 v[132:133], v236 offset:12288
	ds_read_b64_tr_b16 v[134:135], v236 offset:14336
	v_exp_f32_e32 v92, v92
	v_exp_f32_e32 v93, v93
	s_waitcnt lgkmcnt(10)
	v_mfma_f32_32x32x16_bf16 v[68:83], v[192:195], v[136:139], v[68:83]
	ds_read_b64_tr_b16 v[136:137], v237 offset:12288
	ds_read_b64_tr_b16 v[138:139], v237 offset:14336
	s_add_u32 m0, s27, s35
	s_nop 0
	global_load_lds_dwordx4 v149, s[8:9]
	v_exp_f32_e32 v94, v94
	v_exp_f32_e32 v95, v95
	s_waitcnt lgkmcnt(10)
	v_mfma_f32_32x32x16_bf16 v[20:35], v[204:207], v[140:143], v[20:35]
	ds_read_b64_tr_b16 v[140:141], v238 offset:12288
	ds_read_b64_tr_b16 v[142:143], v238 offset:14336
	v_pk_add_f32 v[150:151], v[150:151], v[92:93]
	v_pk_add_f32 v[150:151], v[150:151], v[94:95]
	v_exp_f32_e32 v96, v96
	s_waitcnt lgkmcnt(10)
	v_mfma_f32_32x32x16_bf16 v[36:51], v[204:207], v[144:147], v[36:51]
	ds_read_b64_tr_b16 v[144:145], v239 offset:12288
	ds_read_b64_tr_b16 v[146:147], v239 offset:14336
	v_exp_f32_e32 v97, v97
	v_cvt_pk_bf16_f32 v88, v92, v93
	v_cvt_pk_bf16_f32 v89, v94, v95
	s_waitcnt lgkmcnt(10)
	v_mfma_f32_32x32x16_bf16 v[52:67], v[204:207], v[220:223], v[52:67]
	ds_read_b128 v[220:223], v232
	v_exp_f32_e32 v98, v98
	v_exp_f32_e32 v99, v99
	s_waitcnt lgkmcnt(9)
	v_mfma_f32_32x32x16_bf16 v[68:83], v[204:207], v[224:227], v[68:83]
	ds_read_b128 v[224:227], v232 offset:8192
	s_add_u32 m0, s25, s10
	s_add_u32 m0, m0, 0x2000
	s_nop 0
	global_load_lds_dwordx4 v161, s[4:5]
	v_pk_add_f32 v[150:151], v[150:151], v[96:97]
	v_pk_add_f32 v[150:151], v[150:151], v[98:99]
	v_cvt_pk_bf16_f32 v90, v96, v97
	v_cvt_pk_bf16_f32 v91, v98, v99
	s_waitcnt lgkmcnt(8)
	v_mfma_f32_32x32x16_bf16 v[20:35], v[208:211], v[132:135], v[20:35]
	ds_read_b128 v[132:135], v233
	v_exp_f32_e32 v100, v100
	v_exp_f32_e32 v101, v101
	s_waitcnt lgkmcnt(7)
	v_mfma_f32_32x32x16_bf16 v[36:51], v[208:211], v[136:139], v[36:51]
	ds_read_b128 v[136:139], v233 offset:8192
	v_exp_f32_e32 v102, v102
	v_exp_f32_e32 v103, v103
	s_waitcnt lgkmcnt(6)
	v_mfma_f32_32x32x16_bf16 v[52:67], v[208:211], v[140:143], v[52:67]
	ds_read_b128 v[140:143], v234
	v_pk_add_f32 v[150:151], v[150:151], v[100:101]
	v_pk_add_f32 v[150:151], v[150:151], v[102:103]
	v_exp_f32_e32 v104, v104
	s_waitcnt lgkmcnt(5)
	v_mfma_f32_32x32x16_bf16 v[68:83], v[208:211], v[144:147], v[68:83]
	ds_read_b128 v[144:147], v234 offset:8192
	s_add_u32 m0, s27, s35
	s_add_u32 m0, m0, 0x2000
	s_nop 0
	global_load_lds_dwordx4 v176, s[8:9]
	v_exp_f32_e32 v105, v105
	v_cvt_pk_bf16_f32 v100, v100, v101
	v_cvt_pk_bf16_f32 v101, v102, v103
	s_waitcnt lgkmcnt(5)
	v_mfma_f32_32x32x16_bf16 v[188:203], v[220:223], v[116:119], v[2:17]
	ds_read_b128 v[220:223], v235
	v_exp_f32_e32 v106, v106
	v_exp_f32_e32 v107, v107
	s_waitcnt lgkmcnt(5)
	v_mfma_f32_32x32x16_bf16 v[204:219], v[224:227], v[116:119], v[2:17]
	ds_read_b128 v[224:227], v235 offset:8192
	v_pk_add_f32 v[150:151], v[150:151], v[104:105]
	v_pk_add_f32 v[150:151], v[150:151], v[106:107]
	v_cvt_pk_bf16_f32 v102, v104, v105
	v_cvt_pk_bf16_f32 v103, v106, v107
	s_waitcnt lgkmcnt(5)
	v_mfma_f32_32x32x16_bf16 v[188:203], v[132:135], v[120:123], v[188:203]
	v_exp_f32_e32 v108, v108
	v_exp_f32_e32 v109, v109
	s_waitcnt lgkmcnt(4)
	v_mfma_f32_32x32x16_bf16 v[204:219], v[136:139], v[120:123], v[204:219]
	v_exp_f32_e32 v110, v110
	v_exp_f32_e32 v111, v111
	s_waitcnt lgkmcnt(3)
	v_mfma_f32_32x32x16_bf16 v[188:203], v[140:143], v[124:127], v[188:203]
	v_pk_add_f32 v[150:151], v[150:151], v[108:109]
	v_pk_add_f32 v[150:151], v[150:151], v[110:111]
	v_exp_f32_e32 v112, v112
	s_waitcnt lgkmcnt(2)
	v_mfma_f32_32x32x16_bf16 v[204:219], v[144:147], v[124:127], v[204:219]
	v_exp_f32_e32 v113, v113
	v_cvt_pk_bf16_f32 v104, v108, v109
	v_cvt_pk_bf16_f32 v105, v110, v111
	s_waitcnt lgkmcnt(1)
	v_mfma_f32_32x32x16_bf16 v[188:203], v[220:223], v[128:131], v[188:203]
	v_exp_f32_e32 v114, v114
	v_exp_f32_e32 v115, v115
	s_waitcnt lgkmcnt(0)
	v_mfma_f32_32x32x16_bf16 v[204:219], v[224:227], v[128:131], v[204:219]
	v_pk_add_f32 v[150:151], v[150:151], v[112:113]
	v_pk_add_f32 v[150:151], v[150:151], v[114:115]
	v_cvt_pk_bf16_f32 v106, v112, v113
	v_cvt_pk_bf16_f32 v107, v114, v115
	s_mov_b32 s30, s10
	s_mov_b32 s10, s35
	s_mov_b32 s35, s31
	s_mov_b32 s31, s30
	s_add_u32 s8, s8, 0x40000
	s_addc_u32 s9, s9, 0
	s_add_i32 s36, s36, 64
	s_mov_b32 s24, s29
	s_waitcnt vmcnt(4) lgkmcnt(0)
	s_barrier
	s_cmp_eq_u32 s24, 0
	s_cbranch_scc1 .LatB_near_o

; __device__ __forceinline__ void attn_unit(LAS unsigned char* lds, const bf16_t* Z, bf16_t* A2, const float* tabg, int seq_base, int S, int h, int qb, float lam) {
;     ...
;             p0 = __builtin_amdgcn_mfma_f32_32x32x16_bf16(kf[0], qf[0], cblk, 0, 0, 0);
;             p1 = __builtin_amdgcn_mfma_f32_32x32x16_bf16(kf[1], qf[0], cblk, 0, 0, 0);
; #pragma unroll
;             for (int ds = 1; ds < 4; ++ds) {
;                 p0 = __builtin_amdgcn_mfma_f32_32x32x16_bf16(kf[2 * ds], qf[ds], p0, 0, 0, 0);
;                 p1 = __builtin_amdgcn_mfma_f32_32x32x16_bf16(kf[2 * ds + 1], qf[ds], p1, 0, 0, 0);
;             }
;         }
;     ...
;         const unsigned vbase = (unsigned)(size_t)Vt + vfo;
;         s16x4 va[8], vb[8];
;         VREADS1(va, 0);
;         if (near) {
;             const LAS float* tp = tab + (kv0 + 4 * hi - (qlo + r32) + 224);
; #pragma unroll
;             for (int r = 0; r < 16; ++r) { p0[r] += tp[(r & 3) + 8 * (r >> 2)]; p1[r] += tp[32 + (r & 3) + 8 * (r >> 2)]; }
;         }
;         float mx = max2f(max16f(p0), max16f(p1));
;         const bool first = (t == 0);
;         if (first || __any(mx > THR)) {
;             { auto rr = __builtin_amdgcn_permlane32_swap(__float_as_uint(mx), __float_as_uint(mx), false, false); mx = max2f(__uint_as_float(rr[0]), __uint_as_float(rr[1])); }
;             const float delta = first ? mx : fmaxf(mx, 0.f);
;             const float alpha = first ? 1.0f : __builtin_amdgcn_exp2f(-delta);
;             mu += delta; ls2 *= alpha;
;             if (!first) {
;                 asm volatile("" ::: "memory");
;                 scr[r32] = alpha;
;                 asm volatile("s_waitcnt lgkmcnt(0)" ::: "memory");
; #pragma unroll
;                 for (int g = 0; g < 4; ++g) { const f32x4 a4 = *(const LAS f32x4*)(scr + 8 * g + 4 * hi);
; #pragma unroll
;                     for (int d = 0; d < 4; ++d) { O[d][4 * g + 0] *= a4[0]; O[d][4 * g + 1] *= a4[1]; O[d][4 * g + 2] *= a4[2]; O[d][4 * g + 3] *= a4[3]; } }
;                 asm volatile("s_waitcnt lgkmcnt(0)" ::: "memory");
;             }
; #pragma unroll
;             for (int r = 0; r < 16; ++r) { p0[r] -= delta; p1[r] -= delta; }
;             asm volatile("" : "+v"(p0), "+v"(p1));
;         }
; #pragma unroll
;         for (int r = 0; r < 16; ++r) { p0[r] = __builtin_amdgcn_exp2f(p0[r]); p1[r] = __builtin_amdgcn_exp2f(p1[r]); }
; #pragma unroll
.LatB_rebuildret_o:
	s_waitcnt lgkmcnt(10)
	v_mfma_f32_32x32x16_bf16 v[20:35], v[84:87], v[132:135], v[20:35]
	ds_read_b64_tr_b16 v[132:133], v238 offset:4096
	ds_read_b64_tr_b16 v[134:135], v238 offset:6144
	v_exp_f32_e32 v188, v188
	v_exp_f32_e32 v189, v189
	s_waitcnt lgkmcnt(10)
	v_mfma_f32_32x32x16_bf16 v[36:51], v[84:87], v[136:139], v[36:51]
	ds_read_b64_tr_b16 v[136:137], v239 offset:4096
	ds_read_b64_tr_b16 v[138:139], v239 offset:6144
	v_exp_f32_e32 v190, v190
	v_exp_f32_e32 v191, v191
	s_waitcnt lgkmcnt(10)
	v_mfma_f32_32x32x16_bf16 v[52:67], v[84:87], v[140:143], v[52:67]
	ds_read_b64_tr_b16 v[140:141], v236 offset:8192
	ds_read_b64_tr_b16 v[142:143], v236 offset:10240
	v_pk_add_f32 v[150:151], v[150:151], v[188:189]
	v_pk_add_f32 v[150:151], v[150:151], v[190:191]
	v_exp_f32_e32 v192, v192
	s_waitcnt lgkmcnt(10)
	v_mfma_f32_32x32x16_bf16 v[68:83], v[84:87], v[144:147], v[68:83]
	ds_read_b64_tr_b16 v[144:145], v237 offset:8192
	ds_read_b64_tr_b16 v[146:147], v237 offset:10240
	s_add_u32 m0, s25, s10
	s_nop 0
	global_load_lds_dwordx4 v160, s[4:5]
	v_exp_f32_e32 v193, v193
	v_cvt_pk_bf16_f32 v188, v188, v189
	v_cvt_pk_bf16_f32 v189, v190, v191
	s_waitcnt lgkmcnt(10)
	v_mfma_f32_32x32x16_bf16 v[20:35], v[88:91], v[220:223], v[20:35]
	ds_read_b64_tr_b16 v[220:221], v238 offset:8192
	ds_read_b64_tr_b16 v[222:223], v238 offset:10240
	v_exp_f32_e32 v194, v194
	v_exp_f32_e32 v195, v195
	s_waitcnt lgkmcnt(10)
	v_mfma_f32_32x32x16_bf16 v[36:51], v[88:91], v[224:227], v[36:51]
	ds_read_b64_tr_b16 v[224:225], v239 offset:8192
	ds_read_b64_tr_b16 v[226:227], v239 offset:10240
	v_pk_add_f32 v[150:151], v[150:151], v[192:193]
	v_pk_add_f32 v[150:151], v[150:151], v[194:195]
	v_cvt_pk_bf16_f32 v190, v192, v193
	v_cvt_pk_bf16_f32 v191, v194, v195
	s_waitcnt lgkmcnt(10)
	v_mfma_f32_32x32x16_bf16 v[52:67], v[88:91], v[132:135], v[52:67]
	ds_read_b64_tr_b16 v[132:133], v236 offset:12288
	ds_read_b64_tr_b16 v[134:135], v236 offset:14336
	v_exp_f32_e32 v196, v196
	v_exp_f32_e32 v197, v197
	s_waitcnt lgkmcnt(10)
	v_mfma_f32_32x32x16_bf16 v[68:83], v[88:91], v[136:139], v[68:83]
	ds_read_b64_tr_b16 v[136:137], v237 offset:12288
	ds_read_b64_tr_b16 v[138:139], v237 offset:14336
	s_add_u32 m0, s27, s35
	s_nop 0
	global_load_lds_dwordx4 v149, s[8:9]
	v_exp_f32_e32 v198, v198
	v_exp_f32_e32 v199, v199
	s_waitcnt lgkmcnt(10)
	v_mfma_f32_32x32x16_bf16 v[20:35], v[100:103], v[140:143], v[20:35]
	ds_read_b64_tr_b16 v[140:141], v238 offset:12288
	ds_read_b64_tr_b16 v[142:143], v238 offset:14336
	v_pk_add_f32 v[150:151], v[150:151], v[196:197]
	v_pk_add_f32 v[150:151], v[150:151], v[198:199]
	v_exp_f32_e32 v200, v200
	s_waitcnt lgkmcnt(10)
	v_mfma_f32_32x32x16_bf16 v[36:51], v[100:103], v[144:147], v[36:51]
	ds_read_b64_tr_b16 v[144:145], v239 offset:12288
	ds_read_b64_tr_b16 v[146:147], v239 offset:14336
	v_exp_f32_e32 v201, v201
	v_cvt_pk_bf16_f32 v192, v196, v197
	v_cvt_pk_bf16_f32 v193, v198, v199
	s_waitcnt lgkmcnt(10)
	v_mfma_f32_32x32x16_bf16 v[52:67], v[100:103], v[220:223], v[52:67]
	ds_read_b128 v[220:223], v232
	v_exp_f32_e32 v202, v202
	v_exp_f32_e32 v203, v203
	s_waitcnt lgkmcnt(9)
	v_mfma_f32_32x32x16_bf16 v[68:83], v[100:103], v[224:227], v[68:83]
	ds_read_b128 v[224:227], v232 offset:8192
	s_add_u32 m0, s25, s10
	s_add_u32 m0, m0, 0x2000
	s_nop 0
	global_load_lds_dwordx4 v161, s[4:5]
	v_pk_add_f32 v[150:151], v[150:151], v[200:201]
	v_pk_add_f32 v[150:151], v[150:151], v[202:203]
	v_cvt_pk_bf16_f32 v194, v200, v201
	v_cvt_pk_bf16_f32 v195, v202, v203
	s_waitcnt lgkmcnt(8)
	v_mfma_f32_32x32x16_bf16 v[20:35], v[104:107], v[132:135], v[20:35]
	ds_read_b128 v[132:135], v233
	v_exp_f32_e32 v204, v204
	v_exp_f32_e32 v205, v205
	s_waitcnt lgkmcnt(7)
	v_mfma_f32_32x32x16_bf16 v[36:51], v[104:107], v[136:139], v[36:51]
	ds_read_b128 v[136:139], v233 offset:8192
	v_exp_f32_e32 v206, v206
	v_exp_f32_e32 v207, v207
	s_waitcnt lgkmcnt(6)
	v_mfma_f32_32x32x16_bf16 v[52:67], v[104:107], v[140:143], v[52:67]
	ds_read_b128 v[140:143], v234
	v_pk_add_f32 v[150:151], v[150:151], v[204:205]
	v_pk_add_f32 v[150:151], v[150:151], v[206:207]
	v_exp_f32_e32 v208, v208
	s_waitcnt lgkmcnt(5)
	v_mfma_f32_32x32x16_bf16 v[68:83], v[104:107], v[144:147], v[68:83]
	ds_read_b128 v[144:147], v234 offset:8192
	s_add_u32 m0, s27, s35
	s_add_u32 m0, m0, 0x2000
	s_nop 0
	global_load_lds_dwordx4 v176, s[8:9]
	v_exp_f32_e32 v209, v209
	v_cvt_pk_bf16_f32 v204, v204, v205
	v_cvt_pk_bf16_f32 v205, v206, v207
	s_waitcnt lgkmcnt(5)
	v_mfma_f32_32x32x16_bf16 v[84:99], v[220:223], v[116:119], v[2:17]
	ds_read_b128 v[220:223], v235
	v_exp_f32_e32 v210, v210
	v_exp_f32_e32 v211, v211
	s_waitcnt lgkmcnt(5)
	v_mfma_f32_32x32x16_bf16 v[100:115], v[224:227], v[116:119], v[2:17]
	ds_read_b128 v[224:227], v235 offset:8192
	v_pk_add_f32 v[150:151], v[150:151], v[208:209]
	v_pk_add_f32 v[150:151], v[150:151], v[210:211]
	v_cvt_pk_bf16_f32 v206, v208, v209
	v_cvt_pk_bf16_f32 v207, v210, v211
	s_waitcnt lgkmcnt(5)
	v_mfma_f32_32x32x16_bf16 v[84:99], v[132:135], v[120:123], v[84:99]
	v_exp_f32_e32 v212, v212
	v_exp_f32_e32 v213, v213
	s_waitcnt lgkmcnt(4)
	v_mfma_f32_32x32x16_bf16 v[100:115], v[136:139], v[120:123], v[100:115]
	v_exp_f32_e32 v214, v214
	v_exp_f32_e32 v215, v215
	s_waitcnt lgkmcnt(3)
	v_mfma_f32_32x32x16_bf16 v[84:99], v[140:143], v[124:127], v[84:99]
	v_pk_add_f32 v[150:151], v[150:151], v[212:213]
	v_pk_add_f32 v[150:151], v[150:151], v[214:215]
	v_exp_f32_e32 v216, v216
	s_waitcnt lgkmcnt(2)
	v_mfma_f32_32x32x16_bf16 v[100:115], v[144:147], v[124:127], v[100:115]
	v_exp_f32_e32 v217, v217
	v_cvt_pk_bf16_f32 v208, v212, v213
	v_cvt_pk_bf16_f32 v209, v214, v215
	s_waitcnt lgkmcnt(1)
	v_mfma_f32_32x32x16_bf16 v[84:99], v[220:223], v[128:131], v[84:99]
	v_exp_f32_e32 v218, v218
	v_exp_f32_e32 v219, v219
	s_waitcnt lgkmcnt(0)
	v_mfma_f32_32x32x16_bf16 v[100:115], v[224:227], v[128:131], v[100:115]
	v_pk_add_f32 v[150:151], v[150:151], v[216:217]
	v_pk_add_f32 v[150:151], v[150:151], v[218:219]
	v_cvt_pk_bf16_f32 v210, v216, v217
	v_cvt_pk_bf16_f32 v211, v218, v219
	s_mov_b32 s30, s10
	s_mov_b32 s10, s35
	s_mov_b32 s35, s31
	s_mov_b32 s31, s30
	s_add_u32 s8, s8, 0x40000
	s_addc_u32 s9, s9, 0
	s_add_i32 s36, s36, 64
	s_mov_b32 s24, s29
	s_waitcnt vmcnt(4) lgkmcnt(0)
	s_barrier
	s_add_i32 s23, s23, -1
	s_cmp_lg_u32 s23, 0
	s_cbranch_scc1 .LatB_loop
	s_cmp_eq_u32 s24, 0
	s_cbranch_scc1 .LatB_near_x4

; #define LAS __attribute__((address_space(3)))
; __device__ __forceinline__ float max2f(float a, float b) { float r; asm("v_max_f32_e32 %0, %1, %2" : "=v"(r) : "v"(a), "v"(b)); return r; }
; #define VREADS1(arr, d_) do { const unsigned ad_ = vbase ^ (unsigned)((d_) << 6); __builtin_amdgcn_sched_barrier(0); \
;         _Pragma("unroll") for (int ks_ = 0; ks_ < 4; ++ks_) { VTR(arr[ks_ * 2], ad_, ks_ * 4096); VTR(arr[ks_ * 2 + 1], ad_, ks_ * 4096 + 2048); } __builtin_amdgcn_sched_barrier(0); } while (0)
; __device__ __forceinline__ void attn_unit(LAS unsigned char* lds, const bf16_t* Z, bf16_t* A2, const float* tabg, int seq_base, int S, int h, int qb, float lam) {
;     ...
;         const unsigned vbase = (unsigned)(size_t)Vt + vfo;
;         s16x4 va[8], vb[8];
;         VREADS1(va, 0);
;         if (near) {
;             const LAS float* tp = tab + (kv0 + 4 * hi - (qlo + r32) + 224);
; #pragma unroll
;             for (int r = 0; r < 16; ++r) { p0[r] += tp[(r & 3) + 8 * (r >> 2)]; p1[r] += tp[32 + (r & 3) + 8 * (r >> 2)]; }
;         }
;         float mx = max2f(max16f(p0), max16f(p1));
;         const bool first = (t == 0);
;         if (first || __any(mx > THR)) {
.LatB_nearret_x3:
	v_add_u32_e32 v232, s35, v19
	v_add_u32_e32 v233, s35, v180
	v_add_u32_e32 v234, s35, v181
	v_add_u32_e32 v235, s35, v182
	v_add_u32_e32 v236, s31, v228
	v_add_u32_e32 v237, s31, v229
	v_add_u32_e32 v238, s31, v230
	v_add_u32_e32 v239, s31, v231
	ds_read_b64_tr_b16 v[132:133], v236 offset:0
	ds_read_b64_tr_b16 v[134:135], v236 offset:2048
	ds_read_b64_tr_b16 v[136:137], v237 offset:0
	ds_read_b64_tr_b16 v[138:139], v237 offset:2048
	ds_read_b64_tr_b16 v[140:141], v238 offset:0
	ds_read_b64_tr_b16 v[142:143], v238 offset:2048
	ds_read_b64_tr_b16 v[144:145], v239 offset:0
	ds_read_b64_tr_b16 v[146:147], v239 offset:2048
	ds_read_b64_tr_b16 v[220:221], v236 offset:4096
	ds_read_b64_tr_b16 v[222:223], v236 offset:6144
	ds_read_b64_tr_b16 v[224:225], v237 offset:4096
	ds_read_b64_tr_b16 v[226:227], v237 offset:6144
	v_max3_f32 v251, v188, v189, v190
	v_max3_f32 v252, v191, v192, v193
	v_max3_f32 v251, v251, v194, v195
	v_max3_f32 v252, v252, v196, v197
	v_max3_f32 v251, v251, v198, v199
	v_max3_f32 v252, v252, v200, v201
	v_max3_f32 v251, v251, v202, v203
	v_max3_f32 v252, v252, v204, v205
	v_max3_f32 v251, v251, v206, v207
	v_max3_f32 v252, v252, v208, v209
	v_max3_f32 v251, v251, v210, v211
	v_max3_f32 v252, v252, v212, v213
	v_max3_f32 v251, v251, v214, v215
	v_max3_f32 v252, v252, v216, v217
	v_max3_f32 v251, v251, v218, v219
	v_max_f32_e32 v251, v251, v252
	s_nop 0
	v_cmp_lt_f32_e32 vcc, 0x41000000, v251
	s_cbranch_vccnz .LatB_rare_x3

; #define LAS __attribute__((address_space(3)))
; __device__ __forceinline__ void attn_unit(LAS unsigned char* lds, const bf16_t* Z, bf16_t* A2, const float* tabg, int seq_base, int S, int h, int qb, float lam) {
;     ...
;             for (int ds = 0; ds < 4; ++ds) { kf[2 * ds] = *(const LAS bf16x8*)(Kt + (kfo ^ (unsigned)(ds << 5))); kf[2 * ds + 1] = *(const LAS bf16x8*)(Kt + 32 * 256 + (kfo ^ (unsigned)(ds << 5))); }
;             __builtin_amdgcn_sched_barrier(0);
;             p0 = __builtin_amdgcn_mfma_f32_32x32x16_bf16(kf[0], qf[0], cblk, 0, 0, 0);
;             p1 = __builtin_amdgcn_mfma_f32_32x32x16_bf16(kf[1], qf[0], cblk, 0, 0, 0);
; #pragma unroll
;             for (int ds = 1; ds < 4; ++ds) {
;                 p0 = __builtin_amdgcn_mfma_f32_32x32x16_bf16(kf[2 * ds], qf[ds], p0, 0, 0, 0);
;                 p1 = __builtin_amdgcn_mfma_f32_32x32x16_bf16(kf[2 * ds + 1], qf[ds], p1, 0, 0, 0);
;             }
;         }
;     ...
;         const unsigned vbase = (unsigned)(size_t)Vt + vfo;
;         s16x4 va[8], vb[8];
;         VREADS1(va, 0);
;         if (near) {
;             const LAS float* tp = tab + (kv0 + 4 * hi - (qlo + r32) + 224);
; #pragma unroll
;             for (int r = 0; r < 16; ++r) { p0[r] += tp[(r & 3) + 8 * (r >> 2)]; p1[r] += tp[32 + (r & 3) + 8 * (r >> 2)]; }
;         }
;         float mx = max2f(max16f(p0), max16f(p1));
;         const bool first = (t == 0);
;         if (first || __any(mx > THR)) {
;             { auto rr = __builtin_amdgcn_permlane32_swap(__float_as_uint(mx), __float_as_uint(mx), false, false); mx = max2f(__uint_as_float(rr[0]), __uint_as_float(rr[1])); }
;             const float delta = first ? mx : fmaxf(mx, 0.f);
;             const float alpha = first ? 1.0f : __builtin_amdgcn_exp2f(-delta);
;             mu += delta; ls2 *= alpha;
;             if (!first) {
;                 asm volatile("" ::: "memory");
;                 scr[r32] = alpha;
;                 asm volatile("s_waitcnt lgkmcnt(0)" ::: "memory");
; #pragma unroll
;                 for (int g = 0; g < 4; ++g) { const f32x4 a4 = *(const LAS f32x4*)(scr + 8 * g + 4 * hi);
; #pragma unroll
;                     for (int d = 0; d < 4; ++d) { O[d][4 * g + 0] *= a4[0]; O[d][4 * g + 1] *= a4[1]; O[d][4 * g + 2] *= a4[2]; O[d][4 * g + 3] *= a4[3]; } }
;                 asm volatile("s_waitcnt lgkmcnt(0)" ::: "memory");
;             }
; #pragma unroll
.LatB_rebuildret_x3:
	s_waitcnt lgkmcnt(10)
	v_mfma_f32_32x32x16_bf16 v[20:35], v[84:87], v[132:135], v[20:35]
	ds_read_b64_tr_b16 v[132:133], v238 offset:4096
	ds_read_b64_tr_b16 v[134:135], v238 offset:6144
	v_exp_f32_e32 v188, v188
	v_exp_f32_e32 v189, v189
	s_waitcnt lgkmcnt(10)
	v_mfma_f32_32x32x16_bf16 v[36:51], v[84:87], v[136:139], v[36:51]
	ds_read_b64_tr_b16 v[136:137], v239 offset:4096
	ds_read_b64_tr_b16 v[138:139], v239 offset:6144
	v_exp_f32_e32 v190, v190
	v_exp_f32_e32 v191, v191
	s_waitcnt lgkmcnt(10)
	v_mfma_f32_32x32x16_bf16 v[52:67], v[84:87], v[140:143], v[52:67]
	ds_read_b64_tr_b16 v[140:141], v236 offset:8192
	ds_read_b64_tr_b16 v[142:143], v236 offset:10240
	v_pk_add_f32 v[150:151], v[150:151], v[188:189]
	v_pk_add_f32 v[150:151], v[150:151], v[190:191]
	v_exp_f32_e32 v192, v192
	s_waitcnt lgkmcnt(10)
	v_mfma_f32_32x32x16_bf16 v[68:83], v[84:87], v[144:147], v[68:83]
	ds_read_b64_tr_b16 v[144:145], v237 offset:8192
	ds_read_b64_tr_b16 v[146:147], v237 offset:10240
	v_exp_f32_e32 v193, v193
	v_cvt_pk_bf16_f32 v188, v188, v189
	v_cvt_pk_bf16_f32 v189, v190, v191
	s_waitcnt lgkmcnt(10)
	v_mfma_f32_32x32x16_bf16 v[20:35], v[88:91], v[220:223], v[20:35]
	ds_read_b64_tr_b16 v[220:221], v238 offset:8192
	ds_read_b64_tr_b16 v[222:223], v238 offset:10240
	v_exp_f32_e32 v194, v194
	v_exp_f32_e32 v195, v195
	s_waitcnt lgkmcnt(10)
	v_mfma_f32_32x32x16_bf16 v[36:51], v[88:91], v[224:227], v[36:51]
	ds_read_b64_tr_b16 v[224:225], v239 offset:8192
	ds_read_b64_tr_b16 v[226:227], v239 offset:10240
	v_pk_add_f32 v[150:151], v[150:151], v[192:193]
	v_pk_add_f32 v[150:151], v[150:151], v[194:195]
	v_cvt_pk_bf16_f32 v190, v192, v193
	v_cvt_pk_bf16_f32 v191, v194, v195
	s_waitcnt lgkmcnt(10)
	v_mfma_f32_32x32x16_bf16 v[52:67], v[88:91], v[132:135], v[52:67]
	ds_read_b64_tr_b16 v[132:133], v236 offset:12288
	ds_read_b64_tr_b16 v[134:135], v236 offset:14336
	v_exp_f32_e32 v196, v196
	v_exp_f32_e32 v197, v197
	s_waitcnt lgkmcnt(10)
	v_mfma_f32_32x32x16_bf16 v[68:83], v[88:91], v[136:139], v[68:83]
	ds_read_b64_tr_b16 v[136:137], v237 offset:12288
	ds_read_b64_tr_b16 v[138:139], v237 offset:14336
	s_add_u32 m0, s27, s35
	s_nop 0
	global_load_lds_dwordx4 v149, s[8:9]
	v_exp_f32_e32 v198, v198
	v_exp_f32_e32 v199, v199
	s_waitcnt lgkmcnt(10)
	v_mfma_f32_32x32x16_bf16 v[20:35], v[100:103], v[140:143], v[20:35]
	ds_read_b64_tr_b16 v[140:141], v238 offset:12288
	ds_read_b64_tr_b16 v[142:143], v238 offset:14336
	v_pk_add_f32 v[150:151], v[150:151], v[196:197]
	v_pk_add_f32 v[150:151], v[150:151], v[198:199]
	v_exp_f32_e32 v200, v200
	s_waitcnt lgkmcnt(10)
	v_mfma_f32_32x32x16_bf16 v[36:51], v[100:103], v[144:147], v[36:51]
	ds_read_b64_tr_b16 v[144:145], v239 offset:12288
	ds_read_b64_tr_b16 v[146:147], v239 offset:14336
	v_exp_f32_e32 v201, v201
	v_cvt_pk_bf16_f32 v192, v196, v197
	v_cvt_pk_bf16_f32 v193, v198, v199
	s_waitcnt lgkmcnt(10)
	v_mfma_f32_32x32x16_bf16 v[52:67], v[100:103], v[220:223], v[52:67]
	ds_read_b128 v[220:223], v232
	v_exp_f32_e32 v202, v202
	v_exp_f32_e32 v203, v203
	s_waitcnt lgkmcnt(9)
	v_mfma_f32_32x32x16_bf16 v[68:83], v[100:103], v[224:227], v[68:83]
	ds_read_b128 v[224:227], v232 offset:8192
	v_pk_add_f32 v[150:151], v[150:151], v[200:201]
	v_pk_add_f32 v[150:151], v[150:151], v[202:203]
	v_cvt_pk_bf16_f32 v194, v200, v201
	v_cvt_pk_bf16_f32 v195, v202, v203
	s_waitcnt lgkmcnt(8)
	v_mfma_f32_32x32x16_bf16 v[20:35], v[104:107], v[132:135], v[20:35]
	ds_read_b128 v[132:135], v233
	v_exp_f32_e32 v204, v204
	v_exp_f32_e32 v205, v205
	s_waitcnt lgkmcnt(7)
	v_mfma_f32_32x32x16_bf16 v[36:51], v[104:107], v[136:139], v[36:51]
	ds_read_b128 v[136:139], v233 offset:8192
	v_exp_f32_e32 v206, v206
	v_exp_f32_e32 v207, v207
	s_waitcnt lgkmcnt(6)
	v_mfma_f32_32x32x16_bf16 v[52:67], v[104:107], v[140:143], v[52:67]
	ds_read_b128 v[140:143], v234
	v_pk_add_f32 v[150:151], v[150:151], v[204:205]
	v_pk_add_f32 v[150:151], v[150:151], v[206:207]
	v_exp_f32_e32 v208, v208
	s_waitcnt lgkmcnt(5)
	v_mfma_f32_32x32x16_bf16 v[68:83], v[104:107], v[144:147], v[68:83]
	ds_read_b128 v[144:147], v234 offset:8192
	s_add_u32 m0, s27, s35
	s_add_u32 m0, m0, 0x2000
	s_nop 0
	global_load_lds_dwordx4 v176, s[8:9]
	v_exp_f32_e32 v209, v209
	v_cvt_pk_bf16_f32 v204, v204, v205
	v_cvt_pk_bf16_f32 v205, v206, v207
	s_waitcnt lgkmcnt(5)
	v_mfma_f32_32x32x16_bf16 v[84:99], v[220:223], v[116:119], v[2:17]
	ds_read_b128 v[220:223], v235
	v_exp_f32_e32 v210, v210
	v_exp_f32_e32 v211, v211
	s_waitcnt lgkmcnt(5)
	v_mfma_f32_32x32x16_bf16 v[100:115], v[224:227], v[116:119], v[2:17]
	ds_read_b128 v[224:227], v235 offset:8192
	v_pk_add_f32 v[150:151], v[150:151], v[208:209]
	v_pk_add_f32 v[150:151], v[150:151], v[210:211]
	v_cvt_pk_bf16_f32 v206, v208, v209
	v_cvt_pk_bf16_f32 v207, v210, v211
	s_waitcnt lgkmcnt(5)
	v_mfma_f32_32x32x16_bf16 v[84:99], v[132:135], v[120:123], v[84:99]
	v_exp_f32_e32 v212, v212
	v_exp_f32_e32 v213, v213
	s_waitcnt lgkmcnt(4)
	v_mfma_f32_32x32x16_bf16 v[100:115], v[136:139], v[120:123], v[100:115]
	v_exp_f32_e32 v214, v214
	v_exp_f32_e32 v215, v215
	s_waitcnt lgkmcnt(3)
	v_mfma_f32_32x32x16_bf16 v[84:99], v[140:143], v[124:127], v[84:99]
	v_pk_add_f32 v[150:151], v[150:151], v[212:213]
	v_pk_add_f32 v[150:151], v[150:151], v[214:215]
	v_exp_f32_e32 v216, v216
	s_waitcnt lgkmcnt(2)
	v_mfma_f32_32x32x16_bf16 v[100:115], v[144:147], v[124:127], v[100:115]
	v_exp_f32_e32 v217, v217
	v_cvt_pk_bf16_f32 v208, v212, v213
	v_cvt_pk_bf16_f32 v209, v214, v215
	s_waitcnt lgkmcnt(1)
	v_mfma_f32_32x32x16_bf16 v[84:99], v[220:223], v[128:131], v[84:99]
	v_exp_f32_e32 v218, v218
	v_exp_f32_e32 v219, v219
	s_waitcnt lgkmcnt(0)
	v_mfma_f32_32x32x16_bf16 v[100:115], v[224:227], v[128:131], v[100:115]
	v_pk_add_f32 v[150:151], v[150:151], v[216:217]
	v_pk_add_f32 v[150:151], v[150:151], v[218:219]
	v_cvt_pk_bf16_f32 v210, v216, v217
	v_cvt_pk_bf16_f32 v211, v218, v219
	s_mov_b32 s30, s10
	s_mov_b32 s10, s35
	s_mov_b32 s35, s31
	s_mov_b32 s31, s30
	s_add_u32 s8, s8, 0x40000
	s_addc_u32 s9, s9, 0
	s_add_i32 s36, s36, 64
	s_mov_b32 s24, s29
	s_waitcnt vmcnt(2) lgkmcnt(0)
	s_barrier
	s_cmp_eq_u32 s24, 0
	s_cbranch_scc1 .LatB_near_x2
; #define LAS __attribute__((address_space(3)))
; __device__ __forceinline__ float max2f(float a, float b) { float r; asm("v_max_f32_e32 %0, %1, %2" : "=v"(r) : "v"(a), "v"(b)); return r; }
; #define VREADS1(arr, d_) do { const unsigned ad_ = vbase ^ (unsigned)((d_) << 6); __builtin_amdgcn_sched_barrier(0); \
;         _Pragma("unroll") for (int ks_ = 0; ks_ < 4; ++ks_) { VTR(arr[ks_ * 2], ad_, ks_ * 4096); VTR(arr[ks_ * 2 + 1], ad_, ks_ * 4096 + 2048); } __builtin_amdgcn_sched_barrier(0); } while (0)
; __device__ __forceinline__ void attn_unit(LAS unsigned char* lds, const bf16_t* Z, bf16_t* A2, const float* tabg, int seq_base, int S, int h, int qb, float lam) {
;     ...
;         const unsigned vbase = (unsigned)(size_t)Vt + vfo;
;         s16x4 va[8], vb[8];
;         VREADS1(va, 0);
;         if (near) {
;             const LAS float* tp = tab + (kv0 + 4 * hi - (qlo + r32) + 224);
; #pragma unroll
;             for (int r = 0; r < 16; ++r) { p0[r] += tp[(r & 3) + 8 * (r >> 2)]; p1[r] += tp[32 + (r & 3) + 8 * (r >> 2)]; }
;         }
;         float mx = max2f(max16f(p0), max16f(p1));
;         const bool first = (t == 0);
;         if (first || __any(mx > THR)) {
.LatB_nearret_x2:
	v_add_u32_e32 v232, s35, v19
	v_add_u32_e32 v233, s35, v180
	v_add_u32_e32 v234, s35, v181
	v_add_u32_e32 v235, s35, v182
	v_add_u32_e32 v236, s31, v228
	v_add_u32_e32 v237, s31, v229
	v_add_u32_e32 v238, s31, v230
	v_add_u32_e32 v239, s31, v231
	ds_read_b64_tr_b16 v[132:133], v236 offset:0
	ds_read_b64_tr_b16 v[134:135], v236 offset:2048
	ds_read_b64_tr_b16 v[136:137], v237 offset:0
	ds_read_b64_tr_b16 v[138:139], v237 offset:2048
	ds_read_b64_tr_b16 v[140:141], v238 offset:0
	ds_read_b64_tr_b16 v[142:143], v238 offset:2048
	ds_read_b64_tr_b16 v[144:145], v239 offset:0
	ds_read_b64_tr_b16 v[146:147], v239 offset:2048
	ds_read_b64_tr_b16 v[220:221], v236 offset:4096
	ds_read_b64_tr_b16 v[222:223], v236 offset:6144
	ds_read_b64_tr_b16 v[224:225], v237 offset:4096
	ds_read_b64_tr_b16 v[226:227], v237 offset:6144
	v_max3_f32 v251, v84, v85, v86
	v_max3_f32 v252, v87, v88, v89
	v_max3_f32 v251, v251, v90, v91
	v_max3_f32 v252, v252, v92, v93
	v_max3_f32 v251, v251, v94, v95
	v_max3_f32 v252, v252, v96, v97
	v_max3_f32 v251, v251, v98, v99
	v_max3_f32 v252, v252, v100, v101
	v_max3_f32 v251, v251, v102, v103
	v_max3_f32 v252, v252, v104, v105
	v_max3_f32 v251, v251, v106, v107
	v_max3_f32 v252, v252, v108, v109
	v_max3_f32 v251, v251, v110, v111
	v_max3_f32 v252, v252, v112, v113
	v_max3_f32 v251, v251, v114, v115
	v_max_f32_e32 v251, v251, v252
	s_nop 0
	v_cmp_lt_f32_e32 vcc, 0x41000000, v251
	s_cbranch_vccnz .LatB_rare_x2

; #define LAS __attribute__((address_space(3)))
; __device__ __forceinline__ void attn_unit(LAS unsigned char* lds, const bf16_t* Z, bf16_t* A2, const float* tabg, int seq_base, int S, int h, int qb, float lam) {
;     ...
;             for (int ds = 0; ds < 4; ++ds) { kf[2 * ds] = *(const LAS bf16x8*)(Kt + (kfo ^ (unsigned)(ds << 5))); kf[2 * ds + 1] = *(const LAS bf16x8*)(Kt + 32 * 256 + (kfo ^ (unsigned)(ds << 5))); }
;             __builtin_amdgcn_sched_barrier(0);
;             p0 = __builtin_amdgcn_mfma_f32_32x32x16_bf16(kf[0], qf[0], cblk, 0, 0, 0);
;             p1 = __builtin_amdgcn_mfma_f32_32x32x16_bf16(kf[1], qf[0], cblk, 0, 0, 0);
; #pragma unroll
;             for (int ds = 1; ds < 4; ++ds) {
;                 p0 = __builtin_amdgcn_mfma_f32_32x32x16_bf16(kf[2 * ds], qf[ds], p0, 0, 0, 0);
;                 p1 = __builtin_amdgcn_mfma_f32_32x32x16_bf16(kf[2 * ds + 1], qf[ds], p1, 0, 0, 0);
;             }
;         }
;     ...
;         const unsigned vbase = (unsigned)(size_t)Vt + vfo;
;         s16x4 va[8], vb[8];
;         VREADS1(va, 0);
;         if (near) {
;             const LAS float* tp = tab + (kv0 + 4 * hi - (qlo + r32) + 224);
; #pragma unroll
;             for (int r = 0; r < 16; ++r) { p0[r] += tp[(r & 3) + 8 * (r >> 2)]; p1[r] += tp[32 + (r & 3) + 8 * (r >> 2)]; }
;         }
;         float mx = max2f(max16f(p0), max16f(p1));
;         const bool first = (t == 0);
;         if (first || __any(mx > THR)) {
;             { auto rr = __builtin_amdgcn_permlane32_swap(__float_as_uint(mx), __float_as_uint(mx), false, false); mx = max2f(__uint_as_float(rr[0]), __uint_as_float(rr[1])); }
;             const float delta = first ? mx : fmaxf(mx, 0.f);
;             const float alpha = first ? 1.0f : __builtin_amdgcn_exp2f(-delta);
;             mu += delta; ls2 *= alpha;
;             if (!first) {
;                 asm volatile("" ::: "memory");
;                 scr[r32] = alpha;
;                 asm volatile("s_waitcnt lgkmcnt(0)" ::: "memory");
; #pragma unroll
;                 for (int g = 0; g < 4; ++g) { const f32x4 a4 = *(const LAS f32x4*)(scr + 8 * g + 4 * hi);
; #pragma unroll
;                     for (int d = 0; d < 4; ++d) { O[d][4 * g + 0] *= a4[0]; O[d][4 * g + 1] *= a4[1]; O[d][4 * g + 2] *= a4[2]; O[d][4 * g + 3] *= a4[3]; } }
;                 asm volatile("s_waitcnt lgkmcnt(0)" ::: "memory");
;             }
; #pragma unroll
.LatB_rebuildret_x2:
	s_waitcnt lgkmcnt(10)
	v_mfma_f32_32x32x16_bf16 v[20:35], v[188:191], v[132:135], v[20:35]
	ds_read_b64_tr_b16 v[132:133], v238 offset:4096
	ds_read_b64_tr_b16 v[134:135], v238 offset:6144
	v_exp_f32_e32 v84, v84
	v_exp_f32_e32 v85, v85
	s_waitcnt lgkmcnt(10)
	v_mfma_f32_32x32x16_bf16 v[36:51], v[188:191], v[136:139], v[36:51]
	ds_read_b64_tr_b16 v[136:137], v239 offset:4096
	ds_read_b64_tr_b16 v[138:139], v239 offset:6144
	v_exp_f32_e32 v86, v86
	v_exp_f32_e32 v87, v87
	s_waitcnt lgkmcnt(10)
	v_mfma_f32_32x32x16_bf16 v[52:67], v[188:191], v[140:143], v[52:67]
	ds_read_b64_tr_b16 v[140:141], v236 offset:8192
	ds_read_b64_tr_b16 v[142:143], v236 offset:10240
	v_pk_add_f32 v[150:151], v[150:151], v[84:85]
	v_pk_add_f32 v[150:151], v[150:151], v[86:87]
	v_exp_f32_e32 v88, v88
	s_waitcnt lgkmcnt(10)
	v_mfma_f32_32x32x16_bf16 v[68:83], v[188:191], v[144:147], v[68:83]
	ds_read_b64_tr_b16 v[144:145], v237 offset:8192
	ds_read_b64_tr_b16 v[146:147], v237 offset:10240
	v_exp_f32_e32 v89, v89
	v_cvt_pk_bf16_f32 v84, v84, v85
	v_cvt_pk_bf16_f32 v85, v86, v87
	s_waitcnt lgkmcnt(10)
	v_mfma_f32_32x32x16_bf16 v[20:35], v[192:195], v[220:223], v[20:35]
	ds_read_b64_tr_b16 v[220:221], v238 offset:8192
	ds_read_b64_tr_b16 v[222:223], v238 offset:10240
	v_exp_f32_e32 v90, v90
	v_exp_f32_e32 v91, v91
	s_waitcnt lgkmcnt(10)
	v_mfma_f32_32x32x16_bf16 v[36:51], v[192:195], v[224:227], v[36:51]
	ds_read_b64_tr_b16 v[224:225], v239 offset:8192
	ds_read_b64_tr_b16 v[226:227], v239 offset:10240
	v_pk_add_f32 v[150:151], v[150:151], v[88:89]
	v_pk_add_f32 v[150:151], v[150:151], v[90:91]
	v_cvt_pk_bf16_f32 v86, v88, v89
	v_cvt_pk_bf16_f32 v87, v90, v91
	s_waitcnt lgkmcnt(10)
	v_mfma_f32_32x32x16_bf16 v[52:67], v[192:195], v[132:135], v[52:67]
	ds_read_b64_tr_b16 v[132:133], v236 offset:12288
	ds_read_b64_tr_b16 v[134:135], v236 offset:14336
	v_exp_f32_e32 v92, v92
	v_exp_f32_e32 v93, v93
	s_waitcnt lgkmcnt(10)
	v_mfma_f32_32x32x16_bf16 v[68:83], v[192:195], v[136:139], v[68:83]
	ds_read_b64_tr_b16 v[136:137], v237 offset:12288
	ds_read_b64_tr_b16 v[138:139], v237 offset:14336
	s_add_u32 m0, s27, s35
	s_nop 0
	global_load_lds_dwordx4 v149, s[8:9]
	v_exp_f32_e32 v94, v94
	v_exp_f32_e32 v95, v95
	s_waitcnt lgkmcnt(10)
	v_mfma_f32_32x32x16_bf16 v[20:35], v[204:207], v[140:143], v[20:35]
	ds_read_b64_tr_b16 v[140:141], v238 offset:12288
	ds_read_b64_tr_b16 v[142:143], v238 offset:14336
	v_pk_add_f32 v[150:151], v[150:151], v[92:93]
	v_pk_add_f32 v[150:151], v[150:151], v[94:95]
	v_exp_f32_e32 v96, v96
	s_waitcnt lgkmcnt(10)
	v_mfma_f32_32x32x16_bf16 v[36:51], v[204:207], v[144:147], v[36:51]
	ds_read_b64_tr_b16 v[144:145], v239 offset:12288
	ds_read_b64_tr_b16 v[146:147], v239 offset:14336
	v_exp_f32_e32 v97, v97
	v_cvt_pk_bf16_f32 v88, v92, v93
	v_cvt_pk_bf16_f32 v89, v94, v95
	s_waitcnt lgkmcnt(10)
	v_mfma_f32_32x32x16_bf16 v[52:67], v[204:207], v[220:223], v[52:67]
	ds_read_b128 v[220:223], v232
	v_exp_f32_e32 v98, v98
	v_exp_f32_e32 v99, v99
	s_waitcnt lgkmcnt(9)
	v_mfma_f32_32x32x16_bf16 v[68:83], v[204:207], v[224:227], v[68:83]
	ds_read_b128 v[224:227], v232 offset:8192
	v_pk_add_f32 v[150:151], v[150:151], v[96:97]
	v_pk_add_f32 v[150:151], v[150:151], v[98:99]
	v_cvt_pk_bf16_f32 v90, v96, v97
	v_cvt_pk_bf16_f32 v91, v98, v99
	s_waitcnt lgkmcnt(8)
	v_mfma_f32_32x32x16_bf16 v[20:35], v[208:211], v[132:135], v[20:35]
	ds_read_b128 v[132:135], v233
	v_exp_f32_e32 v100, v100
	v_exp_f32_e32 v101, v101
	s_waitcnt lgkmcnt(7)
	v_mfma_f32_32x32x16_bf16 v[36:51], v[208:211], v[136:139], v[36:51]
	ds_read_b128 v[136:139], v233 offset:8192
	v_exp_f32_e32 v102, v102
	v_exp_f32_e32 v103, v103
	s_waitcnt lgkmcnt(6)
	v_mfma_f32_32x32x16_bf16 v[52:67], v[208:211], v[140:143], v[52:67]
	ds_read_b128 v[140:143], v234
	v_pk_add_f32 v[150:151], v[150:151], v[100:101]
	v_pk_add_f32 v[150:151], v[150:151], v[102:103]
	v_exp_f32_e32 v104, v104
	s_waitcnt lgkmcnt(5)
	v_mfma_f32_32x32x16_bf16 v[68:83], v[208:211], v[144:147], v[68:83]
	ds_read_b128 v[144:147], v234 offset:8192
	s_add_u32 m0, s27, s35
	s_add_u32 m0, m0, 0x2000
	s_nop 0
	global_load_lds_dwordx4 v176, s[8:9]
	v_exp_f32_e32 v105, v105
	v_cvt_pk_bf16_f32 v100, v100, v101
	v_cvt_pk_bf16_f32 v101, v102, v103
	s_waitcnt lgkmcnt(5)
	v_mfma_f32_32x32x16_bf16 v[188:203], v[220:223], v[116:119], v[2:17]
	ds_read_b128 v[220:223], v235
	v_exp_f32_e32 v106, v106
	v_exp_f32_e32 v107, v107
	s_waitcnt lgkmcnt(5)
	v_mfma_f32_32x32x16_bf16 v[204:219], v[224:227], v[116:119], v[2:17]
	ds_read_b128 v[224:227], v235 offset:8192
	v_pk_add_f32 v[150:151], v[150:151], v[104:105]
	v_pk_add_f32 v[150:151], v[150:151], v[106:107]
	v_cvt_pk_bf16_f32 v102, v104, v105
	v_cvt_pk_bf16_f32 v103, v106, v107
	s_waitcnt lgkmcnt(5)
	v_mfma_f32_32x32x16_bf16 v[188:203], v[132:135], v[120:123], v[188:203]
	v_exp_f32_e32 v108, v108
	v_exp_f32_e32 v109, v109
	s_waitcnt lgkmcnt(4)
	v_mfma_f32_32x32x16_bf16 v[204:219], v[136:139], v[120:123], v[204:219]
	v_exp_f32_e32 v110, v110
	v_exp_f32_e32 v111, v111
	s_waitcnt lgkmcnt(3)
	v_mfma_f32_32x32x16_bf16 v[188:203], v[140:143], v[124:127], v[188:203]
	v_pk_add_f32 v[150:151], v[150:151], v[108:109]
	v_pk_add_f32 v[150:151], v[150:151], v[110:111]
	v_exp_f32_e32 v112, v112
	s_waitcnt lgkmcnt(2)
	v_mfma_f32_32x32x16_bf16 v[204:219], v[144:147], v[124:127], v[204:219]
	v_exp_f32_e32 v113, v113
	v_cvt_pk_bf16_f32 v104, v108, v109
	v_cvt_pk_bf16_f32 v105, v110, v111
	s_waitcnt lgkmcnt(1)
	v_mfma_f32_32x32x16_bf16 v[188:203], v[220:223], v[128:131], v[188:203]
	v_exp_f32_e32 v114, v114
	v_exp_f32_e32 v115, v115
	s_waitcnt lgkmcnt(0)
	v_mfma_f32_32x32x16_bf16 v[204:219], v[224:227], v[128:131], v[204:219]
	v_pk_add_f32 v[150:151], v[150:151], v[112:113]
	v_pk_add_f32 v[150:151], v[150:151], v[114:115]
	v_cvt_pk_bf16_f32 v106, v112, v113
	v_cvt_pk_bf16_f32 v107, v114, v115
	s_mov_b32 s30, s10
	s_mov_b32 s10, s35
	s_mov_b32 s35, s31
	s_mov_b32 s31, s30
	s_add_u32 s8, s8, 0x40000
	s_addc_u32 s9, s9, 0
	s_add_i32 s36, s36, 64
	s_mov_b32 s24, s29
	s_waitcnt vmcnt(2) lgkmcnt(0)
	s_barrier
	s_cmp_eq_u32 s24, 0
	s_cbranch_scc1 .LatB_near_x1

; #define VREADS1(arr, d_) do { const unsigned ad_ = vbase ^ (unsigned)((d_) << 6); __builtin_amdgcn_sched_barrier(0); \
;         _Pragma("unroll") for (int ks_ = 0; ks_ < 4; ++ks_) { VTR(arr[ks_ * 2], ad_, ks_ * 4096); VTR(arr[ks_ * 2 + 1], ad_, ks_ * 4096 + 2048); } __builtin_amdgcn_sched_barrier(0); } while (0)
; #define PV1(arr, d_) do { _Pragma("unroll") for (int ks_ = 0; ks_ < 4; ++ks_) { const s16x4 lo_ = arr[ks_ * 2], hh_ = arr[ks_ * 2 + 1]; \
;         const bf16x8 bv_ = (bf16x8){lo_[0], lo_[1], lo_[2], lo_[3], hh_[0], hh_[1], hh_[2], hh_[3]}; \
;         O[d_] = __builtin_amdgcn_mfma_f32_32x32x16_bf16(pa[ks_], bv_, O[d_], 0, 0, 0); } __builtin_amdgcn_sched_barrier(0); } while (0)
; #define LGKM0() do { __builtin_amdgcn_sched_barrier(0); asm volatile("s_waitcnt lgkmcnt(0)" ::: "memory"); __builtin_amdgcn_sched_barrier(0); } while (0)
; __device__ __forceinline__ void attn_unit(LAS unsigned char* lds, const bf16_t* Z, bf16_t* A2, const float* tabg, int seq_base, int S, int h, int qb, float lam) {
;     ...
; #pragma unroll
;         for (int r = 0; r < 16; ++r) { p0[r] = __builtin_amdgcn_exp2f(p0[r]); p1[r] = __builtin_amdgcn_exp2f(p1[r]); }
; #pragma unroll
;         for (int r = 0; r < 16; r += 2) { ls2 += (f32x2){p0[r], p0[r + 1]}; ls2 += (f32x2){p1[r], p1[r + 1]}; }
;         bf16x8 pa[4]; pa[0] = pack8(p0, 0); pa[1] = pack8(p0, 8); pa[2] = pack8(p1, 0); pa[3] = pack8(p1, 8);
;         LGKM0(); VREADS1(vb, 1); PV1(va, 0); LGKM0(); VREADS1(va, 2); PV1(vb, 1); LGKM0(); VREADS1(vb, 3); PV1(va, 2); LGKM0(); PV1(vb, 3);
;     ...
;         if (t + 2 < NT) asm volatile("s_waitcnt vmcnt(4) lgkmcnt(0)" ::: "memory"); else asm volatile("s_waitcnt vmcnt(0) lgkmcnt(0)" ::: "memory");
;         __builtin_amdgcn_s_barrier(); asm volatile("" ::: "memory");
;         bc = (bc == NST - 1) ? 0 : bc + 1; bn = (bn == NST - 1) ? 0 : bn + 1;
.LatB_rareret_x1:
	s_waitcnt lgkmcnt(10)
	v_mfma_f32_32x32x16_bf16 v[20:35], v[84:87], v[132:135], v[20:35]
	ds_read_b64_tr_b16 v[132:133], v238 offset:4096
	ds_read_b64_tr_b16 v[134:135], v238 offset:6144
	v_exp_f32_e32 v188, v188
	v_exp_f32_e32 v189, v189
	v_exp_f32_e32 v190, v190
	s_waitcnt lgkmcnt(10)
	v_mfma_f32_32x32x16_bf16 v[36:51], v[84:87], v[136:139], v[36:51]
	ds_read_b64_tr_b16 v[136:137], v239 offset:4096
	ds_read_b64_tr_b16 v[138:139], v239 offset:6144
	v_exp_f32_e32 v191, v191
	v_pk_add_f32 v[150:151], v[150:151], v[188:189]
	v_pk_add_f32 v[150:151], v[150:151], v[190:191]
	v_exp_f32_e32 v192, v192
	s_waitcnt lgkmcnt(10)
	v_mfma_f32_32x32x16_bf16 v[52:67], v[84:87], v[140:143], v[52:67]
	ds_read_b64_tr_b16 v[140:141], v236 offset:8192
	ds_read_b64_tr_b16 v[142:143], v236 offset:10240
	v_exp_f32_e32 v193, v193
	v_cvt_pk_bf16_f32 v188, v188, v189
	v_cvt_pk_bf16_f32 v189, v190, v191
	v_exp_f32_e32 v194, v194
	s_waitcnt lgkmcnt(10)
	v_mfma_f32_32x32x16_bf16 v[68:83], v[84:87], v[144:147], v[68:83]
	ds_read_b64_tr_b16 v[144:145], v237 offset:8192
	ds_read_b64_tr_b16 v[146:147], v237 offset:10240
	v_exp_f32_e32 v195, v195
	v_pk_add_f32 v[150:151], v[150:151], v[192:193]
	v_pk_add_f32 v[150:151], v[150:151], v[194:195]
	v_cvt_pk_bf16_f32 v190, v192, v193
	v_cvt_pk_bf16_f32 v191, v194, v195
	s_waitcnt lgkmcnt(10)
	v_mfma_f32_32x32x16_bf16 v[20:35], v[88:91], v[220:223], v[20:35]
	ds_read_b64_tr_b16 v[220:221], v238 offset:8192
	ds_read_b64_tr_b16 v[222:223], v238 offset:10240
	v_exp_f32_e32 v196, v196
	v_exp_f32_e32 v197, v197
	v_exp_f32_e32 v198, v198
	s_waitcnt lgkmcnt(10)
	v_mfma_f32_32x32x16_bf16 v[36:51], v[88:91], v[224:227], v[36:51]
	ds_read_b64_tr_b16 v[224:225], v239 offset:8192
	ds_read_b64_tr_b16 v[226:227], v239 offset:10240
	v_exp_f32_e32 v199, v199
	v_pk_add_f32 v[150:151], v[150:151], v[196:197]
	v_pk_add_f32 v[150:151], v[150:151], v[198:199]
	v_exp_f32_e32 v200, v200
	s_waitcnt lgkmcnt(10)
	v_mfma_f32_32x32x16_bf16 v[52:67], v[88:91], v[132:135], v[52:67]
	ds_read_b64_tr_b16 v[132:133], v236 offset:12288
	ds_read_b64_tr_b16 v[134:135], v236 offset:14336
	v_exp_f32_e32 v201, v201
	v_cvt_pk_bf16_f32 v192, v196, v197
	v_cvt_pk_bf16_f32 v193, v198, v199
	v_exp_f32_e32 v202, v202
	s_waitcnt lgkmcnt(10)
	v_mfma_f32_32x32x16_bf16 v[68:83], v[88:91], v[136:139], v[68:83]
	ds_read_b64_tr_b16 v[136:137], v237 offset:12288
	ds_read_b64_tr_b16 v[138:139], v237 offset:14336
	v_exp_f32_e32 v203, v203
	v_pk_add_f32 v[150:151], v[150:151], v[200:201]
	v_pk_add_f32 v[150:151], v[150:151], v[202:203]
	v_cvt_pk_bf16_f32 v194, v200, v201
	v_cvt_pk_bf16_f32 v195, v202, v203
	s_waitcnt lgkmcnt(10)
	v_mfma_f32_32x32x16_bf16 v[20:35], v[100:103], v[140:143], v[20:35]
	ds_read_b64_tr_b16 v[140:141], v238 offset:12288
	ds_read_b64_tr_b16 v[142:143], v238 offset:14336
	v_exp_f32_e32 v204, v204
	v_exp_f32_e32 v205, v205
	v_exp_f32_e32 v206, v206
	s_waitcnt lgkmcnt(10)
	v_mfma_f32_32x32x16_bf16 v[36:51], v[100:103], v[144:147], v[36:51]
	ds_read_b64_tr_b16 v[144:145], v239 offset:12288
	ds_read_b64_tr_b16 v[146:147], v239 offset:14336
	v_exp_f32_e32 v207, v207
	v_pk_add_f32 v[150:151], v[150:151], v[204:205]
	v_pk_add_f32 v[150:151], v[150:151], v[206:207]
	v_exp_f32_e32 v208, v208
	s_waitcnt lgkmcnt(10)
	v_mfma_f32_32x32x16_bf16 v[52:67], v[100:103], v[220:223], v[52:67]
	v_exp_f32_e32 v209, v209
	v_cvt_pk_bf16_f32 v204, v204, v205
	v_cvt_pk_bf16_f32 v205, v206, v207
	v_exp_f32_e32 v210, v210
	s_waitcnt lgkmcnt(8)
	v_mfma_f32_32x32x16_bf16 v[68:83], v[100:103], v[224:227], v[68:83]
	v_exp_f32_e32 v211, v211
	v_pk_add_f32 v[150:151], v[150:151], v[208:209]
	v_pk_add_f32 v[150:151], v[150:151], v[210:211]
	v_cvt_pk_bf16_f32 v206, v208, v209
	v_cvt_pk_bf16_f32 v207, v210, v211
	s_waitcnt lgkmcnt(6)
	v_mfma_f32_32x32x16_bf16 v[20:35], v[104:107], v[132:135], v[20:35]
	v_exp_f32_e32 v212, v212
	v_exp_f32_e32 v213, v213
	v_exp_f32_e32 v214, v214
	s_waitcnt lgkmcnt(4)
	v_mfma_f32_32x32x16_bf16 v[36:51], v[104:107], v[136:139], v[36:51]
	v_exp_f32_e32 v215, v215
	v_pk_add_f32 v[150:151], v[150:151], v[212:213]
	v_pk_add_f32 v[150:151], v[150:151], v[214:215]
	v_exp_f32_e32 v216, v216
	s_waitcnt lgkmcnt(2)
	v_mfma_f32_32x32x16_bf16 v[52:67], v[104:107], v[140:143], v[52:67]
	v_exp_f32_e32 v217, v217
	v_cvt_pk_bf16_f32 v208, v212, v213
	v_cvt_pk_bf16_f32 v209, v214, v215
	v_exp_f32_e32 v218, v218
	s_waitcnt lgkmcnt(0)
	v_mfma_f32_32x32x16_bf16 v[68:83], v[104:107], v[144:147], v[68:83]
	v_exp_f32_e32 v219, v219
	v_pk_add_f32 v[150:151], v[150:151], v[216:217]
	v_pk_add_f32 v[150:151], v[150:151], v[218:219]
	v_cvt_pk_bf16_f32 v210, v216, v217
	v_cvt_pk_bf16_f32 v211, v218, v219
	s_mov_b32 s30, s10
	s_mov_b32 s10, s35
	s_mov_b32 s35, s31
	s_mov_b32 s31, s30
	s_add_u32 s8, s8, 0x40000
	s_addc_u32 s9, s9, 0
	s_add_i32 s36, s36, 64
	s_mov_b32 s24, s29
	s_waitcnt vmcnt(0) lgkmcnt(0)
	s_barrier
; #define VREADS1(arr, d_) do { const unsigned ad_ = vbase ^ (unsigned)((d_) << 6); __builtin_amdgcn_sched_barrier(0); \
;         _Pragma("unroll") for (int ks_ = 0; ks_ < 4; ++ks_) { VTR(arr[ks_ * 2], ad_, ks_ * 4096); VTR(arr[ks_ * 2 + 1], ad_, ks_ * 4096 + 2048); } __builtin_amdgcn_sched_barrier(0); } while (0)
; #define PV1(arr, d_) do { _Pragma("unroll") for (int ks_ = 0; ks_ < 4; ++ks_) { const s16x4 lo_ = arr[ks_ * 2], hh_ = arr[ks_ * 2 + 1]; \
;         const bf16x8 bv_ = (bf16x8){lo_[0], lo_[1], lo_[2], lo_[3], hh_[0], hh_[1], hh_[2], hh_[3]}; \
;         O[d_] = __builtin_amdgcn_mfma_f32_32x32x16_bf16(pa[ks_], bv_, O[d_], 0, 0, 0); } __builtin_amdgcn_sched_barrier(0); } while (0)
; #define LGKM0() do { __builtin_amdgcn_sched_barrier(0); asm volatile("s_waitcnt lgkmcnt(0)" ::: "memory"); __builtin_amdgcn_sched_barrier(0); } while (0)
; __device__ __forceinline__ void attn_unit(LAS unsigned char* lds, const bf16_t* Z, bf16_t* A2, const float* tabg, int seq_base, int S, int h, int qb, float lam) {
;     ...
;         if (kv0 - (qlo + 31) >= 128) { near = false; cc = tabR; } else if (qlo - (kv0 + 63) >= 128) { near = false; cc = tabL; }
;         { const float coff = cc - mu;
;           if (__any(!(coff == coff_cur))) { coff_cur = coff;
; #pragma unroll
;               for (int r = 0; r < 16; ++r) cblk[r] = coff;
;               asm volatile("" : "+v"(cblk)); } }
;     ...
;         LGKM0(); VREADS1(vb, 1); PV1(va, 0); LGKM0(); VREADS1(va, 2); PV1(vb, 1); LGKM0(); VREADS1(vb, 3); PV1(va, 2); LGKM0(); PV1(vb, 3);
;     ...
;         if (t + 2 < NT) asm volatile("s_waitcnt vmcnt(4) lgkmcnt(0)" ::: "memory"); else asm volatile("s_waitcnt vmcnt(0) lgkmcnt(0)" ::: "memory");
;         __builtin_amdgcn_s_barrier(); asm volatile("" ::: "memory");
;         bc = (bc == NST - 1) ? 0 : bc + 1; bn = (bn == NST - 1) ? 0 : bn + 1;
	v_add_u32_e32 v236, s31, v228
	v_add_u32_e32 v237, s31, v229
	v_add_u32_e32 v238, s31, v230
	v_add_u32_e32 v239, s31, v231
	ds_read_b64_tr_b16 v[132:133], v236 offset:0
	ds_read_b64_tr_b16 v[134:135], v236 offset:2048
	ds_read_b64_tr_b16 v[136:137], v237 offset:0
	ds_read_b64_tr_b16 v[138:139], v237 offset:2048
	ds_read_b64_tr_b16 v[140:141], v238 offset:0
	ds_read_b64_tr_b16 v[142:143], v238 offset:2048
	ds_read_b64_tr_b16 v[144:145], v239 offset:0
	ds_read_b64_tr_b16 v[146:147], v239 offset:2048
	ds_read_b64_tr_b16 v[220:221], v236 offset:4096
	ds_read_b64_tr_b16 v[222:223], v236 offset:6144
	ds_read_b64_tr_b16 v[224:225], v237 offset:4096
	ds_read_b64_tr_b16 v[226:227], v237 offset:6144
	s_waitcnt lgkmcnt(10)
	v_mfma_f32_32x32x16_bf16 v[20:35], v[188:191], v[132:135], v[20:35]
	ds_read_b64_tr_b16 v[132:133], v238 offset:4096
	ds_read_b64_tr_b16 v[134:135], v238 offset:6144
	s_waitcnt lgkmcnt(10)
	v_mfma_f32_32x32x16_bf16 v[36:51], v[188:191], v[136:139], v[36:51]
	ds_read_b64_tr_b16 v[136:137], v239 offset:4096
	ds_read_b64_tr_b16 v[138:139], v239 offset:6144
	s_waitcnt lgkmcnt(10)
	v_mfma_f32_32x32x16_bf16 v[52:67], v[188:191], v[140:143], v[52:67]
	ds_read_b64_tr_b16 v[140:141], v236 offset:8192
	ds_read_b64_tr_b16 v[142:143], v236 offset:10240
	s_waitcnt lgkmcnt(10)
	v_mfma_f32_32x32x16_bf16 v[68:83], v[188:191], v[144:147], v[68:83]
	ds_read_b64_tr_b16 v[144:145], v237 offset:8192
	ds_read_b64_tr_b16 v[146:147], v237 offset:10240
	s_waitcnt lgkmcnt(10)
	v_mfma_f32_32x32x16_bf16 v[20:35], v[192:195], v[220:223], v[20:35]
	ds_read_b64_tr_b16 v[220:221], v238 offset:8192
	ds_read_b64_tr_b16 v[222:223], v238 offset:10240
	s_waitcnt lgkmcnt(10)
	v_mfma_f32_32x32x16_bf16 v[36:51], v[192:195], v[224:227], v[36:51]
	ds_read_b64_tr_b16 v[224:225], v239 offset:8192
	ds_read_b64_tr_b16 v[226:227], v239 offset:10240
	s_waitcnt lgkmcnt(10)
	v_mfma_f32_32x32x16_bf16 v[52:67], v[192:195], v[132:135], v[52:67]
	ds_read_b64_tr_b16 v[132:133], v236 offset:12288
	ds_read_b64_tr_b16 v[134:135], v236 offset:14336
	s_waitcnt lgkmcnt(10)
	v_mfma_f32_32x32x16_bf16 v[68:83], v[192:195], v[136:139], v[68:83]
	ds_read_b64_tr_b16 v[136:137], v237 offset:12288
	ds_read_b64_tr_b16 v[138:139], v237 offset:14336
	s_waitcnt lgkmcnt(10)
	v_mfma_f32_32x32x16_bf16 v[20:35], v[204:207], v[140:143], v[20:35]
	ds_read_b64_tr_b16 v[140:141], v238 offset:12288
	ds_read_b64_tr_b16 v[142:143], v238 offset:14336
	s_waitcnt lgkmcnt(10)
	v_mfma_f32_32x32x16_bf16 v[36:51], v[204:207], v[144:147], v[36:51]
	ds_read_b64_tr_b16 v[144:145], v239 offset:12288
	ds_read_b64_tr_b16 v[146:147], v239 offset:14336
	s_waitcnt lgkmcnt(10)
	v_mfma_f32_32x32x16_bf16 v[52:67], v[204:207], v[220:223], v[52:67]
	s_waitcnt lgkmcnt(8)
	v_mfma_f32_32x32x16_bf16 v[68:83], v[204:207], v[224:227], v[68:83]
	s_waitcnt lgkmcnt(6)
	v_mfma_f32_32x32x16_bf16 v[20:35], v[208:211], v[132:135], v[20:35]
	s_waitcnt lgkmcnt(4)
	v_mfma_f32_32x32x16_bf16 v[36:51], v[208:211], v[136:139], v[36:51]
	s_waitcnt lgkmcnt(2)
	v_mfma_f32_32x32x16_bf16 v[52:67], v[208:211], v[140:143], v[52:67]
	s_waitcnt lgkmcnt(0)
	v_mfma_f32_32x32x16_bf16 v[68:83], v[208:211], v[144:147], v[68:83]
	s_waitcnt lgkmcnt(0)
	s_barrier
	s_mov_b32 m0, s32
	s_nop 15
	s_branch .LatB_done
.LatB_rebuild_p0:
	s_mov_b32 s22, s29
	v_mov_b32_e32 v251, 0
	s_cmp_eq_u32 s29, 1
	s_cselect_b64 vcc, -1, 0
	v_cndmask_b32_e32 v251, v251, v177, vcc
	s_cmp_eq_u32 s29, 2
	s_cselect_b64 vcc, -1, 0
	v_cndmask_b32_e32 v251, v251, v178, vcc
	v_sub_f32_e32 v2, v251, v186
	v_mov_b32_e32 v3, v2
	v_mov_b64_e32 v[4:5], v[2:3]
	v_mov_b64_e32 v[6:7], v[2:3]
	v_mov_b64_e32 v[8:9], v[2:3]
	v_mov_b64_e32 v[10:11], v[2:3]
	v_mov_b64_e32 v[12:13], v[2:3]
	v_mov_b64_e32 v[14:15], v[2:3]
	v_mov_b64_e32 v[16:17], v[2:3]
	s_branch .LatB_rebuildret_p0
; #define LAS __attribute__((address_space(3)))
; __device__ __forceinline__ float max2f(float a, float b) { float r; asm("v_max_f32_e32 %0, %1, %2" : "=v"(r) : "v"(a), "v"(b)); return r; }
; __device__ __forceinline__ void attn_unit(LAS unsigned char* lds, const bf16_t* Z, bf16_t* A2, const float* tabg, int seq_base, int S, int h, int qb, float lam) {
;     ...
;         if (near) {
;             const LAS float* tp = tab + (kv0 + 4 * hi - (qlo + r32) + 224);
; #pragma unroll
;             for (int r = 0; r < 16; ++r) { p0[r] += tp[(r & 3) + 8 * (r >> 2)]; p1[r] += tp[32 + (r & 3) + 8 * (r >> 2)]; }
;         }
;         float mx = max2f(max16f(p0), max16f(p1));
;         const bool first = (t == 0);
;         if (first || __any(mx > THR)) {
;             { auto rr = __builtin_amdgcn_permlane32_swap(__float_as_uint(mx), __float_as_uint(mx), false, false); mx = max2f(__uint_as_float(rr[0]), __uint_as_float(rr[1])); }
;             const float delta = first ? mx : fmaxf(mx, 0.f);
;             const float alpha = first ? 1.0f : __builtin_amdgcn_exp2f(-delta);
;             mu += delta; ls2 *= alpha;
;             if (!first) {
;                 asm volatile("" ::: "memory");
;                 scr[r32] = alpha;
;                 asm volatile("s_waitcnt lgkmcnt(0)" ::: "memory");
; #pragma unroll
;                 for (int g = 0; g < 4; ++g) { const f32x4 a4 = *(const LAS f32x4*)(scr + 8 * g + 4 * hi);
; #pragma unroll
;                     for (int d = 0; d < 4; ++d) { O[d][4 * g + 0] *= a4[0]; O[d][4 * g + 1] *= a4[1]; O[d][4 * g + 2] *= a4[2]; O[d][4 * g + 3] *= a4[3]; } }
;                 asm volatile("s_waitcnt lgkmcnt(0)" ::: "memory");
;             }
; #pragma unroll
;             for (int r = 0; r < 16; ++r) { p0[r] -= delta; p1[r] -= delta; }
;             asm volatile("" : "+v"(p0), "+v"(p1));
;         }
.LatB_near_p0:
	s_lshl_b32 s30, s36, 2
	s_add_i32 s30, s30, 0x18b80
	v_add_u32_e32 v187, s30, v162
	ds_read2_b32 v[132:133], v187 offset0:0 offset1:1
	ds_read2_b32 v[134:135], v187 offset0:2 offset1:3
	ds_read2_b32 v[136:137], v187 offset0:8 offset1:9
	ds_read2_b32 v[138:139], v187 offset0:10 offset1:11
	s_waitcnt lgkmcnt(0)
	v_pk_add_f32 v[84:85], v[84:85], v[132:133]
	v_pk_add_f32 v[86:87], v[86:87], v[134:135]
	v_pk_add_f32 v[88:89], v[88:89], v[136:137]
	v_pk_add_f32 v[90:91], v[90:91], v[138:139]
	ds_read2_b32 v[132:133], v187 offset0:16 offset1:17
	ds_read2_b32 v[134:135], v187 offset0:18 offset1:19
	ds_read2_b32 v[136:137], v187 offset0:24 offset1:25
	ds_read2_b32 v[138:139], v187 offset0:26 offset1:27
	s_waitcnt lgkmcnt(0)
	v_pk_add_f32 v[92:93], v[92:93], v[132:133]
	v_pk_add_f32 v[94:95], v[94:95], v[134:135]
	v_pk_add_f32 v[96:97], v[96:97], v[136:137]
	v_pk_add_f32 v[98:99], v[98:99], v[138:139]
	ds_read2_b32 v[132:133], v187 offset0:32 offset1:33
	ds_read2_b32 v[134:135], v187 offset0:34 offset1:35
	ds_read2_b32 v[136:137], v187 offset0:40 offset1:41
	ds_read2_b32 v[138:139], v187 offset0:42 offset1:43
	s_waitcnt lgkmcnt(0)
	v_pk_add_f32 v[100:101], v[100:101], v[132:133]
	v_pk_add_f32 v[102:103], v[102:103], v[134:135]
	v_pk_add_f32 v[104:105], v[104:105], v[136:137]
	v_pk_add_f32 v[106:107], v[106:107], v[138:139]
	ds_read2_b32 v[132:133], v187 offset0:48 offset1:49
	ds_read2_b32 v[134:135], v187 offset0:50 offset1:51
	ds_read2_b32 v[136:137], v187 offset0:56 offset1:57
	ds_read2_b32 v[138:139], v187 offset0:58 offset1:59
	s_waitcnt lgkmcnt(0)
	v_pk_add_f32 v[108:109], v[108:109], v[132:133]
	v_pk_add_f32 v[110:111], v[110:111], v[134:135]
	v_pk_add_f32 v[112:113], v[112:113], v[136:137]
	v_pk_add_f32 v[114:115], v[114:115], v[138:139]
	s_branch .LatB_nearret_p0
.LatB_rare_t0:
	v_mov_b32_e32 v252, v251
	s_nop 1
	v_permlane32_swap_b32_e32 v251, v252
	v_max_f32_e32 v251, v251, v252
	v_max_f32_e32 v253, 0, v251
	v_exp_f32_e64 v254, -v253
	v_add_f32_e32 v186, v186, v253
	s_nop 0
	v_mul_f32_e32 v150, v150, v254
	v_mul_f32_e32 v151, v151, v254
	ds_write_b32 v184, v254
	s_waitcnt lgkmcnt(0)
	ds_read_b128 v[196:199], v185
	ds_read_b128 v[200:203], v185 offset:32
	ds_read_b128 v[212:215], v185 offset:64
	ds_read_b128 v[216:219], v185 offset:96
	s_waitcnt lgkmcnt(0)
	s_nop 15
	s_nop 15
	v_mul_f32_e32 v20, v20, v196
	v_mul_f32_e32 v21, v21, v197
	v_mul_f32_e32 v22, v22, v198
	v_mul_f32_e32 v23, v23, v199
	v_mul_f32_e32 v24, v24, v200
	v_mul_f32_e32 v25, v25, v201
	v_mul_f32_e32 v26, v26, v202
	v_mul_f32_e32 v27, v27, v203
	v_mul_f32_e32 v28, v28, v212
	v_mul_f32_e32 v29, v29, v213
	v_mul_f32_e32 v30, v30, v214
	v_mul_f32_e32 v31, v31, v215
	v_mul_f32_e32 v32, v32, v216
	v_mul_f32_e32 v33, v33, v217
	v_mul_f32_e32 v34, v34, v218
	v_mul_f32_e32 v35, v35, v219
	v_mul_f32_e32 v36, v36, v196
	v_mul_f32_e32 v37, v37, v197
	v_mul_f32_e32 v38, v38, v198
	v_mul_f32_e32 v39, v39, v199
	v_mul_f32_e32 v40, v40, v200
	v_mul_f32_e32 v41, v41, v201
	v_mul_f32_e32 v42, v42, v202
	v_mul_f32_e32 v43, v43, v203
	v_mul_f32_e32 v44, v44, v212
	v_mul_f32_e32 v45, v45, v213
	v_mul_f32_e32 v46, v46, v214
	v_mul_f32_e32 v47, v47, v215
	v_mul_f32_e32 v48, v48, v216
	v_mul_f32_e32 v49, v49, v217
	v_mul_f32_e32 v50, v50, v218
	v_mul_f32_e32 v51, v51, v219
	v_mul_f32_e32 v52, v52, v196
	v_mul_f32_e32 v53, v53, v197
	v_mul_f32_e32 v54, v54, v198
	v_mul_f32_e32 v55, v55, v199
	v_mul_f32_e32 v56, v56, v200
	v_mul_f32_e32 v57, v57, v201
	v_mul_f32_e32 v58, v58, v202
	v_mul_f32_e32 v59, v59, v203
	v_mul_f32_e32 v60, v60, v212
	v_mul_f32_e32 v61, v61, v213
	v_mul_f32_e32 v62, v62, v214
	v_mul_f32_e32 v63, v63, v215
	v_mul_f32_e32 v64, v64, v216
	v_mul_f32_e32 v65, v65, v217
	v_mul_f32_e32 v66, v66, v218
	v_mul_f32_e32 v67, v67, v219
	v_mul_f32_e32 v68, v68, v196
	v_mul_f32_e32 v69, v69, v197
	v_mul_f32_e32 v70, v70, v198
	v_mul_f32_e32 v71, v71, v199
	v_mul_f32_e32 v72, v72, v200
	v_mul_f32_e32 v73, v73, v201
	v_mul_f32_e32 v74, v74, v202
	v_mul_f32_e32 v75, v75, v203
	v_mul_f32_e32 v76, v76, v212
	v_mul_f32_e32 v77, v77, v213
	v_mul_f32_e32 v78, v78, v214
	v_mul_f32_e32 v79, v79, v215
	v_mul_f32_e32 v80, v80, v216
	v_mul_f32_e32 v81, v81, v217
	v_mul_f32_e32 v82, v82, v218
	v_mul_f32_e32 v83, v83, v219
	v_sub_f32_e32 v84, v84, v253
	v_sub_f32_e32 v85, v85, v253
	v_sub_f32_e32 v86, v86, v253
	v_sub_f32_e32 v87, v87, v253
	v_sub_f32_e32 v88, v88, v253
	v_sub_f32_e32 v89, v89, v253
	v_sub_f32_e32 v90, v90, v253
	v_sub_f32_e32 v91, v91, v253
	v_sub_f32_e32 v92, v92, v253
	v_sub_f32_e32 v93, v93, v253
	v_sub_f32_e32 v94, v94, v253
	v_sub_f32_e32 v95, v95, v253
	v_sub_f32_e32 v96, v96, v253
	v_sub_f32_e32 v97, v97, v253
	v_sub_f32_e32 v98, v98, v253
	v_sub_f32_e32 v99, v99, v253
	v_sub_f32_e32 v100, v100, v253
	v_sub_f32_e32 v101, v101, v253
	v_sub_f32_e32 v102, v102, v253
	v_sub_f32_e32 v103, v103, v253
	v_sub_f32_e32 v104, v104, v253
	v_sub_f32_e32 v105, v105, v253
	v_sub_f32_e32 v106, v106, v253
	v_sub_f32_e32 v107, v107, v253
	v_sub_f32_e32 v108, v108, v253
	v_sub_f32_e32 v109, v109, v253
	v_sub_f32_e32 v110, v110, v253
	v_sub_f32_e32 v111, v111, v253
	v_sub_f32_e32 v112, v112, v253
	v_sub_f32_e32 v113, v113, v253
	v_sub_f32_e32 v114, v114, v253
	v_sub_f32_e32 v115, v115, v253
	s_mov_b32 s22, -1
	s_branch .LatB_rareret_t0

; #define LAS __attribute__((address_space(3)))
; __device__ __forceinline__ void attn_unit(LAS unsigned char* lds, const bf16_t* Z, bf16_t* A2, const float* tabg, int seq_base, int S, int h, int qb, float lam) {
;     ...
;         if (near) {
;             const LAS float* tp = tab + (kv0 + 4 * hi - (qlo + r32) + 224);
; #pragma unroll
;             for (int r = 0; r < 16; ++r) { p0[r] += tp[(r & 3) + 8 * (r >> 2)]; p1[r] += tp[32 + (r & 3) + 8 * (r >> 2)]; }
;         }
.LatB_near_t1:
	s_lshl_b32 s30, s36, 2
	s_add_i32 s30, s30, 0x18b80
	v_add_u32_e32 v187, s30, v162
	ds_read2_b32 v[132:133], v187 offset0:0 offset1:1
	ds_read2_b32 v[134:135], v187 offset0:2 offset1:3
	ds_read2_b32 v[136:137], v187 offset0:8 offset1:9
	ds_read2_b32 v[138:139], v187 offset0:10 offset1:11
	s_waitcnt lgkmcnt(0)
	v_pk_add_f32 v[188:189], v[188:189], v[132:133]
	v_pk_add_f32 v[190:191], v[190:191], v[134:135]
	v_pk_add_f32 v[192:193], v[192:193], v[136:137]
	v_pk_add_f32 v[194:195], v[194:195], v[138:139]
	ds_read2_b32 v[132:133], v187 offset0:16 offset1:17
	ds_read2_b32 v[134:135], v187 offset0:18 offset1:19
	ds_read2_b32 v[136:137], v187 offset0:24 offset1:25
	ds_read2_b32 v[138:139], v187 offset0:26 offset1:27
	s_waitcnt lgkmcnt(0)
	v_pk_add_f32 v[196:197], v[196:197], v[132:133]
	v_pk_add_f32 v[198:199], v[198:199], v[134:135]
	v_pk_add_f32 v[200:201], v[200:201], v[136:137]
	v_pk_add_f32 v[202:203], v[202:203], v[138:139]
	ds_read2_b32 v[132:133], v187 offset0:32 offset1:33
	ds_read2_b32 v[134:135], v187 offset0:34 offset1:35
	ds_read2_b32 v[136:137], v187 offset0:40 offset1:41
	ds_read2_b32 v[138:139], v187 offset0:42 offset1:43
	s_waitcnt lgkmcnt(0)
	v_pk_add_f32 v[204:205], v[204:205], v[132:133]
	v_pk_add_f32 v[206:207], v[206:207], v[134:135]
	v_pk_add_f32 v[208:209], v[208:209], v[136:137]
	v_pk_add_f32 v[210:211], v[210:211], v[138:139]
	ds_read2_b32 v[132:133], v187 offset0:48 offset1:49
	ds_read2_b32 v[134:135], v187 offset0:50 offset1:51
	ds_read2_b32 v[136:137], v187 offset0:56 offset1:57
	ds_read2_b32 v[138:139], v187 offset0:58 offset1:59
	s_waitcnt lgkmcnt(0)
	v_pk_add_f32 v[212:213], v[212:213], v[132:133]
	v_pk_add_f32 v[214:215], v[214:215], v[134:135]
	v_pk_add_f32 v[216:217], v[216:217], v[136:137]
	v_pk_add_f32 v[218:219], v[218:219], v[138:139]
	s_branch .LatB_nearret_t1
; #define LAS __attribute__((address_space(3)))
; __device__ __forceinline__ float max2f(float a, float b) { float r; asm("v_max_f32_e32 %0, %1, %2" : "=v"(r) : "v"(a), "v"(b)); return r; }
; __device__ __forceinline__ void attn_unit(LAS unsigned char* lds, const bf16_t* Z, bf16_t* A2, const float* tabg, int seq_base, int S, int h, int qb, float lam) {
;     ...
;         if (first || __any(mx > THR)) {
;             { auto rr = __builtin_amdgcn_permlane32_swap(__float_as_uint(mx), __float_as_uint(mx), false, false); mx = max2f(__uint_as_float(rr[0]), __uint_as_float(rr[1])); }
;             const float delta = first ? mx : fmaxf(mx, 0.f);
;             const float alpha = first ? 1.0f : __builtin_amdgcn_exp2f(-delta);
;             mu += delta; ls2 *= alpha;
;             if (!first) {
;                 asm volatile("" ::: "memory");
;                 scr[r32] = alpha;
;                 asm volatile("s_waitcnt lgkmcnt(0)" ::: "memory");
; #pragma unroll
;                 for (int g = 0; g < 4; ++g) { const f32x4 a4 = *(const LAS f32x4*)(scr + 8 * g + 4 * hi);
; #pragma unroll
;                     for (int d = 0; d < 4; ++d) { O[d][4 * g + 0] *= a4[0]; O[d][4 * g + 1] *= a4[1]; O[d][4 * g + 2] *= a4[2]; O[d][4 * g + 3] *= a4[3]; } }
;                 asm volatile("s_waitcnt lgkmcnt(0)" ::: "memory");
;             }
; #pragma unroll
;             for (int r = 0; r < 16; ++r) { p0[r] -= delta; p1[r] -= delta; }
;             asm volatile("" : "+v"(p0), "+v"(p1));
;         }
.LatB_rare_t1:
	v_mov_b32_e32 v252, v251
	s_nop 1
	v_permlane32_swap_b32_e32 v251, v252
	v_max_f32_e32 v251, v251, v252
	v_max_f32_e32 v253, 0, v251
	v_exp_f32_e64 v254, -v253
	v_add_f32_e32 v186, v186, v253
	s_nop 0
	v_mul_f32_e32 v150, v150, v254
	v_mul_f32_e32 v151, v151, v254
	ds_write_b32 v184, v254
	s_waitcnt lgkmcnt(0)
	v_mfma_f32_32x32x16_bf16 v[20:35], v[84:87], v[132:135], v[20:35]
	v_mfma_f32_32x32x16_bf16 v[36:51], v[84:87], v[136:139], v[36:51]
	v_mfma_f32_32x32x16_bf16 v[52:67], v[84:87], v[140:143], v[52:67]
	v_mfma_f32_32x32x16_bf16 v[68:83], v[84:87], v[144:147], v[68:83]
	v_mfma_f32_32x32x16_bf16 v[20:35], v[88:91], v[220:223], v[20:35]
	v_mfma_f32_32x32x16_bf16 v[36:51], v[88:91], v[224:227], v[36:51]
	ds_read_b64_tr_b16 v[132:133], v238 offset:4096
	ds_read_b64_tr_b16 v[134:135], v238 offset:6144
	ds_read_b64_tr_b16 v[136:137], v239 offset:4096
	ds_read_b64_tr_b16 v[138:139], v239 offset:6144
	ds_read_b64_tr_b16 v[140:141], v236 offset:8192
	ds_read_b64_tr_b16 v[142:143], v236 offset:10240
	ds_read_b64_tr_b16 v[144:145], v237 offset:8192
	ds_read_b64_tr_b16 v[146:147], v237 offset:10240
	ds_read_b64_tr_b16 v[220:221], v238 offset:8192
	ds_read_b64_tr_b16 v[222:223], v238 offset:10240
	ds_read_b64_tr_b16 v[224:225], v239 offset:8192
	ds_read_b64_tr_b16 v[226:227], v239 offset:10240
	s_waitcnt lgkmcnt(0)
	v_mfma_f32_32x32x16_bf16 v[52:67], v[88:91], v[132:135], v[52:67]
	v_mfma_f32_32x32x16_bf16 v[68:83], v[88:91], v[136:139], v[68:83]
	v_mfma_f32_32x32x16_bf16 v[20:35], v[100:103], v[140:143], v[20:35]
	v_mfma_f32_32x32x16_bf16 v[36:51], v[100:103], v[144:147], v[36:51]
	v_mfma_f32_32x32x16_bf16 v[52:67], v[100:103], v[220:223], v[52:67]
	v_mfma_f32_32x32x16_bf16 v[68:83], v[100:103], v[224:227], v[68:83]
	ds_read_b64_tr_b16 v[132:133], v236 offset:12288
	ds_read_b64_tr_b16 v[134:135], v236 offset:14336
	ds_read_b64_tr_b16 v[136:137], v237 offset:12288
	ds_read_b64_tr_b16 v[138:139], v237 offset:14336
	ds_read_b64_tr_b16 v[140:141], v238 offset:12288
	ds_read_b64_tr_b16 v[142:143], v238 offset:14336
	ds_read_b64_tr_b16 v[144:145], v239 offset:12288
	ds_read_b64_tr_b16 v[146:147], v239 offset:14336
	s_waitcnt lgkmcnt(0)
	v_mfma_f32_32x32x16_bf16 v[20:35], v[104:107], v[132:135], v[20:35]
	v_mfma_f32_32x32x16_bf16 v[36:51], v[104:107], v[136:139], v[36:51]
	v_mfma_f32_32x32x16_bf16 v[52:67], v[104:107], v[140:143], v[52:67]
	v_mfma_f32_32x32x16_bf16 v[68:83], v[104:107], v[144:147], v[68:83]
	ds_read_b128 v[92:95], v185
	ds_read_b128 v[96:99], v185 offset:32
	ds_read_b128 v[108:111], v185 offset:64
	ds_read_b128 v[112:115], v185 offset:96
	s_waitcnt lgkmcnt(0)
	s_nop 15
	s_nop 15
	v_mul_f32_e32 v20, v20, v92
	v_mul_f32_e32 v21, v21, v93
	v_mul_f32_e32 v22, v22, v94
	v_mul_f32_e32 v23, v23, v95
	v_mul_f32_e32 v24, v24, v96
	v_mul_f32_e32 v25, v25, v97
	v_mul_f32_e32 v26, v26, v98
	v_mul_f32_e32 v27, v27, v99
	v_mul_f32_e32 v28, v28, v108
	v_mul_f32_e32 v29, v29, v109
	v_mul_f32_e32 v30, v30, v110
	v_mul_f32_e32 v31, v31, v111
	v_mul_f32_e32 v32, v32, v112
	v_mul_f32_e32 v33, v33, v113
	v_mul_f32_e32 v34, v34, v114
	v_mul_f32_e32 v35, v35, v115
	v_mul_f32_e32 v36, v36, v92
	v_mul_f32_e32 v37, v37, v93
	v_mul_f32_e32 v38, v38, v94
	v_mul_f32_e32 v39, v39, v95
	v_mul_f32_e32 v40, v40, v96
	v_mul_f32_e32 v41, v41, v97
	v_mul_f32_e32 v42, v42, v98
	v_mul_f32_e32 v43, v43, v99
	v_mul_f32_e32 v44, v44, v108
	v_mul_f32_e32 v45, v45, v109
	v_mul_f32_e32 v46, v46, v110
	v_mul_f32_e32 v47, v47, v111
	v_mul_f32_e32 v48, v48, v112
	v_mul_f32_e32 v49, v49, v113
	v_mul_f32_e32 v50, v50, v114
	v_mul_f32_e32 v51, v51, v115
	v_mul_f32_e32 v52, v52, v92
	v_mul_f32_e32 v53, v53, v93
	v_mul_f32_e32 v54, v54, v94
	v_mul_f32_e32 v55, v55, v95
	v_mul_f32_e32 v56, v56, v96
	v_mul_f32_e32 v57, v57, v97
	v_mul_f32_e32 v58, v58, v98
	v_mul_f32_e32 v59, v59, v99
	v_mul_f32_e32 v60, v60, v108
	v_mul_f32_e32 v61, v61, v109
	v_mul_f32_e32 v62, v62, v110
	v_mul_f32_e32 v63, v63, v111
	v_mul_f32_e32 v64, v64, v112
	v_mul_f32_e32 v65, v65, v113
	v_mul_f32_e32 v66, v66, v114
	v_mul_f32_e32 v67, v67, v115
	v_mul_f32_e32 v68, v68, v92
	v_mul_f32_e32 v69, v69, v93
	v_mul_f32_e32 v70, v70, v94
	v_mul_f32_e32 v71, v71, v95
	v_mul_f32_e32 v72, v72, v96
	v_mul_f32_e32 v73, v73, v97
	v_mul_f32_e32 v74, v74, v98
	v_mul_f32_e32 v75, v75, v99
	v_mul_f32_e32 v76, v76, v108
	v_mul_f32_e32 v77, v77, v109
	v_mul_f32_e32 v78, v78, v110
	v_mul_f32_e32 v79, v79, v111
	v_mul_f32_e32 v80, v80, v112
	v_mul_f32_e32 v81, v81, v113
	v_mul_f32_e32 v82, v82, v114
	v_mul_f32_e32 v83, v83, v115
	v_sub_f32_e32 v188, v188, v253
	v_sub_f32_e32 v189, v189, v253
	v_sub_f32_e32 v190, v190, v253
	v_sub_f32_e32 v191, v191, v253
	v_sub_f32_e32 v192, v192, v253
	v_sub_f32_e32 v193, v193, v253
	v_sub_f32_e32 v194, v194, v253
	v_sub_f32_e32 v195, v195, v253
	v_sub_f32_e32 v196, v196, v253
	v_sub_f32_e32 v197, v197, v253
	v_sub_f32_e32 v198, v198, v253
	v_sub_f32_e32 v199, v199, v253
	v_sub_f32_e32 v200, v200, v253
	v_sub_f32_e32 v201, v201, v253
	v_sub_f32_e32 v202, v202, v253
	v_sub_f32_e32 v203, v203, v253
	v_sub_f32_e32 v204, v204, v253
	v_sub_f32_e32 v205, v205, v253
	v_sub_f32_e32 v206, v206, v253
	v_sub_f32_e32 v207, v207, v253
	v_sub_f32_e32 v208, v208, v253
	v_sub_f32_e32 v209, v209, v253
	v_sub_f32_e32 v210, v210, v253
	v_sub_f32_e32 v211, v211, v253
	v_sub_f32_e32 v212, v212, v253
	v_sub_f32_e32 v213, v213, v253
	v_sub_f32_e32 v214, v214, v253
	v_sub_f32_e32 v215, v215, v253
	v_sub_f32_e32 v216, v216, v253
	v_sub_f32_e32 v217, v217, v253
	v_sub_f32_e32 v218, v218, v253
	v_sub_f32_e32 v219, v219, v253
	v_mov_b32_e32 v84, 0
	v_mov_b32_e32 v85, 0
	v_mov_b32_e32 v86, 0
	v_mov_b32_e32 v87, 0
	v_mov_b32_e32 v88, 0
	v_mov_b32_e32 v89, 0
	v_mov_b32_e32 v90, 0
	v_mov_b32_e32 v91, 0
	v_mov_b32_e32 v100, 0
	v_mov_b32_e32 v101, 0
	v_mov_b32_e32 v102, 0
	v_mov_b32_e32 v103, 0
	v_mov_b32_e32 v104, 0
	v_mov_b32_e32 v105, 0
	v_mov_b32_e32 v106, 0
	v_mov_b32_e32 v107, 0
	s_mov_b32 s22, -1
	s_branch .LatB_rareret_t1

; #define LAS __attribute__((address_space(3)))
; __device__ __forceinline__ float max2f(float a, float b) { float r; asm("v_max_f32_e32 %0, %1, %2" : "=v"(r) : "v"(a), "v"(b)); return r; }
; __device__ __forceinline__ void attn_unit(LAS unsigned char* lds, const bf16_t* Z, bf16_t* A2, const float* tabg, int seq_base, int S, int h, int qb, float lam) {
;     ...
;         if (first || __any(mx > THR)) {
;             { auto rr = __builtin_amdgcn_permlane32_swap(__float_as_uint(mx), __float_as_uint(mx), false, false); mx = max2f(__uint_as_float(rr[0]), __uint_as_float(rr[1])); }
;             const float delta = first ? mx : fmaxf(mx, 0.f);
;             const float alpha = first ? 1.0f : __builtin_amdgcn_exp2f(-delta);
;             mu += delta; ls2 *= alpha;
;             if (!first) {
;                 asm volatile("" ::: "memory");
;                 scr[r32] = alpha;
;                 asm volatile("s_waitcnt lgkmcnt(0)" ::: "memory");
; #pragma unroll
;                 for (int g = 0; g < 4; ++g) { const f32x4 a4 = *(const LAS f32x4*)(scr + 8 * g + 4 * hi);
; #pragma unroll
;                     for (int d = 0; d < 4; ++d) { O[d][4 * g + 0] *= a4[0]; O[d][4 * g + 1] *= a4[1]; O[d][4 * g + 2] *= a4[2]; O[d][4 * g + 3] *= a4[3]; } }
;                 asm volatile("s_waitcnt lgkmcnt(0)" ::: "memory");
;             }
; #pragma unroll
;             for (int r = 0; r < 16; ++r) { p0[r] -= delta; p1[r] -= delta; }
;             asm volatile("" : "+v"(p0), "+v"(p1));
;         }
.LatB_rare_e:
	v_mov_b32_e32 v252, v251
	s_nop 1
	v_permlane32_swap_b32_e32 v251, v252
	v_max_f32_e32 v251, v251, v252
	v_max_f32_e32 v253, 0, v251
	v_exp_f32_e64 v254, -v253
	v_add_f32_e32 v186, v186, v253
	s_nop 0
	v_mul_f32_e32 v150, v150, v254
	v_mul_f32_e32 v151, v151, v254
	ds_write_b32 v184, v254
	s_waitcnt lgkmcnt(0)
	v_mfma_f32_32x32x16_bf16 v[20:35], v[188:191], v[132:135], v[20:35]
	v_mfma_f32_32x32x16_bf16 v[36:51], v[188:191], v[136:139], v[36:51]
	v_mfma_f32_32x32x16_bf16 v[52:67], v[188:191], v[140:143], v[52:67]
	v_mfma_f32_32x32x16_bf16 v[68:83], v[188:191], v[144:147], v[68:83]
	v_mfma_f32_32x32x16_bf16 v[20:35], v[192:195], v[220:223], v[20:35]
	v_mfma_f32_32x32x16_bf16 v[36:51], v[192:195], v[224:227], v[36:51]
	ds_read_b64_tr_b16 v[132:133], v238 offset:4096
	ds_read_b64_tr_b16 v[134:135], v238 offset:6144
	ds_read_b64_tr_b16 v[136:137], v239 offset:4096
	ds_read_b64_tr_b16 v[138:139], v239 offset:6144
	ds_read_b64_tr_b16 v[140:141], v236 offset:8192
	ds_read_b64_tr_b16 v[142:143], v236 offset:10240
	ds_read_b64_tr_b16 v[144:145], v237 offset:8192
	ds_read_b64_tr_b16 v[146:147], v237 offset:10240
	ds_read_b64_tr_b16 v[220:221], v238 offset:8192
	ds_read_b64_tr_b16 v[222:223], v238 offset:10240
	ds_read_b64_tr_b16 v[224:225], v239 offset:8192
	ds_read_b64_tr_b16 v[226:227], v239 offset:10240
	s_waitcnt lgkmcnt(0)
	v_mfma_f32_32x32x16_bf16 v[52:67], v[192:195], v[132:135], v[52:67]
	v_mfma_f32_32x32x16_bf16 v[68:83], v[192:195], v[136:139], v[68:83]
	v_mfma_f32_32x32x16_bf16 v[20:35], v[204:207], v[140:143], v[20:35]
	v_mfma_f32_32x32x16_bf16 v[36:51], v[204:207], v[144:147], v[36:51]
	v_mfma_f32_32x32x16_bf16 v[52:67], v[204:207], v[220:223], v[52:67]
	v_mfma_f32_32x32x16_bf16 v[68:83], v[204:207], v[224:227], v[68:83]
	ds_read_b64_tr_b16 v[132:133], v236 offset:12288
	ds_read_b64_tr_b16 v[134:135], v236 offset:14336
	ds_read_b64_tr_b16 v[136:137], v237 offset:12288
	ds_read_b64_tr_b16 v[138:139], v237 offset:14336
	ds_read_b64_tr_b16 v[140:141], v238 offset:12288
	ds_read_b64_tr_b16 v[142:143], v238 offset:14336
	ds_read_b64_tr_b16 v[144:145], v239 offset:12288
	ds_read_b64_tr_b16 v[146:147], v239 offset:14336
	s_waitcnt lgkmcnt(0)
	v_mfma_f32_32x32x16_bf16 v[20:35], v[208:211], v[132:135], v[20:35]
	v_mfma_f32_32x32x16_bf16 v[36:51], v[208:211], v[136:139], v[36:51]
	v_mfma_f32_32x32x16_bf16 v[52:67], v[208:211], v[140:143], v[52:67]
	v_mfma_f32_32x32x16_bf16 v[68:83], v[208:211], v[144:147], v[68:83]
	ds_read_b128 v[196:199], v185
	ds_read_b128 v[200:203], v185 offset:32
	ds_read_b128 v[212:215], v185 offset:64
	ds_read_b128 v[216:219], v185 offset:96
	s_waitcnt lgkmcnt(0)
	s_nop 15
	s_nop 15
	v_mul_f32_e32 v20, v20, v196
	v_mul_f32_e32 v21, v21, v197
	v_mul_f32_e32 v22, v22, v198
	v_mul_f32_e32 v23, v23, v199
	v_mul_f32_e32 v24, v24, v200
	v_mul_f32_e32 v25, v25, v201
	v_mul_f32_e32 v26, v26, v202
	v_mul_f32_e32 v27, v27, v203
	v_mul_f32_e32 v28, v28, v212
	v_mul_f32_e32 v29, v29, v213
	v_mul_f32_e32 v30, v30, v214
	v_mul_f32_e32 v31, v31, v215
	v_mul_f32_e32 v32, v32, v216
	v_mul_f32_e32 v33, v33, v217
	v_mul_f32_e32 v34, v34, v218
	v_mul_f32_e32 v35, v35, v219
	v_mul_f32_e32 v36, v36, v196
	v_mul_f32_e32 v37, v37, v197
	v_mul_f32_e32 v38, v38, v198
	v_mul_f32_e32 v39, v39, v199
	v_mul_f32_e32 v40, v40, v200
	v_mul_f32_e32 v41, v41, v201
	v_mul_f32_e32 v42, v42, v202
	v_mul_f32_e32 v43, v43, v203
	v_mul_f32_e32 v44, v44, v212
	v_mul_f32_e32 v45, v45, v213
	v_mul_f32_e32 v46, v46, v214
	v_mul_f32_e32 v47, v47, v215
	v_mul_f32_e32 v48, v48, v216
	v_mul_f32_e32 v49, v49, v217
	v_mul_f32_e32 v50, v50, v218
	v_mul_f32_e32 v51, v51, v219
	v_mul_f32_e32 v52, v52, v196
	v_mul_f32_e32 v53, v53, v197
	v_mul_f32_e32 v54, v54, v198
	v_mul_f32_e32 v55, v55, v199
	v_mul_f32_e32 v56, v56, v200
	v_mul_f32_e32 v57, v57, v201
	v_mul_f32_e32 v58, v58, v202
	v_mul_f32_e32 v59, v59, v203
	v_mul_f32_e32 v60, v60, v212
	v_mul_f32_e32 v61, v61, v213
	v_mul_f32_e32 v62, v62, v214
	v_mul_f32_e32 v63, v63, v215
	v_mul_f32_e32 v64, v64, v216
	v_mul_f32_e32 v65, v65, v217
	v_mul_f32_e32 v66, v66, v218
	v_mul_f32_e32 v67, v67, v219
	v_mul_f32_e32 v68, v68, v196
	v_mul_f32_e32 v69, v69, v197
	v_mul_f32_e32 v70, v70, v198
	v_mul_f32_e32 v71, v71, v199
	v_mul_f32_e32 v72, v72, v200
	v_mul_f32_e32 v73, v73, v201
	v_mul_f32_e32 v74, v74, v202
	v_mul_f32_e32 v75, v75, v203
	v_mul_f32_e32 v76, v76, v212
	v_mul_f32_e32 v77, v77, v213
	v_mul_f32_e32 v78, v78, v214
	v_mul_f32_e32 v79, v79, v215
	v_mul_f32_e32 v80, v80, v216
	v_mul_f32_e32 v81, v81, v217
	v_mul_f32_e32 v82, v82, v218
	v_mul_f32_e32 v83, v83, v219
	v_sub_f32_e32 v84, v84, v253
	v_sub_f32_e32 v85, v85, v253
	v_sub_f32_e32 v86, v86, v253
	v_sub_f32_e32 v87, v87, v253
	v_sub_f32_e32 v88, v88, v253
	v_sub_f32_e32 v89, v89, v253
	v_sub_f32_e32 v90, v90, v253
	v_sub_f32_e32 v91, v91, v253
	v_sub_f32_e32 v92, v92, v253
	v_sub_f32_e32 v93, v93, v253
	v_sub_f32_e32 v94, v94, v253
	v_sub_f32_e32 v95, v95, v253
	v_sub_f32_e32 v96, v96, v253
	v_sub_f32_e32 v97, v97, v253
	v_sub_f32_e32 v98, v98, v253
	v_sub_f32_e32 v99, v99, v253
	v_sub_f32_e32 v100, v100, v253
	v_sub_f32_e32 v101, v101, v253
	v_sub_f32_e32 v102, v102, v253
	v_sub_f32_e32 v103, v103, v253
	v_sub_f32_e32 v104, v104, v253
	v_sub_f32_e32 v105, v105, v253
	v_sub_f32_e32 v106, v106, v253
	v_sub_f32_e32 v107, v107, v253
	v_sub_f32_e32 v108, v108, v253
	v_sub_f32_e32 v109, v109, v253
	v_sub_f32_e32 v110, v110, v253
	v_sub_f32_e32 v111, v111, v253
	v_sub_f32_e32 v112, v112, v253
	v_sub_f32_e32 v113, v113, v253
	v_sub_f32_e32 v114, v114, v253
	v_sub_f32_e32 v115, v115, v253
	v_mov_b32_e32 v188, 0
	v_mov_b32_e32 v189, 0
	v_mov_b32_e32 v190, 0
	v_mov_b32_e32 v191, 0
	v_mov_b32_e32 v192, 0
	v_mov_b32_e32 v193, 0
	v_mov_b32_e32 v194, 0
	v_mov_b32_e32 v195, 0
	v_mov_b32_e32 v204, 0
	v_mov_b32_e32 v205, 0
	v_mov_b32_e32 v206, 0
	v_mov_b32_e32 v207, 0
	v_mov_b32_e32 v208, 0
	v_mov_b32_e32 v209, 0
	v_mov_b32_e32 v210, 0
	v_mov_b32_e32 v211, 0
	s_mov_b32 s22, -1
	s_branch .LatB_rareret_e
